# first K-loop iteration of every GEMM unit peeled (srcC=0), accumulator zeroing removed; NSA window-branch epilogue loads issued together
# speedup vs baseline: 1.0120x; 1.0030x over previous
; #define PG8_STAGE(bufoff, gbase, voff) do { _Pragma("unroll") for (int _i = 0; _i < 2; ++_i) \
;         __builtin_amdgcn_global_load_lds((const unsigned*)((const char*)(gbase) + (voff)[_i]), (PG8_LAS unsigned*)(lds + (bufoff) + ldsw + _i * 8192), 16, 0, 0); } while (0)
; #define PG8_LDA(dst, b, h) do { _Pragma("unroll") for (int m = 0; m < 4; ++m) _Pragma("unroll") for (int k = 0; k < 2; ++k) dst[m][k] = *(const PG8_LAS bf16x8*)(lds + PG8_SA(b, h) + aoff + m * 2048 + k * 1024); } while (0)
; #define PG8_LDB(dst, b, h) do { _Pragma("unroll") for (int n = 0; n < 2; ++n) _Pragma("unroll") for (int k = 0; k < 2; ++k) dst[n][k] = *(const PG8_LAS bf16x8*)(lds + PG8_SB(b, h) + boff + n * 2048 + k * 1024); } while (0)
; template <class Epi, class Sched, bool ALIGN_EPI = false, bool SP2 = false>
; __device__ __forceinline__ void gemm_phase(PG8_LAS unsigned char* lds, const Gemm g, const Sched& S, const Epi& E) {
;     ...
;         const bool has_next = S.next(ui + 1, nxt);
;         const char* nA = has_next ? (const char*)g.A + (size_t)nxt.pm * tstep : cA; const char* nB = has_next ? (const char*)g.Bt + (size_t)nxt.pn * tstep : cB;
;         for (int t = 0; t < nt; t += 2) {
;             const bool last = (t == nt - 2);
;             const char* a1 = cA + (size_t)(t + 1) * kstep;
;             const char* a2 = last ? nA : cA + (size_t)(t + 2) * kstep; const char* b2 = last ? nB : cB + (size_t)(t + 2) * kstep;
;             const char* a3 = a2 + kstep; const char* b3 = b2 + kstep;
;             if (last && has_next) S.a_ready(nxt);
;             if constexpr (SP2) {
;             PG8_LDB(B0, 0, 0); PG8_LDB(B1, 0, 1); PG8_SCHED; PG8_LDA(At, 0, 0); PG8_STAGE(PG8_SA(1, 1), a1 + hstep, voffA);
;             PG8_WAIT_V(8); PG8_WAIT_L(0); PG8_BAR; PG8_MMA(0, 0, At, B0); PG8_MMA(0, 1, At, B1); PG8_BAR; PG8_SCHED;
;             PG8_LDA(At, 0, 1); PG8_STAGE(PG8_SB(0, 0), b2, voffB); PG8_STAGE(PG8_SB(0, 1), b2 + hstep, voffB); PG8_STAGE(PG8_SA(0, 0), a2, voffA);
;             PG8_WAIT_V(8); PG8_WAIT_L(0); PG8_BAR; PG8_MMA(1, 0, At, B0); PG8_MMA(1, 1, At, B1); PG8_BAR; PG8_SCHED;
;     ...
; #pragma unroll
;         for (int a = 0; a < 2; ++a)
; #pragma unroll
;             for (int b = 0; b < 2; ++b)
; #pragma unroll
;                 for (int m = 0; m < 4; ++m)
; #pragma unroll
;                     for (int n = 0; n < 2; ++n) acc[a][b][m][n] = (f32x4){0.f, 0.f, 0.f, 0.f};
.LBB0_1166:
	s_ashr_i32 s17, s16, 31
	s_lshl_b64 s[20:21], s[16:17], 20
	s_add_u32 s20, s3, s20
	s_addc_u32 s21, s2, s21
	s_and_b64 s[34:35], s[4:5], exec
	s_cselect_b32 s17, s21, s37
	s_cselect_b32 s30, s20, s36
	s_ashr_i32 s15, s14, 31
	s_lshl_b64 s[34:35], s[14:15], 20
	s_add_u32 s34, s29, s34
	s_addc_u32 s35, s40, s35
	s_and_b64 s[42:43], s[4:5], exec
	s_cselect_b32 s15, s35, s39
	s_cselect_b32 s55, s34, s38
	s_add_u32 s36, s36, 0x80080
	s_addc_u32 s37, s37, 0
	s_add_u32 s56, s38, 0x100
	s_addc_u32 s57, s39, 0
	s_mov_b32 s62, -2
	s_add_u32 s26, s36, 0xfff80080
	s_addc_u32 s38, s37, -1
	s_add_i32 s63, 0, 0x10000
	s_cmp_eq_u32 s62, 28
	s_cselect_b32 s43, s17, s38
	s_cselect_b32 s42, s30, s26
	v_add_u32_e32 v144, s63, v145
	s_cselect_b32 s39, s15, s57
	s_cselect_b32 s38, s55, s56
	s_add_i32 s26, 0, 0x14000
	ds_read_b128 v[154:157], v144
	ds_read_b128 v[158:161], v144 offset:1024
	ds_read_b128 v[162:165], v144 offset:2048
	ds_read_b128 v[166:169], v144 offset:3072
	v_add_u32_e32 v144, s26, v145
	ds_read_b128 v[170:173], v144
	ds_read_b128 v[174:177], v144 offset:1024
	ds_read_b128 v[182:185], v144 offset:2048
	ds_read_b128 v[186:189], v144 offset:3072
	v_lshl_add_u64 v[146:147], s[36:37], 0, v[140:141]
	s_add_i32 m0, s45, 0xc000
	ds_read_b128 v[190:193], v153
	ds_read_b128 v[194:197], v153 offset:1024
	ds_read_b128 v[198:201], v153 offset:2048
	ds_read_b128 v[202:205], v153 offset:3072
	ds_read_b128 v[206:209], v153 offset:4096
	ds_read_b128 v[210:213], v153 offset:5120
	ds_read_b128 v[214:217], v153 offset:6144
	ds_read_b128 v[218:221], v153 offset:7168
	global_load_lds_dwordx4 v[146:147], off
	v_lshl_add_u64 v[146:147], s[36:37], 0, v[142:143]
	s_add_i32 m0, s45, 0xe000
	s_nop 0
	global_load_lds_dwordx4 v[146:147], off
	s_waitcnt vmcnt(8)
	s_waitcnt lgkmcnt(0)
	s_setprio 1
	s_barrier
	v_mfma_f32_16x16x32_bf16 v[80:83], v[154:157], v[190:193], 0
	v_mfma_f32_16x16x32_bf16 v[76:79], v[162:165], v[190:193], 0
	v_mfma_f32_16x16x32_bf16 v[64:67], v[154:157], v[198:201], 0
	v_mfma_f32_16x16x32_bf16 v[60:63], v[162:165], v[198:201], 0
	v_mfma_f32_16x16x32_bf16 v[56:59], v[154:157], v[206:209], 0
	v_mfma_f32_16x16x32_bf16 v[52:55], v[162:165], v[206:209], 0
	v_mfma_f32_16x16x32_bf16 v[44:47], v[154:157], v[214:217], 0
	v_mfma_f32_16x16x32_bf16 v[36:39], v[162:165], v[214:217], 0
	v_mfma_f32_16x16x32_bf16 v[80:83], v[158:161], v[194:197], v[80:83]
	v_mfma_f32_16x16x32_bf16 v[76:79], v[166:169], v[194:197], v[76:79]
	v_mfma_f32_16x16x32_bf16 v[64:67], v[158:161], v[202:205], v[64:67]
	v_mfma_f32_16x16x32_bf16 v[60:63], v[166:169], v[202:205], v[60:63]
	v_mfma_f32_16x16x32_bf16 v[56:59], v[158:161], v[210:213], v[56:59]
	v_mfma_f32_16x16x32_bf16 v[52:55], v[166:169], v[210:213], v[52:55]
	v_mfma_f32_16x16x32_bf16 v[44:47], v[158:161], v[218:221], v[44:47]
	v_mfma_f32_16x16x32_bf16 v[36:39], v[166:169], v[218:221], v[36:39]
	s_setprio 0
	s_setprio 1
	v_mfma_f32_16x16x32_bf16 v[128:131], v[170:173], v[190:193], 0
	v_mfma_f32_16x16x32_bf16 v[124:127], v[182:185], v[190:193], 0
	v_mfma_f32_16x16x32_bf16 v[120:123], v[170:173], v[198:201], 0
	v_mfma_f32_16x16x32_bf16 v[116:119], v[182:185], v[198:201], 0
	v_mfma_f32_16x16x32_bf16 v[112:115], v[170:173], v[206:209], 0
	v_mfma_f32_16x16x32_bf16 v[108:111], v[182:185], v[206:209], 0
	v_mfma_f32_16x16x32_bf16 v[104:107], v[170:173], v[214:217], 0
	v_mfma_f32_16x16x32_bf16 v[100:103], v[182:185], v[214:217], 0
	v_mfma_f32_16x16x32_bf16 v[128:131], v[174:177], v[194:197], v[128:131]
	v_mfma_f32_16x16x32_bf16 v[124:127], v[186:189], v[194:197], v[124:127]
	v_mfma_f32_16x16x32_bf16 v[120:123], v[174:177], v[202:205], v[120:123]
	v_mfma_f32_16x16x32_bf16 v[116:119], v[186:189], v[202:205], v[116:119]
	v_mfma_f32_16x16x32_bf16 v[112:115], v[174:177], v[210:213], v[112:115]
	v_mfma_f32_16x16x32_bf16 v[108:111], v[186:189], v[210:213], v[108:111]
	v_mfma_f32_16x16x32_bf16 v[104:107], v[174:177], v[218:221], v[104:107]
	v_mfma_f32_16x16x32_bf16 v[100:103], v[186:189], v[218:221], v[100:103]
	s_barrier
	s_setprio 0
	s_add_i32 s63, s63, s44
	v_lshl_add_u64 v[146:147], s[38:39], 0, v[2:3]
	s_mov_b32 m0, s63
	ds_read_b128 v[190:193], v153 offset:16384
	ds_read_b128 v[194:197], v153 offset:17408
	ds_read_b128 v[198:201], v153 offset:18432
	ds_read_b128 v[202:205], v153 offset:19456
	ds_read_b128 v[206:209], v153 offset:20480
	ds_read_b128 v[210:213], v153 offset:21504
	ds_read_b128 v[214:217], v153 offset:22528
	ds_read_b128 v[218:221], v153 offset:23552
	global_load_lds_dwordx4 v[146:147], off
	s_add_i32 m0, s63, 0x2000
	s_add_u32 s66, s38, 0x80000
	v_lshl_add_u64 v[150:151], s[38:39], 0, v[132:133]
	s_addc_u32 s67, s39, 0
	s_add_i32 s26, s26, s44
	global_load_lds_dwordx4 v[150:151], off
	v_lshl_add_u64 v[178:179], s[66:67], 0, v[2:3]
	s_mov_b32 m0, s26
	v_lshl_add_u64 v[222:223], s[42:43], 0, v[134:135]
	global_load_lds_dwordx4 v[178:179], off
	v_lshl_add_u64 v[178:179], s[66:67], 0, v[132:133]
	s_add_i32 m0, s26, 0x2000
	s_nop 0
	global_load_lds_dwordx4 v[178:179], off
	v_lshl_add_u64 v[178:179], s[42:43], 0, v[136:137]
	s_mov_b32 m0, s45
	s_nop 0
	global_load_lds_dwordx4 v[178:179], off
	s_mov_b32 m0, s46
	s_nop 0
	global_load_lds_dwordx4 v[222:223], off
	s_waitcnt vmcnt(8)
	s_waitcnt lgkmcnt(0)
	s_setprio 1
	s_barrier
; #define PG8_STAGE(bufoff, gbase, voff) do { _Pragma("unroll") for (int _i = 0; _i < 2; ++_i) \
;         __builtin_amdgcn_global_load_lds((const unsigned*)((const char*)(gbase) + (voff)[_i]), (PG8_LAS unsigned*)(lds + (bufoff) + ldsw + _i * 8192), 16, 0, 0); } while (0)
; #define PG8_LDA(dst, b, h) do { _Pragma("unroll") for (int m = 0; m < 4; ++m) _Pragma("unroll") for (int k = 0; k < 2; ++k) dst[m][k] = *(const PG8_LAS bf16x8*)(lds + PG8_SA(b, h) + aoff + m * 2048 + k * 1024); } while (0)
; #define PG8_LDB(dst, b, h) do { _Pragma("unroll") for (int n = 0; n < 2; ++n) _Pragma("unroll") for (int k = 0; k < 2; ++k) dst[n][k] = *(const PG8_LAS bf16x8*)(lds + PG8_SB(b, h) + boff + n * 2048 + k * 1024); } while (0)
; #define PG8_MMA(ai, bj, At, Bt) do { __builtin_amdgcn_s_setprio(1); _Pragma("unroll") for (int m = 0; m < 4; ++m) _Pragma("unroll") for (int n = 0; n < 2; ++n) _Pragma("unroll") for (int k = 0; k < 2; ++k) \
;         acc[ai][bj][m][n] = __builtin_amdgcn_mfma_f32_16x16x32_bf16(Bt[n][k], At[m][k], acc[ai][bj][m][n], 0, 0, 0); __builtin_amdgcn_s_setprio(0); } while (0)
; #define PG8_WAIT_V(n) asm volatile("s_waitcnt vmcnt(" #n ")" ::: "memory")
; #define PG8_WAIT_L(n) asm volatile("s_waitcnt lgkmcnt(" #n ")" ::: "memory")
; #define PG8_BAR __builtin_amdgcn_s_barrier()
; #define PG8_SCHED __builtin_amdgcn_sched_barrier(0)
; template <class Epi, class Sched, bool ALIGN_EPI = false, bool SP2 = false>
; __device__ __forceinline__ void gemm_phase(PG8_LAS unsigned char* lds, const Gemm g, const Sched& S, const Epi& E) {
;     ...
;             PG8_WAIT_V(8); PG8_WAIT_L(0); PG8_BAR; PG8_MMA(1, 0, At, B0); PG8_MMA(1, 1, At, B1); PG8_BAR; PG8_SCHED;
;             PG8_LDB(B0, 1, 0); PG8_LDB(B1, 1, 1); PG8_SCHED; PG8_LDA(At, 1, 0); PG8_STAGE(PG8_SA(0, 1), a2 + hstep, voffA);
;             PG8_WAIT_V(8); PG8_WAIT_L(0); PG8_BAR; PG8_MMA(0, 0, At, B0); PG8_MMA(0, 1, At, B1); PG8_BAR; PG8_SCHED;
	v_mfma_f32_16x16x32_bf16 v[32:35], v[154:157], v[190:193], 0
	v_mfma_f32_16x16x32_bf16 v[28:31], v[162:165], v[190:193], 0
	v_mfma_f32_16x16x32_bf16 v[24:27], v[154:157], v[198:201], 0
	v_mfma_f32_16x16x32_bf16 v[20:23], v[162:165], v[198:201], 0
	v_mfma_f32_16x16x32_bf16 v[16:19], v[154:157], v[206:209], 0
	v_mfma_f32_16x16x32_bf16 v[12:15], v[162:165], v[206:209], 0
	v_mfma_f32_16x16x32_bf16 v[8:11], v[154:157], v[214:217], 0
	v_mfma_f32_16x16x32_bf16 v[4:7], v[162:165], v[214:217], 0
	v_mfma_f32_16x16x32_bf16 v[32:35], v[158:161], v[194:197], v[32:35]
	v_mfma_f32_16x16x32_bf16 v[28:31], v[166:169], v[194:197], v[28:31]
	v_mfma_f32_16x16x32_bf16 v[24:27], v[158:161], v[202:205], v[24:27]
	v_mfma_f32_16x16x32_bf16 v[20:23], v[166:169], v[202:205], v[20:23]
	v_mfma_f32_16x16x32_bf16 v[16:19], v[158:161], v[210:213], v[16:19]
	v_mfma_f32_16x16x32_bf16 v[12:15], v[166:169], v[210:213], v[12:15]
	v_mfma_f32_16x16x32_bf16 v[8:11], v[158:161], v[218:221], v[8:11]
	v_mfma_f32_16x16x32_bf16 v[4:7], v[166:169], v[218:221], v[4:7]
	s_setprio 0
	s_setprio 1
	v_mfma_f32_16x16x32_bf16 v[96:99], v[170:173], v[190:193], 0
	v_mfma_f32_16x16x32_bf16 v[92:95], v[182:185], v[190:193], 0
	v_mfma_f32_16x16x32_bf16 v[88:91], v[170:173], v[198:201], 0
	v_mfma_f32_16x16x32_bf16 v[84:87], v[182:185], v[198:201], 0
	v_mfma_f32_16x16x32_bf16 v[72:75], v[170:173], v[206:209], 0
	v_mfma_f32_16x16x32_bf16 v[68:71], v[182:185], v[206:209], 0
	v_mfma_f32_16x16x32_bf16 v[48:51], v[170:173], v[214:217], 0
	v_mfma_f32_16x16x32_bf16 v[40:43], v[182:185], v[214:217], 0
	v_mfma_f32_16x16x32_bf16 v[96:99], v[174:177], v[194:197], v[96:99]
	v_mfma_f32_16x16x32_bf16 v[92:95], v[186:189], v[194:197], v[92:95]
	v_mfma_f32_16x16x32_bf16 v[88:91], v[174:177], v[202:205], v[88:91]
	v_mfma_f32_16x16x32_bf16 v[84:87], v[186:189], v[202:205], v[84:87]
	v_mfma_f32_16x16x32_bf16 v[72:75], v[174:177], v[210:213], v[72:75]
	v_mfma_f32_16x16x32_bf16 v[68:71], v[186:189], v[210:213], v[68:71]
	v_mfma_f32_16x16x32_bf16 v[48:51], v[174:177], v[218:221], v[48:51]
	v_mfma_f32_16x16x32_bf16 v[40:43], v[186:189], v[218:221], v[40:43]
	s_barrier
	s_setprio 0
	s_add_i32 s26, 0, 0x18000
	v_add_u32_e32 v144, s26, v145
	s_add_i32 s63, 0, 0x1c000
	ds_read_b128 v[154:157], v144
	ds_read_b128 v[158:161], v144 offset:1024
	ds_read_b128 v[162:165], v144 offset:2048
	ds_read_b128 v[166:169], v144 offset:3072
	v_add_u32_e32 v144, s63, v145
	ds_read_b128 v[170:173], v144
	ds_read_b128 v[174:177], v144 offset:1024
	ds_read_b128 v[182:185], v144 offset:2048
	ds_read_b128 v[186:189], v144 offset:3072
	s_add_u32 s42, s42, 0x80000
	s_addc_u32 s43, s43, 0
	s_mov_b32 m0, s47
	v_lshl_add_u64 v[224:225], s[42:43], 0, v[136:137]
	ds_read_b128 v[190:193], v153 offset:32768
	ds_read_b128 v[194:197], v153 offset:33792
	ds_read_b128 v[198:201], v153 offset:34816
	ds_read_b128 v[202:205], v153 offset:35840
	ds_read_b128 v[206:209], v153 offset:36864
	ds_read_b128 v[210:213], v153 offset:37888
	ds_read_b128 v[214:217], v153 offset:38912
	ds_read_b128 v[218:221], v153 offset:39936
	global_load_lds_dwordx4 v[224:225], off
	v_lshl_add_u64 v[224:225], s[42:43], 0, v[134:135]
	s_mov_b32 m0, s50
	s_nop 0
	global_load_lds_dwordx4 v[224:225], off
	s_waitcnt vmcnt(8)
	s_waitcnt lgkmcnt(0)
	s_setprio 1
	s_barrier
	v_mfma_f32_16x16x32_bf16 v[80:83], v[154:157], v[190:193], v[80:83]
	v_mfma_f32_16x16x32_bf16 v[76:79], v[162:165], v[190:193], v[76:79]
	v_mfma_f32_16x16x32_bf16 v[64:67], v[154:157], v[198:201], v[64:67]
	v_mfma_f32_16x16x32_bf16 v[60:63], v[162:165], v[198:201], v[60:63]
	v_mfma_f32_16x16x32_bf16 v[56:59], v[154:157], v[206:209], v[56:59]
	v_mfma_f32_16x16x32_bf16 v[52:55], v[162:165], v[206:209], v[52:55]
	v_mfma_f32_16x16x32_bf16 v[44:47], v[154:157], v[214:217], v[44:47]
	v_mfma_f32_16x16x32_bf16 v[36:39], v[162:165], v[214:217], v[36:39]
	v_mfma_f32_16x16x32_bf16 v[80:83], v[158:161], v[194:197], v[80:83]
	v_mfma_f32_16x16x32_bf16 v[76:79], v[166:169], v[194:197], v[76:79]
	v_mfma_f32_16x16x32_bf16 v[64:67], v[158:161], v[202:205], v[64:67]
	v_mfma_f32_16x16x32_bf16 v[60:63], v[166:169], v[202:205], v[60:63]
	v_mfma_f32_16x16x32_bf16 v[56:59], v[158:161], v[210:213], v[56:59]
	v_mfma_f32_16x16x32_bf16 v[52:55], v[166:169], v[210:213], v[52:55]
	v_mfma_f32_16x16x32_bf16 v[44:47], v[158:161], v[218:221], v[44:47]
	v_mfma_f32_16x16x32_bf16 v[36:39], v[166:169], v[218:221], v[36:39]
	s_setprio 0
	s_setprio 1
	v_mfma_f32_16x16x32_bf16 v[128:131], v[170:173], v[190:193], v[128:131]
	v_mfma_f32_16x16x32_bf16 v[124:127], v[182:185], v[190:193], v[124:127]
	v_mfma_f32_16x16x32_bf16 v[120:123], v[170:173], v[198:201], v[120:123]
	v_mfma_f32_16x16x32_bf16 v[116:119], v[182:185], v[198:201], v[116:119]
	v_mfma_f32_16x16x32_bf16 v[112:115], v[170:173], v[206:209], v[112:115]
	v_mfma_f32_16x16x32_bf16 v[108:111], v[182:185], v[206:209], v[108:111]
	v_mfma_f32_16x16x32_bf16 v[104:107], v[170:173], v[214:217], v[104:107]
	v_mfma_f32_16x16x32_bf16 v[100:103], v[182:185], v[214:217], v[100:103]
	v_mfma_f32_16x16x32_bf16 v[128:131], v[174:177], v[194:197], v[128:131]
	v_mfma_f32_16x16x32_bf16 v[124:127], v[186:189], v[194:197], v[124:127]
	v_mfma_f32_16x16x32_bf16 v[120:123], v[174:177], v[202:205], v[120:123]
	v_mfma_f32_16x16x32_bf16 v[116:119], v[186:189], v[202:205], v[116:119]
	v_mfma_f32_16x16x32_bf16 v[112:115], v[174:177], v[210:213], v[112:115]
	v_mfma_f32_16x16x32_bf16 v[108:111], v[186:189], v[210:213], v[108:111]
	v_mfma_f32_16x16x32_bf16 v[104:107], v[174:177], v[218:221], v[104:107]
	v_mfma_f32_16x16x32_bf16 v[100:103], v[186:189], v[218:221], v[100:103]
	s_barrier
; #define PG8_STAGE(bufoff, gbase, voff) do { _Pragma("unroll") for (int _i = 0; _i < 2; ++_i) \
;         __builtin_amdgcn_global_load_lds((const unsigned*)((const char*)(gbase) + (voff)[_i]), (PG8_LAS unsigned*)(lds + (bufoff) + ldsw + _i * 8192), 16, 0, 0); } while (0)
; #define PG8_LDA(dst, b, h) do { _Pragma("unroll") for (int m = 0; m < 4; ++m) _Pragma("unroll") for (int k = 0; k < 2; ++k) dst[m][k] = *(const PG8_LAS bf16x8*)(lds + PG8_SA(b, h) + aoff + m * 2048 + k * 1024); } while (0)
; #define PG8_LDB(dst, b, h) do { _Pragma("unroll") for (int n = 0; n < 2; ++n) _Pragma("unroll") for (int k = 0; k < 2; ++k) dst[n][k] = *(const PG8_LAS bf16x8*)(lds + PG8_SB(b, h) + boff + n * 2048 + k * 1024); } while (0)
; #define PG8_MMA(ai, bj, At, Bt) do { __builtin_amdgcn_s_setprio(1); _Pragma("unroll") for (int m = 0; m < 4; ++m) _Pragma("unroll") for (int n = 0; n < 2; ++n) _Pragma("unroll") for (int k = 0; k < 2; ++k) \
;         acc[ai][bj][m][n] = __builtin_amdgcn_mfma_f32_16x16x32_bf16(Bt[n][k], At[m][k], acc[ai][bj][m][n], 0, 0, 0); __builtin_amdgcn_s_setprio(0); } while (0)
; #define PG8_WAIT_V(n) asm volatile("s_waitcnt vmcnt(" #n ")" ::: "memory")
; template <class Epi, class Sched, bool ALIGN_EPI = false, bool SP2 = false>
; __device__ __forceinline__ void gemm_phase(PG8_LAS unsigned char* lds, const Gemm g, const Sched& S, const Epi& E) {
;     ...
;             PG8_LDB(B0, 0, 0); PG8_LDB(B1, 0, 1); PG8_SCHED; PG8_LDA(At, 0, 0); PG8_STAGE(PG8_SA(1, 1), a1 + hstep, voffA);
;             PG8_WAIT_V(8); PG8_WAIT_L(0); PG8_BAR; PG8_MMA(0, 0, At, B0); PG8_MMA(0, 1, At, B1); PG8_BAR; PG8_SCHED;
;             PG8_LDA(At, 0, 1); PG8_STAGE(PG8_SB(0, 0), b2, voffB); PG8_STAGE(PG8_SB(0, 1), b2 + hstep, voffB); PG8_STAGE(PG8_SA(0, 0), a2, voffA);
;             PG8_WAIT_V(8); PG8_WAIT_L(0); PG8_BAR; PG8_MMA(1, 0, At, B0); PG8_MMA(1, 1, At, B1); PG8_BAR; PG8_SCHED;
;             PG8_LDB(B0, 1, 0); PG8_LDB(B1, 1, 1); PG8_SCHED; PG8_LDA(At, 1, 0); PG8_STAGE(PG8_SA(0, 1), a2 + hstep, voffA);
;             PG8_WAIT_V(8); PG8_WAIT_L(0); PG8_BAR; PG8_MMA(0, 0, At, B0); PG8_MMA(0, 1, At, B1); PG8_BAR; PG8_SCHED;
;             PG8_LDA(At, 1, 1); PG8_STAGE(PG8_SB(1, 0), b3, voffB); PG8_STAGE(PG8_SB(1, 1), b3 + hstep, voffB); PG8_STAGE(PG8_SA(1, 0), a3, voffA);
;             PG8_WAIT_V(8); PG8_WAIT_L(0); PG8_BAR; PG8_MMA(1, 0, At, B0); PG8_MMA(1, 1, At, B1); PG8_BAR; PG8_SCHED;
	s_setprio 0
	s_add_i32 s26, s26, s44
	v_lshl_add_u64 v[146:147], v[146:147], 0, s[60:61]
	s_mov_b32 m0, s26
	ds_read_b128 v[190:193], v153 offset:49152
	ds_read_b128 v[194:197], v153 offset:50176
	ds_read_b128 v[198:201], v153 offset:51200
	ds_read_b128 v[202:205], v153 offset:52224
	ds_read_b128 v[206:209], v153 offset:53248
	ds_read_b128 v[210:213], v153 offset:54272
	ds_read_b128 v[214:217], v153 offset:55296
	ds_read_b128 v[218:221], v153 offset:56320
	global_load_lds_dwordx4 v[146:147], off
	s_add_i32 m0, s26, 0x2000
	s_add_u32 s38, s38, 0x80080
	v_lshl_add_u64 v[146:147], v[150:151], 0, s[60:61]
	s_addc_u32 s39, s39, 0
	s_add_i32 s26, s63, s44
	global_load_lds_dwordx4 v[146:147], off
	v_lshl_add_u64 v[146:147], s[38:39], 0, v[2:3]
	s_mov_b32 m0, s26
	s_nop 0
	global_load_lds_dwordx4 v[146:147], off
	v_lshl_add_u64 v[146:147], s[38:39], 0, v[132:133]
	s_add_i32 m0, s26, 0x2000
	s_nop 0
	global_load_lds_dwordx4 v[146:147], off
	v_lshl_add_u64 v[146:147], v[178:179], 0, s[60:61]
	s_mov_b32 m0, s51
	s_nop 0
	global_load_lds_dwordx4 v[146:147], off
	v_lshl_add_u64 v[146:147], v[222:223], 0, s[60:61]
	s_mov_b32 m0, s52
	s_nop 0
	global_load_lds_dwordx4 v[146:147], off
	s_waitcnt vmcnt(8)
	s_waitcnt lgkmcnt(0)
	s_setprio 1
	s_barrier
	v_mfma_f32_16x16x32_bf16 v[32:35], v[154:157], v[190:193], v[32:35]
	v_mfma_f32_16x16x32_bf16 v[28:31], v[162:165], v[190:193], v[28:31]
	v_mfma_f32_16x16x32_bf16 v[24:27], v[154:157], v[198:201], v[24:27]
	v_mfma_f32_16x16x32_bf16 v[20:23], v[162:165], v[198:201], v[20:23]
	v_mfma_f32_16x16x32_bf16 v[16:19], v[154:157], v[206:209], v[16:19]
	v_mfma_f32_16x16x32_bf16 v[12:15], v[162:165], v[206:209], v[12:15]
	v_mfma_f32_16x16x32_bf16 v[8:11], v[154:157], v[214:217], v[8:11]
	v_mfma_f32_16x16x32_bf16 v[4:7], v[162:165], v[214:217], v[4:7]
	v_mfma_f32_16x16x32_bf16 v[32:35], v[158:161], v[194:197], v[32:35]
	v_mfma_f32_16x16x32_bf16 v[28:31], v[166:169], v[194:197], v[28:31]
	v_mfma_f32_16x16x32_bf16 v[24:27], v[158:161], v[202:205], v[24:27]
	v_mfma_f32_16x16x32_bf16 v[20:23], v[166:169], v[202:205], v[20:23]
	v_mfma_f32_16x16x32_bf16 v[16:19], v[158:161], v[210:213], v[16:19]
	v_mfma_f32_16x16x32_bf16 v[12:15], v[166:169], v[210:213], v[12:15]
	v_mfma_f32_16x16x32_bf16 v[8:11], v[158:161], v[218:221], v[8:11]
	v_mfma_f32_16x16x32_bf16 v[4:7], v[166:169], v[218:221], v[4:7]
	s_setprio 0
	s_setprio 1
	v_mfma_f32_16x16x32_bf16 v[96:99], v[170:173], v[190:193], v[96:99]
	v_mfma_f32_16x16x32_bf16 v[92:95], v[182:185], v[190:193], v[92:95]
	v_mfma_f32_16x16x32_bf16 v[88:91], v[170:173], v[198:201], v[88:91]
	v_mfma_f32_16x16x32_bf16 v[84:87], v[182:185], v[198:201], v[84:87]
	v_mfma_f32_16x16x32_bf16 v[72:75], v[170:173], v[206:209], v[72:75]
	v_mfma_f32_16x16x32_bf16 v[68:71], v[182:185], v[206:209], v[68:71]
	v_mfma_f32_16x16x32_bf16 v[48:51], v[170:173], v[214:217], v[48:51]
	v_mfma_f32_16x16x32_bf16 v[40:43], v[182:185], v[214:217], v[40:43]
	v_mfma_f32_16x16x32_bf16 v[96:99], v[174:177], v[194:197], v[96:99]
	v_mfma_f32_16x16x32_bf16 v[92:95], v[186:189], v[194:197], v[92:95]
	v_mfma_f32_16x16x32_bf16 v[88:91], v[174:177], v[202:205], v[88:91]
	v_mfma_f32_16x16x32_bf16 v[84:87], v[186:189], v[202:205], v[84:87]
	v_mfma_f32_16x16x32_bf16 v[72:75], v[174:177], v[210:213], v[72:75]
	v_mfma_f32_16x16x32_bf16 v[68:71], v[186:189], v[210:213], v[68:71]
	v_mfma_f32_16x16x32_bf16 v[48:51], v[174:177], v[218:221], v[48:51]
	v_mfma_f32_16x16x32_bf16 v[40:43], v[186:189], v[218:221], v[40:43]
	s_barrier
	s_setprio 0
	s_add_i32 s62, s62, 2
	s_add_u32 s36, s36, 0x100
	s_addc_u32 s37, s37, 0
	s_add_u32 s56, s56, 0x100
	s_addc_u32 s57, s57, 0
	s_cmp_gt_u32 s62, 29
	s_cbranch_scc0 .LBB0_1167
	s_branch .Lpeel_post_p1
.LBB0_1167:
	s_add_u32 s26, s36, 0xfff80080
	s_addc_u32 s38, s37, -1
	s_add_i32 s63, 0, 0x10000
	s_cmp_eq_u32 s62, 28
	s_cselect_b32 s43, s17, s38
	s_cselect_b32 s42, s30, s26
	v_add_u32_e32 v144, s63, v145
	s_cselect_b32 s39, s15, s57
	s_cselect_b32 s38, s55, s56
	s_add_i32 s26, 0, 0x14000
	ds_read_b128 v[154:157], v144
	ds_read_b128 v[158:161], v144 offset:1024
	ds_read_b128 v[162:165], v144 offset:2048
	ds_read_b128 v[166:169], v144 offset:3072
	v_add_u32_e32 v144, s26, v145
	ds_read_b128 v[170:173], v144
	ds_read_b128 v[174:177], v144 offset:1024
	ds_read_b128 v[182:185], v144 offset:2048
	ds_read_b128 v[186:189], v144 offset:3072
	v_lshl_add_u64 v[146:147], s[36:37], 0, v[140:141]
	s_add_i32 m0, s45, 0xc000
	ds_read_b128 v[190:193], v153
	ds_read_b128 v[194:197], v153 offset:1024
	ds_read_b128 v[198:201], v153 offset:2048
	ds_read_b128 v[202:205], v153 offset:3072
	ds_read_b128 v[206:209], v153 offset:4096
	ds_read_b128 v[210:213], v153 offset:5120
	ds_read_b128 v[214:217], v153 offset:6144
	ds_read_b128 v[218:221], v153 offset:7168
	global_load_lds_dwordx4 v[146:147], off
	v_lshl_add_u64 v[146:147], s[36:37], 0, v[142:143]
	s_add_i32 m0, s45, 0xe000
	s_nop 0
	global_load_lds_dwordx4 v[146:147], off
	s_waitcnt vmcnt(8)
	s_waitcnt lgkmcnt(0)
	s_setprio 1
	s_barrier
; #define PG8_STAGE(bufoff, gbase, voff) do { _Pragma("unroll") for (int _i = 0; _i < 2; ++_i) \
;         __builtin_amdgcn_global_load_lds((const unsigned*)((const char*)(gbase) + (voff)[_i]), (PG8_LAS unsigned*)(lds + (bufoff) + ldsw + _i * 8192), 16, 0, 0); } while (0)
; #define PG8_LDA(dst, b, h) do { _Pragma("unroll") for (int m = 0; m < 4; ++m) _Pragma("unroll") for (int k = 0; k < 2; ++k) dst[m][k] = *(const PG8_LAS bf16x8*)(lds + PG8_SA(b, h) + aoff + m * 2048 + k * 1024); } while (0)
; #define PG8_MMA(ai, bj, At, Bt) do { __builtin_amdgcn_s_setprio(1); _Pragma("unroll") for (int m = 0; m < 4; ++m) _Pragma("unroll") for (int n = 0; n < 2; ++n) _Pragma("unroll") for (int k = 0; k < 2; ++k) \
;         acc[ai][bj][m][n] = __builtin_amdgcn_mfma_f32_16x16x32_bf16(Bt[n][k], At[m][k], acc[ai][bj][m][n], 0, 0, 0); __builtin_amdgcn_s_setprio(0); } while (0)
; #define PG8_WAIT_V(n) asm volatile("s_waitcnt vmcnt(" #n ")" ::: "memory")
; #define PG8_WAIT_L(n) asm volatile("s_waitcnt lgkmcnt(" #n ")" ::: "memory")
; #define PG8_BAR __builtin_amdgcn_s_barrier()
; #define PG8_SCHED __builtin_amdgcn_sched_barrier(0)
; template <class Epi, class Sched, bool ALIGN_EPI = false, bool SP2 = false>
; __device__ __forceinline__ void gemm_phase(PG8_LAS unsigned char* lds, const Gemm g, const Sched& S, const Epi& E) {
;     ...
;             PG8_WAIT_V(8); PG8_WAIT_L(0); PG8_BAR; PG8_MMA(0, 0, At, B0); PG8_MMA(0, 1, At, B1); PG8_BAR; PG8_SCHED;
;             PG8_LDA(At, 0, 1); PG8_STAGE(PG8_SB(0, 0), b2, voffB); PG8_STAGE(PG8_SB(0, 1), b2 + hstep, voffB); PG8_STAGE(PG8_SA(0, 0), a2, voffA);
;             PG8_WAIT_V(8); PG8_WAIT_L(0); PG8_BAR; PG8_MMA(1, 0, At, B0); PG8_MMA(1, 1, At, B1); PG8_BAR; PG8_SCHED;
	v_mfma_f32_16x16x32_bf16 v[80:83], v[154:157], v[190:193], v[80:83]
	v_mfma_f32_16x16x32_bf16 v[76:79], v[162:165], v[190:193], v[76:79]
	v_mfma_f32_16x16x32_bf16 v[64:67], v[154:157], v[198:201], v[64:67]
	v_mfma_f32_16x16x32_bf16 v[60:63], v[162:165], v[198:201], v[60:63]
	v_mfma_f32_16x16x32_bf16 v[56:59], v[154:157], v[206:209], v[56:59]
	v_mfma_f32_16x16x32_bf16 v[52:55], v[162:165], v[206:209], v[52:55]
	v_mfma_f32_16x16x32_bf16 v[44:47], v[154:157], v[214:217], v[44:47]
	v_mfma_f32_16x16x32_bf16 v[36:39], v[162:165], v[214:217], v[36:39]
	v_mfma_f32_16x16x32_bf16 v[80:83], v[158:161], v[194:197], v[80:83]
	v_mfma_f32_16x16x32_bf16 v[76:79], v[166:169], v[194:197], v[76:79]
	v_mfma_f32_16x16x32_bf16 v[64:67], v[158:161], v[202:205], v[64:67]
	v_mfma_f32_16x16x32_bf16 v[60:63], v[166:169], v[202:205], v[60:63]
	v_mfma_f32_16x16x32_bf16 v[56:59], v[158:161], v[210:213], v[56:59]
	v_mfma_f32_16x16x32_bf16 v[52:55], v[166:169], v[210:213], v[52:55]
	v_mfma_f32_16x16x32_bf16 v[44:47], v[158:161], v[218:221], v[44:47]
	v_mfma_f32_16x16x32_bf16 v[36:39], v[166:169], v[218:221], v[36:39]
	s_setprio 0
	s_setprio 1
	v_mfma_f32_16x16x32_bf16 v[128:131], v[170:173], v[190:193], v[128:131]
	v_mfma_f32_16x16x32_bf16 v[124:127], v[182:185], v[190:193], v[124:127]
	v_mfma_f32_16x16x32_bf16 v[120:123], v[170:173], v[198:201], v[120:123]
	v_mfma_f32_16x16x32_bf16 v[116:119], v[182:185], v[198:201], v[116:119]
	v_mfma_f32_16x16x32_bf16 v[112:115], v[170:173], v[206:209], v[112:115]
	v_mfma_f32_16x16x32_bf16 v[108:111], v[182:185], v[206:209], v[108:111]
	v_mfma_f32_16x16x32_bf16 v[104:107], v[170:173], v[214:217], v[104:107]
	v_mfma_f32_16x16x32_bf16 v[100:103], v[182:185], v[214:217], v[100:103]
	v_mfma_f32_16x16x32_bf16 v[128:131], v[174:177], v[194:197], v[128:131]
	v_mfma_f32_16x16x32_bf16 v[124:127], v[186:189], v[194:197], v[124:127]
	v_mfma_f32_16x16x32_bf16 v[120:123], v[174:177], v[202:205], v[120:123]
	v_mfma_f32_16x16x32_bf16 v[116:119], v[186:189], v[202:205], v[116:119]
	v_mfma_f32_16x16x32_bf16 v[112:115], v[174:177], v[210:213], v[112:115]
	v_mfma_f32_16x16x32_bf16 v[108:111], v[186:189], v[210:213], v[108:111]
	v_mfma_f32_16x16x32_bf16 v[104:107], v[174:177], v[218:221], v[104:107]
	v_mfma_f32_16x16x32_bf16 v[100:103], v[186:189], v[218:221], v[100:103]
	s_barrier
	s_setprio 0
	s_add_i32 s63, s63, s44
	v_lshl_add_u64 v[146:147], s[38:39], 0, v[2:3]
	s_mov_b32 m0, s63
	ds_read_b128 v[190:193], v153 offset:16384
	ds_read_b128 v[194:197], v153 offset:17408
	ds_read_b128 v[198:201], v153 offset:18432
	ds_read_b128 v[202:205], v153 offset:19456
	ds_read_b128 v[206:209], v153 offset:20480
	ds_read_b128 v[210:213], v153 offset:21504
	ds_read_b128 v[214:217], v153 offset:22528
	ds_read_b128 v[218:221], v153 offset:23552
	global_load_lds_dwordx4 v[146:147], off
	s_add_i32 m0, s63, 0x2000
	s_add_u32 s66, s38, 0x80000
	v_lshl_add_u64 v[150:151], s[38:39], 0, v[132:133]
	s_addc_u32 s67, s39, 0
	s_add_i32 s26, s26, s44
	global_load_lds_dwordx4 v[150:151], off
	v_lshl_add_u64 v[178:179], s[66:67], 0, v[2:3]
	s_mov_b32 m0, s26
	v_lshl_add_u64 v[222:223], s[42:43], 0, v[134:135]
	global_load_lds_dwordx4 v[178:179], off
	v_lshl_add_u64 v[178:179], s[66:67], 0, v[132:133]
	s_add_i32 m0, s26, 0x2000
	s_nop 0
	global_load_lds_dwordx4 v[178:179], off
	v_lshl_add_u64 v[178:179], s[42:43], 0, v[136:137]
	s_mov_b32 m0, s45
	s_nop 0
	global_load_lds_dwordx4 v[178:179], off
	s_mov_b32 m0, s46
	s_nop 0
	global_load_lds_dwordx4 v[222:223], off
	s_waitcnt vmcnt(8)
	s_waitcnt lgkmcnt(0)
	s_setprio 1
	s_barrier
	v_mfma_f32_16x16x32_bf16 v[32:35], v[154:157], v[190:193], v[32:35]
	v_mfma_f32_16x16x32_bf16 v[28:31], v[162:165], v[190:193], v[28:31]
	v_mfma_f32_16x16x32_bf16 v[24:27], v[154:157], v[198:201], v[24:27]
	v_mfma_f32_16x16x32_bf16 v[20:23], v[162:165], v[198:201], v[20:23]
	v_mfma_f32_16x16x32_bf16 v[16:19], v[154:157], v[206:209], v[16:19]
	v_mfma_f32_16x16x32_bf16 v[12:15], v[162:165], v[206:209], v[12:15]
	v_mfma_f32_16x16x32_bf16 v[8:11], v[154:157], v[214:217], v[8:11]
	v_mfma_f32_16x16x32_bf16 v[4:7], v[162:165], v[214:217], v[4:7]
	v_mfma_f32_16x16x32_bf16 v[32:35], v[158:161], v[194:197], v[32:35]
	v_mfma_f32_16x16x32_bf16 v[28:31], v[166:169], v[194:197], v[28:31]
	v_mfma_f32_16x16x32_bf16 v[24:27], v[158:161], v[202:205], v[24:27]
	v_mfma_f32_16x16x32_bf16 v[20:23], v[166:169], v[202:205], v[20:23]
	v_mfma_f32_16x16x32_bf16 v[16:19], v[158:161], v[210:213], v[16:19]
	v_mfma_f32_16x16x32_bf16 v[12:15], v[166:169], v[210:213], v[12:15]
	v_mfma_f32_16x16x32_bf16 v[8:11], v[158:161], v[218:221], v[8:11]
	v_mfma_f32_16x16x32_bf16 v[4:7], v[166:169], v[218:221], v[4:7]
	s_setprio 0
	s_setprio 1
	v_mfma_f32_16x16x32_bf16 v[96:99], v[170:173], v[190:193], v[96:99]
	v_mfma_f32_16x16x32_bf16 v[92:95], v[182:185], v[190:193], v[92:95]
	v_mfma_f32_16x16x32_bf16 v[88:91], v[170:173], v[198:201], v[88:91]
	v_mfma_f32_16x16x32_bf16 v[84:87], v[182:185], v[198:201], v[84:87]
	v_mfma_f32_16x16x32_bf16 v[72:75], v[170:173], v[206:209], v[72:75]
	v_mfma_f32_16x16x32_bf16 v[68:71], v[182:185], v[206:209], v[68:71]
	v_mfma_f32_16x16x32_bf16 v[48:51], v[170:173], v[214:217], v[48:51]
	v_mfma_f32_16x16x32_bf16 v[40:43], v[182:185], v[214:217], v[40:43]
	v_mfma_f32_16x16x32_bf16 v[96:99], v[174:177], v[194:197], v[96:99]
	v_mfma_f32_16x16x32_bf16 v[92:95], v[186:189], v[194:197], v[92:95]
	v_mfma_f32_16x16x32_bf16 v[88:91], v[174:177], v[202:205], v[88:91]
	v_mfma_f32_16x16x32_bf16 v[84:87], v[186:189], v[202:205], v[84:87]
	v_mfma_f32_16x16x32_bf16 v[72:75], v[174:177], v[210:213], v[72:75]
	v_mfma_f32_16x16x32_bf16 v[68:71], v[186:189], v[210:213], v[68:71]
	v_mfma_f32_16x16x32_bf16 v[48:51], v[174:177], v[218:221], v[48:51]
	v_mfma_f32_16x16x32_bf16 v[40:43], v[186:189], v[218:221], v[40:43]
	s_barrier
; #define PG8_STAGE(bufoff, gbase, voff) do { _Pragma("unroll") for (int _i = 0; _i < 2; ++_i) \
;         __builtin_amdgcn_global_load_lds((const unsigned*)((const char*)(gbase) + (voff)[_i]), (PG8_LAS unsigned*)(lds + (bufoff) + ldsw + _i * 8192), 16, 0, 0); } while (0)
; #define PG8_LDA(dst, b, h) do { _Pragma("unroll") for (int m = 0; m < 4; ++m) _Pragma("unroll") for (int k = 0; k < 2; ++k) dst[m][k] = *(const PG8_LAS bf16x8*)(lds + PG8_SA(b, h) + aoff + m * 2048 + k * 1024); } while (0)
; #define PG8_LDB(dst, b, h) do { _Pragma("unroll") for (int n = 0; n < 2; ++n) _Pragma("unroll") for (int k = 0; k < 2; ++k) dst[n][k] = *(const PG8_LAS bf16x8*)(lds + PG8_SB(b, h) + boff + n * 2048 + k * 1024); } while (0)
; #define PG8_MMA(ai, bj, At, Bt) do { __builtin_amdgcn_s_setprio(1); _Pragma("unroll") for (int m = 0; m < 4; ++m) _Pragma("unroll") for (int n = 0; n < 2; ++n) _Pragma("unroll") for (int k = 0; k < 2; ++k) \
;         acc[ai][bj][m][n] = __builtin_amdgcn_mfma_f32_16x16x32_bf16(Bt[n][k], At[m][k], acc[ai][bj][m][n], 0, 0, 0); __builtin_amdgcn_s_setprio(0); } while (0)
; #define PG8_WAIT_V(n) asm volatile("s_waitcnt vmcnt(" #n ")" ::: "memory")
; #define PG8_WAIT_L(n) asm volatile("s_waitcnt lgkmcnt(" #n ")" ::: "memory")
; #define PG8_BAR __builtin_amdgcn_s_barrier()
; #define PG8_SCHED __builtin_amdgcn_sched_barrier(0)
; template <class Epi, class Sched, bool ALIGN_EPI = false, bool SP2 = false>
; __device__ __forceinline__ void gemm_phase(PG8_LAS unsigned char* lds, const Gemm g, const Sched& S, const Epi& E) {
;     ...
;             PG8_LDB(B0, 1, 0); PG8_LDB(B1, 1, 1); PG8_SCHED; PG8_LDA(At, 1, 0); PG8_STAGE(PG8_SA(0, 1), a2 + hstep, voffA);
;             PG8_WAIT_V(8); PG8_WAIT_L(0); PG8_BAR; PG8_MMA(0, 0, At, B0); PG8_MMA(0, 1, At, B1); PG8_BAR; PG8_SCHED;
	s_setprio 0
	s_add_i32 s26, 0, 0x18000
	v_add_u32_e32 v144, s26, v145
	s_add_i32 s63, 0, 0x1c000
	ds_read_b128 v[154:157], v144
	ds_read_b128 v[158:161], v144 offset:1024
	ds_read_b128 v[162:165], v144 offset:2048
	ds_read_b128 v[166:169], v144 offset:3072
	v_add_u32_e32 v144, s63, v145
	ds_read_b128 v[170:173], v144
	ds_read_b128 v[174:177], v144 offset:1024
	ds_read_b128 v[182:185], v144 offset:2048
	ds_read_b128 v[186:189], v144 offset:3072
	s_add_u32 s42, s42, 0x80000
	s_addc_u32 s43, s43, 0
	s_mov_b32 m0, s47
	v_lshl_add_u64 v[224:225], s[42:43], 0, v[136:137]
	ds_read_b128 v[190:193], v153 offset:32768
	ds_read_b128 v[194:197], v153 offset:33792
	ds_read_b128 v[198:201], v153 offset:34816
	ds_read_b128 v[202:205], v153 offset:35840
	ds_read_b128 v[206:209], v153 offset:36864
	ds_read_b128 v[210:213], v153 offset:37888
	ds_read_b128 v[214:217], v153 offset:38912
	ds_read_b128 v[218:221], v153 offset:39936
	global_load_lds_dwordx4 v[224:225], off
	v_lshl_add_u64 v[224:225], s[42:43], 0, v[134:135]
	s_mov_b32 m0, s50
	s_nop 0
	global_load_lds_dwordx4 v[224:225], off
	s_waitcnt vmcnt(8)
	s_waitcnt lgkmcnt(0)
	s_setprio 1
	s_barrier
	v_mfma_f32_16x16x32_bf16 v[80:83], v[154:157], v[190:193], v[80:83]
	v_mfma_f32_16x16x32_bf16 v[76:79], v[162:165], v[190:193], v[76:79]
	v_mfma_f32_16x16x32_bf16 v[64:67], v[154:157], v[198:201], v[64:67]
	v_mfma_f32_16x16x32_bf16 v[60:63], v[162:165], v[198:201], v[60:63]
	v_mfma_f32_16x16x32_bf16 v[56:59], v[154:157], v[206:209], v[56:59]
	v_mfma_f32_16x16x32_bf16 v[52:55], v[162:165], v[206:209], v[52:55]
	v_mfma_f32_16x16x32_bf16 v[44:47], v[154:157], v[214:217], v[44:47]
	v_mfma_f32_16x16x32_bf16 v[36:39], v[162:165], v[214:217], v[36:39]
	v_mfma_f32_16x16x32_bf16 v[80:83], v[158:161], v[194:197], v[80:83]
	v_mfma_f32_16x16x32_bf16 v[76:79], v[166:169], v[194:197], v[76:79]
	v_mfma_f32_16x16x32_bf16 v[64:67], v[158:161], v[202:205], v[64:67]
	v_mfma_f32_16x16x32_bf16 v[60:63], v[166:169], v[202:205], v[60:63]
	v_mfma_f32_16x16x32_bf16 v[56:59], v[158:161], v[210:213], v[56:59]
	v_mfma_f32_16x16x32_bf16 v[52:55], v[166:169], v[210:213], v[52:55]
	v_mfma_f32_16x16x32_bf16 v[44:47], v[158:161], v[218:221], v[44:47]
	v_mfma_f32_16x16x32_bf16 v[36:39], v[166:169], v[218:221], v[36:39]
	s_setprio 0
	s_setprio 1
	v_mfma_f32_16x16x32_bf16 v[128:131], v[170:173], v[190:193], v[128:131]
	v_mfma_f32_16x16x32_bf16 v[124:127], v[182:185], v[190:193], v[124:127]
	v_mfma_f32_16x16x32_bf16 v[120:123], v[170:173], v[198:201], v[120:123]
	v_mfma_f32_16x16x32_bf16 v[116:119], v[182:185], v[198:201], v[116:119]
	v_mfma_f32_16x16x32_bf16 v[112:115], v[170:173], v[206:209], v[112:115]
	v_mfma_f32_16x16x32_bf16 v[108:111], v[182:185], v[206:209], v[108:111]
	v_mfma_f32_16x16x32_bf16 v[104:107], v[170:173], v[214:217], v[104:107]
	v_mfma_f32_16x16x32_bf16 v[100:103], v[182:185], v[214:217], v[100:103]
	v_mfma_f32_16x16x32_bf16 v[128:131], v[174:177], v[194:197], v[128:131]
	v_mfma_f32_16x16x32_bf16 v[124:127], v[186:189], v[194:197], v[124:127]
	v_mfma_f32_16x16x32_bf16 v[120:123], v[174:177], v[202:205], v[120:123]
	v_mfma_f32_16x16x32_bf16 v[116:119], v[186:189], v[202:205], v[116:119]
	v_mfma_f32_16x16x32_bf16 v[112:115], v[174:177], v[210:213], v[112:115]
	v_mfma_f32_16x16x32_bf16 v[108:111], v[186:189], v[210:213], v[108:111]
	v_mfma_f32_16x16x32_bf16 v[104:107], v[174:177], v[218:221], v[104:107]
	v_mfma_f32_16x16x32_bf16 v[100:103], v[186:189], v[218:221], v[100:103]
	s_barrier
; #define PG8_STAGE(bufoff, gbase, voff) do { _Pragma("unroll") for (int _i = 0; _i < 2; ++_i) \
;         __builtin_amdgcn_global_load_lds((const unsigned*)((const char*)(gbase) + (voff)[_i]), (PG8_LAS unsigned*)(lds + (bufoff) + ldsw + _i * 8192), 16, 0, 0); } while (0)
; #define PG8_LDA(dst, b, h) do { _Pragma("unroll") for (int m = 0; m < 4; ++m) _Pragma("unroll") for (int k = 0; k < 2; ++k) dst[m][k] = *(const PG8_LAS bf16x8*)(lds + PG8_SA(b, h) + aoff + m * 2048 + k * 1024); } while (0)
; #define PG8_MMA(ai, bj, At, Bt) do { __builtin_amdgcn_s_setprio(1); _Pragma("unroll") for (int m = 0; m < 4; ++m) _Pragma("unroll") for (int n = 0; n < 2; ++n) _Pragma("unroll") for (int k = 0; k < 2; ++k) \
;         acc[ai][bj][m][n] = __builtin_amdgcn_mfma_f32_16x16x32_bf16(Bt[n][k], At[m][k], acc[ai][bj][m][n], 0, 0, 0); __builtin_amdgcn_s_setprio(0); } while (0)
; #define PG8_WAIT_V(n) asm volatile("s_waitcnt vmcnt(" #n ")" ::: "memory")
; #define PG8_WAIT_L(n) asm volatile("s_waitcnt lgkmcnt(" #n ")" ::: "memory")
; #define PG8_BAR __builtin_amdgcn_s_barrier()
; #define PG8_SCHED __builtin_amdgcn_sched_barrier(0)
; template <class Epi, class Sched, bool ALIGN_EPI = false, bool SP2 = false>
; __device__ __forceinline__ void gemm_phase(PG8_LAS unsigned char* lds, const Gemm g, const Sched& S, const Epi& E) {
;     ...
;             PG8_LDA(At, 1, 1); PG8_STAGE(PG8_SB(1, 0), b3, voffB); PG8_STAGE(PG8_SB(1, 1), b3 + hstep, voffB); PG8_STAGE(PG8_SA(1, 0), a3, voffA);
;             PG8_WAIT_V(8); PG8_WAIT_L(0); PG8_BAR; PG8_MMA(1, 0, At, B0); PG8_MMA(1, 1, At, B1); PG8_BAR; PG8_SCHED;
;     ...
;         if constexpr (ALIGN_EPI) { if (wr == 0) PG8_BAR; }
	s_setprio 0
	s_add_i32 s26, s26, s44
	v_lshl_add_u64 v[146:147], v[146:147], 0, s[60:61]
	s_mov_b32 m0, s26
	ds_read_b128 v[190:193], v153 offset:49152
	ds_read_b128 v[194:197], v153 offset:50176
	ds_read_b128 v[198:201], v153 offset:51200
	ds_read_b128 v[202:205], v153 offset:52224
	ds_read_b128 v[206:209], v153 offset:53248
	ds_read_b128 v[210:213], v153 offset:54272
	ds_read_b128 v[214:217], v153 offset:55296
	ds_read_b128 v[218:221], v153 offset:56320
	global_load_lds_dwordx4 v[146:147], off
	s_add_i32 m0, s26, 0x2000
	s_add_u32 s38, s38, 0x80080
	v_lshl_add_u64 v[146:147], v[150:151], 0, s[60:61]
	s_addc_u32 s39, s39, 0
	s_add_i32 s26, s63, s44
	global_load_lds_dwordx4 v[146:147], off
	v_lshl_add_u64 v[146:147], s[38:39], 0, v[2:3]
	s_mov_b32 m0, s26
	s_nop 0
	global_load_lds_dwordx4 v[146:147], off
	v_lshl_add_u64 v[146:147], s[38:39], 0, v[132:133]
	s_add_i32 m0, s26, 0x2000
	s_nop 0
	global_load_lds_dwordx4 v[146:147], off
	v_lshl_add_u64 v[146:147], v[178:179], 0, s[60:61]
	s_mov_b32 m0, s51
	s_nop 0
	global_load_lds_dwordx4 v[146:147], off
	v_lshl_add_u64 v[146:147], v[222:223], 0, s[60:61]
	s_mov_b32 m0, s52
	s_nop 0
	global_load_lds_dwordx4 v[146:147], off
	s_waitcnt vmcnt(8)
	s_waitcnt lgkmcnt(0)
	s_setprio 1
	s_barrier
	v_mfma_f32_16x16x32_bf16 v[32:35], v[154:157], v[190:193], v[32:35]
	v_mfma_f32_16x16x32_bf16 v[28:31], v[162:165], v[190:193], v[28:31]
	v_mfma_f32_16x16x32_bf16 v[24:27], v[154:157], v[198:201], v[24:27]
	v_mfma_f32_16x16x32_bf16 v[20:23], v[162:165], v[198:201], v[20:23]
	v_mfma_f32_16x16x32_bf16 v[16:19], v[154:157], v[206:209], v[16:19]
	v_mfma_f32_16x16x32_bf16 v[12:15], v[162:165], v[206:209], v[12:15]
	v_mfma_f32_16x16x32_bf16 v[8:11], v[154:157], v[214:217], v[8:11]
	v_mfma_f32_16x16x32_bf16 v[4:7], v[162:165], v[214:217], v[4:7]
	v_mfma_f32_16x16x32_bf16 v[32:35], v[158:161], v[194:197], v[32:35]
	v_mfma_f32_16x16x32_bf16 v[28:31], v[166:169], v[194:197], v[28:31]
	v_mfma_f32_16x16x32_bf16 v[24:27], v[158:161], v[202:205], v[24:27]
	v_mfma_f32_16x16x32_bf16 v[20:23], v[166:169], v[202:205], v[20:23]
	v_mfma_f32_16x16x32_bf16 v[16:19], v[158:161], v[210:213], v[16:19]
	v_mfma_f32_16x16x32_bf16 v[12:15], v[166:169], v[210:213], v[12:15]
	v_mfma_f32_16x16x32_bf16 v[8:11], v[158:161], v[218:221], v[8:11]
	v_mfma_f32_16x16x32_bf16 v[4:7], v[166:169], v[218:221], v[4:7]
	s_setprio 0
	s_setprio 1
	v_mfma_f32_16x16x32_bf16 v[96:99], v[170:173], v[190:193], v[96:99]
	v_mfma_f32_16x16x32_bf16 v[92:95], v[182:185], v[190:193], v[92:95]
	v_mfma_f32_16x16x32_bf16 v[88:91], v[170:173], v[198:201], v[88:91]
	v_mfma_f32_16x16x32_bf16 v[84:87], v[182:185], v[198:201], v[84:87]
	v_mfma_f32_16x16x32_bf16 v[72:75], v[170:173], v[206:209], v[72:75]
	v_mfma_f32_16x16x32_bf16 v[68:71], v[182:185], v[206:209], v[68:71]
	v_mfma_f32_16x16x32_bf16 v[48:51], v[170:173], v[214:217], v[48:51]
	v_mfma_f32_16x16x32_bf16 v[40:43], v[182:185], v[214:217], v[40:43]
	v_mfma_f32_16x16x32_bf16 v[96:99], v[174:177], v[194:197], v[96:99]
	v_mfma_f32_16x16x32_bf16 v[92:95], v[186:189], v[194:197], v[92:95]
	v_mfma_f32_16x16x32_bf16 v[88:91], v[174:177], v[202:205], v[88:91]
	v_mfma_f32_16x16x32_bf16 v[84:87], v[186:189], v[202:205], v[84:87]
	v_mfma_f32_16x16x32_bf16 v[72:75], v[174:177], v[210:213], v[72:75]
	v_mfma_f32_16x16x32_bf16 v[68:71], v[186:189], v[210:213], v[68:71]
	v_mfma_f32_16x16x32_bf16 v[48:51], v[174:177], v[218:221], v[48:51]
	v_mfma_f32_16x16x32_bf16 v[40:43], v[186:189], v[218:221], v[40:43]
	s_barrier
	s_setprio 0
	s_add_i32 s62, s62, 2
	s_add_u32 s36, s36, 0x100
	s_addc_u32 s37, s37, 0
	s_add_u32 s56, s56, 0x100
	s_addc_u32 s57, s57, 0
	s_cmp_gt_u32 s62, 29
	s_cbranch_scc0 .LBB0_1167
.Lpeel_post_p1:
	s_and_b64 vcc, exec, s[10:11]
	s_cbranch_vccz .LBB0_1170
	s_barrier

; __device__ __forceinline__ float bf2f(bf16 v) { return __uint_as_float(((unsigned)v) << 16); }
; __device__ __forceinline__ float sigmoidf_(float x) { return 1.0f / (1.0f + __expf(-x)); }
; __device__ __forceinline__ unsigned cvt2(float lo, float hi) { f32x2 v = {lo, hi}; return __builtin_bit_cast(unsigned, __builtin_convertvector(v, bf16x2_t)); }
; __device__ __forceinline__ void ph_nsa_main(const bf16* __restrict__ NQ, const bf16* __restrict__ KS, const bf16* __restrict__ KW, const bf16* __restrict__ VST, const bf16* __restrict__ VWT, ...
;     ...
;         { const float l = lsum + __shfl_xor(lsum, 32); const float sc = sigmoidf_(small[m * 32 + SM_GC + 12 + head]) / l;
; #pragma unroll
;           for (int dt = 0; dt < 4; ++dt)
; #pragma unroll
;               for (int gq = 0; gq < 4; ++gq) { const int d = 32 * dt + 8 * gq + 4 * h;
;                   u32x2* mp = (u32x2*)(mix + m * D_MODEL + 1280 + head * 128 + d); const u32x2 pv = *mp;
;                   u32x2 w; w.x = cvt2(O[dt][4 * gq] * sc + bf2f((bf16)(pv.x & 0xffff)), O[dt][4 * gq + 1] * sc + bf2f((bf16)(pv.x >> 16)));
;                   w.y = cvt2(O[dt][4 * gq + 2] * sc + bf2f((bf16)(pv.y & 0xffff)), O[dt][4 * gq + 3] * sc + bf2f((bf16)(pv.y >> 16)));
;                   *mp = w; } }
.LBB0_1818:
	global_load_dword v1, v[190:191], off offset:96
	global_load_dwordx2 v[132:133], v[186:187], off
	global_load_dwordx2 v[134:135], v[186:187], off offset:16
	global_load_dwordx2 v[136:137], v[186:187], off offset:32
	global_load_dwordx2 v[138:139], v[186:187], off offset:48
	global_load_dwordx2 v[140:141], v[186:187], off offset:64
	global_load_dwordx2 v[142:143], v[186:187], off offset:80
	global_load_dwordx2 v[144:145], v[186:187], off offset:96
	global_load_dwordx2 v[146:147], v[186:187], off offset:112
	global_load_dwordx2 v[148:149], v[186:187], off offset:128
	global_load_dwordx2 v[150:151], v[186:187], off offset:144
	global_load_dwordx2 v[152:153], v[186:187], off offset:160
	global_load_dwordx2 v[154:155], v[186:187], off offset:176
	global_load_dwordx2 v[156:157], v[186:187], off offset:192
	global_load_dwordx2 v[158:159], v[186:187], off offset:208
	global_load_dwordx2 v[160:161], v[186:187], off offset:224
	global_load_dwordx2 v[162:163], v[186:187], off offset:240
	ds_bpermute_b32 v181, v182, v197
	s_movk_i32 s76, 0x2000
	s_movk_i32 s78, 0x4000
	s_movk_i32 s80, 0x6000
	s_mov_b32 s86, 0xa000
	s_mov_b32 s87, 0xc000
	s_mov_b32 s66, 0x3fb8aa3b
	s_waitcnt vmcnt(0)
	v_mul_f32_e32 v1, 0xbfb8aa3b, v1
	v_exp_f32_e32 v196, v1
	s_waitcnt lgkmcnt(0)
	v_pk_add_f32 v[68:69], v[196:197], v[180:181]
	s_nop 0
	v_div_scale_f32 v1, s[10:11], v68, v68, 1.0
	v_rcp_f32_e32 v2, v1
	s_nop 0
	v_fma_f32 v70, -v1, v2, 1.0
	v_fmac_f32_e32 v2, v70, v2
	v_div_scale_f32 v70, vcc, 1.0, v68, 1.0
	v_mul_f32_e32 v71, v70, v2
	v_fma_f32 v72, -v1, v71, v70
	v_fmac_f32_e32 v71, v72, v2
	v_fma_f32 v1, -v1, v71, v70
	v_div_fmas_f32 v1, v1, v2, v71
	v_div_fixup_f32 v1, v1, v68, 1.0
	v_div_scale_f32 v2, s[10:11], v69, v69, v1
	v_rcp_f32_e32 v68, v2
	s_mov_b64 s[10:11], 0
	v_fma_f32 v70, -v2, v68, 1.0
	v_fmac_f32_e32 v68, v70, v68
	v_div_scale_f32 v70, vcc, v1, v69, v1
	v_mul_f32_e32 v71, v70, v68
	v_fma_f32 v72, -v2, v71, v70
	v_fmac_f32_e32 v71, v72, v68
	v_fma_f32 v2, -v2, v71, v70
	v_div_fmas_f32 v2, v2, v68, v71
	v_div_fixup_f32 v2, v2, v69, v1
	v_mov_b64_e32 v[68:69], v[132:133]
	s_nop 0
	v_and_b32_e32 v71, 0xffff0000, v68
	v_lshlrev_b32_e32 v70, 16, v68
	v_pk_fma_f32 v[52:53], v[52:53], v[2:3], v[70:71] op_sel_hi:[1,0,1]
	v_and_b32_e32 v71, 0xffff0000, v69
	v_lshlrev_b32_e32 v70, 16, v69
	v_pk_fma_f32 v[54:55], v[54:55], v[2:3], v[70:71] op_sel_hi:[1,0,1]
	v_cvt_pk_bf16_f32 v52, v52, v53
	v_cvt_pk_bf16_f32 v53, v54, v55
	global_store_dwordx2 v[186:187], v[52:53], off
	v_mov_b64_e32 v[52:53], v[134:135]
	s_nop 0
	v_and_b32_e32 v55, 0xffff0000, v52
	v_lshlrev_b32_e32 v54, 16, v52
	v_pk_fma_f32 v[54:55], v[56:57], v[2:3], v[54:55] op_sel_hi:[1,0,1]
	s_nop 0
	v_cvt_pk_bf16_f32 v52, v54, v55
	v_and_b32_e32 v55, 0xffff0000, v53
	v_lshlrev_b32_e32 v54, 16, v53
	v_pk_fma_f32 v[54:55], v[58:59], v[2:3], v[54:55] op_sel_hi:[1,0,1]
	s_nop 0
	v_cvt_pk_bf16_f32 v53, v54, v55
	global_store_dwordx2 v[186:187], v[52:53], off offset:16
	v_mov_b64_e32 v[52:53], v[136:137]
	s_nop 0
	v_and_b32_e32 v55, 0xffff0000, v52
	v_lshlrev_b32_e32 v54, 16, v52
	v_pk_fma_f32 v[54:55], v[60:61], v[2:3], v[54:55] op_sel_hi:[1,0,1]
	s_nop 0
	v_cvt_pk_bf16_f32 v52, v54, v55
	v_and_b32_e32 v55, 0xffff0000, v53
	v_lshlrev_b32_e32 v54, 16, v53
	v_pk_fma_f32 v[54:55], v[62:63], v[2:3], v[54:55] op_sel_hi:[1,0,1]
	s_nop 0
	v_cvt_pk_bf16_f32 v53, v54, v55
	global_store_dwordx2 v[186:187], v[52:53], off offset:32
	v_mov_b64_e32 v[52:53], v[138:139]
	s_nop 0
	v_and_b32_e32 v55, 0xffff0000, v52
	v_lshlrev_b32_e32 v54, 16, v52
	v_pk_fma_f32 v[54:55], v[64:65], v[2:3], v[54:55] op_sel_hi:[1,0,1]
	s_nop 0
	v_cvt_pk_bf16_f32 v52, v54, v55
	v_and_b32_e32 v55, 0xffff0000, v53
	v_lshlrev_b32_e32 v54, 16, v53
	v_pk_fma_f32 v[54:55], v[66:67], v[2:3], v[54:55] op_sel_hi:[1,0,1]
	s_nop 0
	v_cvt_pk_bf16_f32 v53, v54, v55
	global_store_dwordx2 v[186:187], v[52:53], off offset:48
	v_mov_b64_e32 v[52:53], v[140:141]
	s_nop 0
	v_and_b32_e32 v55, 0xffff0000, v52
	v_lshlrev_b32_e32 v54, 16, v52
	v_pk_fma_f32 v[36:37], v[36:37], v[2:3], v[54:55] op_sel_hi:[1,0,1]
	v_and_b32_e32 v55, 0xffff0000, v53
	v_lshlrev_b32_e32 v54, 16, v53
	v_pk_fma_f32 v[38:39], v[38:39], v[2:3], v[54:55] op_sel_hi:[1,0,1]
	v_cvt_pk_bf16_f32 v36, v36, v37
	v_cvt_pk_bf16_f32 v37, v38, v39
	global_store_dwordx2 v[186:187], v[36:37], off offset:64
	v_mov_b64_e32 v[36:37], v[142:143]
	s_nop 0
	v_and_b32_e32 v39, 0xffff0000, v36
	v_lshlrev_b32_e32 v38, 16, v36
	v_pk_fma_f32 v[38:39], v[40:41], v[2:3], v[38:39] op_sel_hi:[1,0,1]
	s_nop 0
	v_cvt_pk_bf16_f32 v36, v38, v39
	v_and_b32_e32 v39, 0xffff0000, v37
	v_lshlrev_b32_e32 v38, 16, v37
; __device__ __forceinline__ float bf2f(bf16 v) { return __uint_as_float(((unsigned)v) << 16); }
; __device__ __forceinline__ unsigned cvt2(float lo, float hi) { f32x2 v = {lo, hi}; return __builtin_bit_cast(unsigned, __builtin_convertvector(v, bf16x2_t)); }
; __device__ __forceinline__ void ph_nsa_main(const bf16* __restrict__ NQ, const bf16* __restrict__ KS, const bf16* __restrict__ KW, const bf16* __restrict__ VST, const bf16* __restrict__ VWT, ...
;     ...
;           for (int dt = 0; dt < 4; ++dt)
; #pragma unroll
;               for (int gq = 0; gq < 4; ++gq) { const int d = 32 * dt + 8 * gq + 4 * h;
;                   u32x2* mp = (u32x2*)(mix + m * D_MODEL + 1280 + head * 128 + d); const u32x2 pv = *mp;
;                   u32x2 w; w.x = cvt2(O[dt][4 * gq] * sc + bf2f((bf16)(pv.x & 0xffff)), O[dt][4 * gq + 1] * sc + bf2f((bf16)(pv.x >> 16)));
;                   w.y = cvt2(O[dt][4 * gq + 2] * sc + bf2f((bf16)(pv.y & 0xffff)), O[dt][4 * gq + 3] * sc + bf2f((bf16)(pv.y >> 16)));
;                   *mp = w; } }
	v_pk_fma_f32 v[38:39], v[42:43], v[2:3], v[38:39] op_sel_hi:[1,0,1]
	s_nop 0
	v_cvt_pk_bf16_f32 v37, v38, v39
	global_store_dwordx2 v[186:187], v[36:37], off offset:80
	v_mov_b64_e32 v[36:37], v[144:145]
	s_nop 0
	v_and_b32_e32 v39, 0xffff0000, v36
	v_lshlrev_b32_e32 v38, 16, v36
	v_pk_fma_f32 v[38:39], v[44:45], v[2:3], v[38:39] op_sel_hi:[1,0,1]
	s_nop 0
	v_cvt_pk_bf16_f32 v36, v38, v39
	v_and_b32_e32 v39, 0xffff0000, v37
	v_lshlrev_b32_e32 v38, 16, v37
	v_pk_fma_f32 v[38:39], v[46:47], v[2:3], v[38:39] op_sel_hi:[1,0,1]
	s_nop 0
	v_cvt_pk_bf16_f32 v37, v38, v39
	global_store_dwordx2 v[186:187], v[36:37], off offset:96
	v_mov_b64_e32 v[36:37], v[146:147]
	s_nop 0
	v_and_b32_e32 v39, 0xffff0000, v36
	v_lshlrev_b32_e32 v38, 16, v36
	v_pk_fma_f32 v[38:39], v[48:49], v[2:3], v[38:39] op_sel_hi:[1,0,1]
	s_nop 0
	v_cvt_pk_bf16_f32 v36, v38, v39
	v_and_b32_e32 v39, 0xffff0000, v37
	v_lshlrev_b32_e32 v38, 16, v37
	v_pk_fma_f32 v[38:39], v[50:51], v[2:3], v[38:39] op_sel_hi:[1,0,1]
	s_nop 0
	v_cvt_pk_bf16_f32 v37, v38, v39
	global_store_dwordx2 v[186:187], v[36:37], off offset:112
	v_mov_b64_e32 v[36:37], v[148:149]
	s_nop 0
	v_and_b32_e32 v39, 0xffff0000, v36
	v_lshlrev_b32_e32 v38, 16, v36
	v_pk_fma_f32 v[20:21], v[20:21], v[2:3], v[38:39] op_sel_hi:[1,0,1]
	v_and_b32_e32 v39, 0xffff0000, v37
	v_lshlrev_b32_e32 v38, 16, v37
	v_pk_fma_f32 v[22:23], v[22:23], v[2:3], v[38:39] op_sel_hi:[1,0,1]
	v_cvt_pk_bf16_f32 v20, v20, v21
	v_cvt_pk_bf16_f32 v21, v22, v23
	global_store_dwordx2 v[186:187], v[20:21], off offset:128
	v_mov_b64_e32 v[20:21], v[150:151]
	s_nop 0
	v_and_b32_e32 v23, 0xffff0000, v20
	v_lshlrev_b32_e32 v22, 16, v20
	v_pk_fma_f32 v[22:23], v[24:25], v[2:3], v[22:23] op_sel_hi:[1,0,1]
	s_nop 0
	v_cvt_pk_bf16_f32 v20, v22, v23
	v_and_b32_e32 v23, 0xffff0000, v21
	v_lshlrev_b32_e32 v22, 16, v21
	v_pk_fma_f32 v[22:23], v[26:27], v[2:3], v[22:23] op_sel_hi:[1,0,1]
	s_nop 0
	v_cvt_pk_bf16_f32 v21, v22, v23
	global_store_dwordx2 v[186:187], v[20:21], off offset:144
	v_mov_b64_e32 v[20:21], v[152:153]
	s_nop 0
	v_and_b32_e32 v23, 0xffff0000, v20
	v_lshlrev_b32_e32 v22, 16, v20
	v_pk_fma_f32 v[22:23], v[28:29], v[2:3], v[22:23] op_sel_hi:[1,0,1]
	s_nop 0
	v_cvt_pk_bf16_f32 v20, v22, v23
	v_and_b32_e32 v23, 0xffff0000, v21
	v_lshlrev_b32_e32 v22, 16, v21
	v_pk_fma_f32 v[22:23], v[30:31], v[2:3], v[22:23] op_sel_hi:[1,0,1]
	s_nop 0
	v_cvt_pk_bf16_f32 v21, v22, v23
	global_store_dwordx2 v[186:187], v[20:21], off offset:160
	v_mov_b64_e32 v[20:21], v[154:155]
	s_nop 0
	v_and_b32_e32 v23, 0xffff0000, v20
	v_lshlrev_b32_e32 v22, 16, v20
	v_pk_fma_f32 v[22:23], v[32:33], v[2:3], v[22:23] op_sel_hi:[1,0,1]
	s_nop 0
	v_cvt_pk_bf16_f32 v20, v22, v23
	v_and_b32_e32 v23, 0xffff0000, v21
	v_lshlrev_b32_e32 v22, 16, v21
	v_pk_fma_f32 v[22:23], v[34:35], v[2:3], v[22:23] op_sel_hi:[1,0,1]
	s_nop 0
	v_cvt_pk_bf16_f32 v21, v22, v23
	global_store_dwordx2 v[186:187], v[20:21], off offset:176
	v_mov_b64_e32 v[20:21], v[156:157]
	s_nop 0
	v_and_b32_e32 v23, 0xffff0000, v20
	v_lshlrev_b32_e32 v22, 16, v20
	v_pk_fma_f32 v[4:5], v[4:5], v[2:3], v[22:23] op_sel_hi:[1,0,1]
	v_and_b32_e32 v23, 0xffff0000, v21
	v_lshlrev_b32_e32 v22, 16, v21
	v_pk_fma_f32 v[6:7], v[6:7], v[2:3], v[22:23] op_sel_hi:[1,0,1]
	v_cvt_pk_bf16_f32 v4, v4, v5
	v_cvt_pk_bf16_f32 v5, v6, v7
	global_store_dwordx2 v[186:187], v[4:5], off offset:192
	v_mov_b64_e32 v[4:5], v[158:159]
	s_nop 0
	v_and_b32_e32 v7, 0xffff0000, v4
	v_lshlrev_b32_e32 v6, 16, v4
	v_pk_fma_f32 v[6:7], v[8:9], v[2:3], v[6:7] op_sel_hi:[1,0,1]
	s_nop 0
	v_cvt_pk_bf16_f32 v4, v6, v7
	v_and_b32_e32 v7, 0xffff0000, v5
	v_lshlrev_b32_e32 v6, 16, v5
	v_pk_fma_f32 v[6:7], v[10:11], v[2:3], v[6:7] op_sel_hi:[1,0,1]
	s_nop 0
	v_cvt_pk_bf16_f32 v5, v6, v7
	global_store_dwordx2 v[186:187], v[4:5], off offset:208
	v_mov_b64_e32 v[4:5], v[160:161]
	s_nop 0
	v_and_b32_e32 v7, 0xffff0000, v4
	v_lshlrev_b32_e32 v6, 16, v4
	v_pk_fma_f32 v[6:7], v[12:13], v[2:3], v[6:7] op_sel_hi:[1,0,1]
	s_nop 0
	v_cvt_pk_bf16_f32 v4, v6, v7
	v_and_b32_e32 v7, 0xffff0000, v5
	v_lshlrev_b32_e32 v6, 16, v5
	v_pk_fma_f32 v[6:7], v[14:15], v[2:3], v[6:7] op_sel_hi:[1,0,1]
	s_nop 0
	v_cvt_pk_bf16_f32 v5, v6, v7
	global_store_dwordx2 v[186:187], v[4:5], off offset:224
	v_mov_b64_e32 v[4:5], v[162:163]
	s_nop 0
	v_and_b32_e32 v7, 0xffff0000, v4
	v_lshlrev_b32_e32 v6, 16, v4
	v_pk_fma_f32 v[6:7], v[16:17], v[2:3], v[6:7] op_sel_hi:[1,0,1]
	s_nop 0
	v_cvt_pk_bf16_f32 v4, v6, v7
	v_and_b32_e32 v7, 0xffff0000, v5
	v_lshlrev_b32_e32 v6, 16, v5
	v_pk_fma_f32 v[6:7], v[18:19], v[2:3], v[6:7] op_sel_hi:[1,0,1]
	s_nop 0
	v_cvt_pk_bf16_f32 v5, v6, v7
	global_store_dwordx2 v[186:187], v[4:5], off offset:240

; #define PG8_STAGE(bufoff, gbase, voff) do { _Pragma("unroll") for (int _i = 0; _i < 2; ++_i) \
;         __builtin_amdgcn_global_load_lds((const unsigned*)((const char*)(gbase) + (voff)[_i]), (PG8_LAS unsigned*)(lds + (bufoff) + ldsw + _i * 8192), 16, 0, 0); } while (0)
; #define PG8_LDA(dst, b, h) do { _Pragma("unroll") for (int m = 0; m < 4; ++m) _Pragma("unroll") for (int k = 0; k < 2; ++k) dst[m][k] = *(const PG8_LAS bf16x8*)(lds + PG8_SA(b, h) + aoff + m * 2048 + k * 1024); } while (0)
; #define PG8_LDB(dst, b, h) do { _Pragma("unroll") for (int n = 0; n < 2; ++n) _Pragma("unroll") for (int k = 0; k < 2; ++k) dst[n][k] = *(const PG8_LAS bf16x8*)(lds + PG8_SB(b, h) + boff + n * 2048 + k * 1024); } while (0)
; template <class Epi, class Sched, bool ALIGN_EPI = false, bool SP2 = false>
; __device__ __forceinline__ void gemm_phase(PG8_LAS unsigned char* lds, const Gemm g, const Sched& S, const Epi& E) {
;     ...
;         const bool has_next = S.next(ui + 1, nxt);
;         const char* nA = has_next ? (const char*)g.A + (size_t)nxt.pm * tstep : cA; const char* nB = has_next ? (const char*)g.Bt + (size_t)nxt.pn * tstep : cB;
;         for (int t = 0; t < nt; t += 2) {
;             const bool last = (t == nt - 2);
;             const char* a1 = cA + (size_t)(t + 1) * kstep;
;             const char* a2 = last ? nA : cA + (size_t)(t + 2) * kstep; const char* b2 = last ? nB : cB + (size_t)(t + 2) * kstep;
;             const char* a3 = a2 + kstep; const char* b3 = b2 + kstep;
;             if (last && has_next) S.a_ready(nxt);
;             if constexpr (SP2) {
;             PG8_LDB(B0, 0, 0); PG8_LDB(B1, 0, 1); PG8_SCHED; PG8_LDA(At, 0, 0); PG8_STAGE(PG8_SA(1, 1), a1 + hstep, voffA);
;             PG8_WAIT_V(8); PG8_WAIT_L(0); PG8_BAR; PG8_MMA(0, 0, At, B0); PG8_MMA(0, 1, At, B1); PG8_BAR; PG8_SCHED;
;             PG8_LDA(At, 0, 1); PG8_STAGE(PG8_SB(0, 0), b2, voffB); PG8_STAGE(PG8_SB(0, 1), b2 + hstep, voffB); PG8_STAGE(PG8_SA(0, 0), a2, voffA);
;             PG8_WAIT_V(8); PG8_WAIT_L(0); PG8_BAR; PG8_MMA(1, 0, At, B0); PG8_MMA(1, 1, At, B1); PG8_BAR; PG8_SCHED;
;     ...
; #pragma unroll
;         for (int a = 0; a < 2; ++a)
; #pragma unroll
;             for (int b = 0; b < 2; ++b)
; #pragma unroll
;                 for (int m = 0; m < 4; ++m)
; #pragma unroll
;                     for (int n = 0; n < 2; ++n) acc[a][b][m][n] = (f32x4){0.f, 0.f, 0.f, 0.f};
.LBB0_1960:
	s_ashr_i32 s21, s20, 31
	s_lshl_b64 s[34:35], s[20:21], 20
	s_add_u32 s34, s2, s34
	s_addc_u32 s35, s3, s35
	s_and_b64 s[36:37], s[6:7], exec
	s_cselect_b32 s21, s35, s39
	s_cselect_b32 s57, s34, s38
	s_ashr_i32 s19, s18, 31
	s_lshl_b64 s[36:37], s[18:19], 20
	s_add_u32 s36, s29, s36
	s_addc_u32 s37, s40, s37
	s_and_b64 s[44:45], s[6:7], exec
	s_cselect_b32 s19, s37, s43
	s_cselect_b32 s62, s36, s42
	s_add_u32 s38, s38, 0x80080
	s_addc_u32 s39, s39, 0
	s_add_u32 s63, s42, 0x100
	s_addc_u32 s64, s43, 0
	s_mov_b32 s66, -2
	s_waitcnt lgkmcnt(0)
	s_add_u32 s26, s38, 0xfff80080
	s_addc_u32 s31, s39, -1
	s_add_i32 s67, 0, 0x10000
	s_cmp_eq_u32 s66, 28
	s_cselect_b32 s45, s21, s31
	s_cselect_b32 s44, s57, s26
	s_cselect_b32 s43, s19, s64
	s_cselect_b32 s42, s62, s63
	s_add_i32 s26, 0, 0x14000
	v_add_u32_e32 v128, s67, v178
	v_add_u32_e32 v170, s26, v178
	ds_read_b128 v[116:119], v128
	ds_read_b128 v[120:123], v128 offset:1024
	ds_read_b128 v[124:127], v128 offset:2048
	ds_read_b128 v[128:131], v128 offset:3072
	ds_read_b128 v[132:135], v170
	ds_read_b128 v[136:139], v170 offset:1024
	ds_read_b128 v[166:169], v170 offset:2048
	ds_read_b128 v[170:173], v170 offset:3072
	v_lshl_add_u64 v[210:211], s[38:39], 0, v[162:163]
	s_add_i32 m0, s47, 0xc000
	ds_read_b128 v[174:177], v181
	ds_read_b128 v[182:185], v181 offset:1024
	ds_read_b128 v[186:189], v181 offset:2048
	ds_read_b128 v[190:193], v181 offset:3072
	ds_read_b128 v[194:197], v181 offset:4096
	ds_read_b128 v[198:201], v181 offset:5120
	ds_read_b128 v[202:205], v181 offset:6144
	ds_read_b128 v[206:209], v181 offset:7168
	global_load_lds_dwordx4 v[210:211], off
	v_lshl_add_u64 v[210:211], s[38:39], 0, v[164:165]
	s_add_i32 m0, s47, 0xe000
	s_nop 0
	global_load_lds_dwordx4 v[210:211], off
	s_waitcnt vmcnt(8)
	s_waitcnt lgkmcnt(0)
	s_setprio 1
	s_barrier
	v_mfma_f32_16x16x32_bf16 v[152:155], v[116:119], v[174:177], 0
	v_mfma_f32_16x16x32_bf16 v[148:151], v[124:127], v[174:177], 0
	v_mfma_f32_16x16x32_bf16 v[112:115], v[116:119], v[186:189], 0
	v_mfma_f32_16x16x32_bf16 v[108:111], v[124:127], v[186:189], 0
	v_mfma_f32_16x16x32_bf16 v[96:99], v[116:119], v[194:197], 0
	v_mfma_f32_16x16x32_bf16 v[92:95], v[124:127], v[194:197], 0
	v_mfma_f32_16x16x32_bf16 v[80:83], v[116:119], v[202:205], 0
	v_mfma_f32_16x16x32_bf16 v[76:79], v[124:127], v[202:205], 0
	v_mfma_f32_16x16x32_bf16 v[152:155], v[120:123], v[182:185], v[152:155]
	v_mfma_f32_16x16x32_bf16 v[148:151], v[128:131], v[182:185], v[148:151]
	v_mfma_f32_16x16x32_bf16 v[112:115], v[120:123], v[190:193], v[112:115]
	v_mfma_f32_16x16x32_bf16 v[108:111], v[128:131], v[190:193], v[108:111]
	v_mfma_f32_16x16x32_bf16 v[96:99], v[120:123], v[198:201], v[96:99]
	v_mfma_f32_16x16x32_bf16 v[92:95], v[128:131], v[198:201], v[92:95]
	v_mfma_f32_16x16x32_bf16 v[80:83], v[120:123], v[206:209], v[80:83]
	v_mfma_f32_16x16x32_bf16 v[76:79], v[128:131], v[206:209], v[76:79]
	s_setprio 0
	s_setprio 1
	v_mfma_f32_16x16x32_bf16 v[144:147], v[132:135], v[174:177], 0
	v_mfma_f32_16x16x32_bf16 v[140:143], v[166:169], v[174:177], 0
	v_mfma_f32_16x16x32_bf16 v[104:107], v[132:135], v[186:189], 0
	v_mfma_f32_16x16x32_bf16 v[100:103], v[166:169], v[186:189], 0
	v_mfma_f32_16x16x32_bf16 v[88:91], v[132:135], v[194:197], 0
	v_mfma_f32_16x16x32_bf16 v[84:87], v[166:169], v[194:197], 0
	v_mfma_f32_16x16x32_bf16 v[72:75], v[132:135], v[202:205], 0
	v_mfma_f32_16x16x32_bf16 v[68:71], v[166:169], v[202:205], 0
	v_mfma_f32_16x16x32_bf16 v[144:147], v[136:139], v[182:185], v[144:147]
	v_mfma_f32_16x16x32_bf16 v[140:143], v[170:173], v[182:185], v[140:143]
	v_mfma_f32_16x16x32_bf16 v[104:107], v[136:139], v[190:193], v[104:107]
	v_mfma_f32_16x16x32_bf16 v[100:103], v[170:173], v[190:193], v[100:103]
	v_mfma_f32_16x16x32_bf16 v[88:91], v[136:139], v[198:201], v[88:91]
	v_mfma_f32_16x16x32_bf16 v[84:87], v[170:173], v[198:201], v[84:87]
	v_mfma_f32_16x16x32_bf16 v[72:75], v[136:139], v[206:209], v[72:75]
	v_mfma_f32_16x16x32_bf16 v[68:71], v[170:173], v[206:209], v[68:71]
	s_barrier
	s_setprio 0
	s_add_i32 s31, s67, s46
	v_lshl_add_u64 v[210:211], s[42:43], 0, v[2:3]
	s_mov_b32 m0, s31
	ds_read_b128 v[174:177], v181 offset:16384
	ds_read_b128 v[182:185], v181 offset:17408
	ds_read_b128 v[186:189], v181 offset:18432
	ds_read_b128 v[190:193], v181 offset:19456
	ds_read_b128 v[194:197], v181 offset:20480
	ds_read_b128 v[198:201], v181 offset:21504
	ds_read_b128 v[202:205], v181 offset:22528
	ds_read_b128 v[206:209], v181 offset:23552
	global_load_lds_dwordx4 v[210:211], off
	s_add_i32 m0, s31, 0x2000
	s_add_u32 s68, s42, 0x80000
	v_lshl_add_u64 v[212:213], s[42:43], 0, v[156:157]
	s_addc_u32 s69, s43, 0
	s_add_i32 s26, s26, s46
	global_load_lds_dwordx4 v[212:213], off
	v_lshl_add_u64 v[214:215], s[68:69], 0, v[2:3]
	s_mov_b32 m0, s26
	v_lshl_add_u64 v[216:217], s[44:45], 0, v[158:159]
	global_load_lds_dwordx4 v[214:215], off
	v_lshl_add_u64 v[214:215], s[68:69], 0, v[156:157]
	s_add_i32 m0, s26, 0x2000
	s_nop 0
	global_load_lds_dwordx4 v[214:215], off
	v_lshl_add_u64 v[214:215], s[44:45], 0, v[160:161]
	s_mov_b32 m0, s47
	s_nop 0
	global_load_lds_dwordx4 v[214:215], off
	s_mov_b32 m0, s50
	s_nop 0
	global_load_lds_dwordx4 v[216:217], off
	s_waitcnt vmcnt(8)
	s_waitcnt lgkmcnt(0)
	s_setprio 1
	s_barrier
; #define PG8_STAGE(bufoff, gbase, voff) do { _Pragma("unroll") for (int _i = 0; _i < 2; ++_i) \
;         __builtin_amdgcn_global_load_lds((const unsigned*)((const char*)(gbase) + (voff)[_i]), (PG8_LAS unsigned*)(lds + (bufoff) + ldsw + _i * 8192), 16, 0, 0); } while (0)
; #define PG8_LDA(dst, b, h) do { _Pragma("unroll") for (int m = 0; m < 4; ++m) _Pragma("unroll") for (int k = 0; k < 2; ++k) dst[m][k] = *(const PG8_LAS bf16x8*)(lds + PG8_SA(b, h) + aoff + m * 2048 + k * 1024); } while (0)
; #define PG8_LDB(dst, b, h) do { _Pragma("unroll") for (int n = 0; n < 2; ++n) _Pragma("unroll") for (int k = 0; k < 2; ++k) dst[n][k] = *(const PG8_LAS bf16x8*)(lds + PG8_SB(b, h) + boff + n * 2048 + k * 1024); } while (0)
; #define PG8_MMA(ai, bj, At, Bt) do { __builtin_amdgcn_s_setprio(1); _Pragma("unroll") for (int m = 0; m < 4; ++m) _Pragma("unroll") for (int n = 0; n < 2; ++n) _Pragma("unroll") for (int k = 0; k < 2; ++k) \
;         acc[ai][bj][m][n] = __builtin_amdgcn_mfma_f32_16x16x32_bf16(Bt[n][k], At[m][k], acc[ai][bj][m][n], 0, 0, 0); __builtin_amdgcn_s_setprio(0); } while (0)
; #define PG8_WAIT_V(n) asm volatile("s_waitcnt vmcnt(" #n ")" ::: "memory")
; #define PG8_WAIT_L(n) asm volatile("s_waitcnt lgkmcnt(" #n ")" ::: "memory")
; #define PG8_BAR __builtin_amdgcn_s_barrier()
; #define PG8_SCHED __builtin_amdgcn_sched_barrier(0)
; template <class Epi, class Sched, bool ALIGN_EPI = false, bool SP2 = false>
; __device__ __forceinline__ void gemm_phase(PG8_LAS unsigned char* lds, const Gemm g, const Sched& S, const Epi& E) {
;     ...
;             PG8_WAIT_V(8); PG8_WAIT_L(0); PG8_BAR; PG8_MMA(1, 0, At, B0); PG8_MMA(1, 1, At, B1); PG8_BAR; PG8_SCHED;
;             PG8_LDB(B0, 1, 0); PG8_LDB(B1, 1, 1); PG8_SCHED; PG8_LDA(At, 1, 0); PG8_STAGE(PG8_SA(0, 1), a2 + hstep, voffA);
;             PG8_WAIT_V(8); PG8_WAIT_L(0); PG8_BAR; PG8_MMA(0, 0, At, B0); PG8_MMA(0, 1, At, B1); PG8_BAR; PG8_SCHED;
	v_mfma_f32_16x16x32_bf16 v[64:67], v[116:119], v[174:177], 0
	v_mfma_f32_16x16x32_bf16 v[60:63], v[124:127], v[174:177], 0
	v_mfma_f32_16x16x32_bf16 v[48:51], v[116:119], v[186:189], 0
	v_mfma_f32_16x16x32_bf16 v[44:47], v[124:127], v[186:189], 0
	v_mfma_f32_16x16x32_bf16 v[32:35], v[116:119], v[194:197], 0
	v_mfma_f32_16x16x32_bf16 v[28:31], v[124:127], v[194:197], 0
	v_mfma_f32_16x16x32_bf16 v[16:19], v[116:119], v[202:205], 0
	v_mfma_f32_16x16x32_bf16 v[12:15], v[124:127], v[202:205], 0
	v_mfma_f32_16x16x32_bf16 v[64:67], v[120:123], v[182:185], v[64:67]
	v_mfma_f32_16x16x32_bf16 v[60:63], v[128:131], v[182:185], v[60:63]
	v_mfma_f32_16x16x32_bf16 v[48:51], v[120:123], v[190:193], v[48:51]
	v_mfma_f32_16x16x32_bf16 v[44:47], v[128:131], v[190:193], v[44:47]
	v_mfma_f32_16x16x32_bf16 v[32:35], v[120:123], v[198:201], v[32:35]
	v_mfma_f32_16x16x32_bf16 v[28:31], v[128:131], v[198:201], v[28:31]
	v_mfma_f32_16x16x32_bf16 v[16:19], v[120:123], v[206:209], v[16:19]
	v_mfma_f32_16x16x32_bf16 v[12:15], v[128:131], v[206:209], v[12:15]
	s_setprio 0
	s_setprio 1
	v_mfma_f32_16x16x32_bf16 v[56:59], v[132:135], v[174:177], 0
	v_mfma_f32_16x16x32_bf16 v[52:55], v[166:169], v[174:177], 0
	v_mfma_f32_16x16x32_bf16 v[40:43], v[132:135], v[186:189], 0
	v_mfma_f32_16x16x32_bf16 v[36:39], v[166:169], v[186:189], 0
	v_mfma_f32_16x16x32_bf16 v[24:27], v[132:135], v[194:197], 0
	v_mfma_f32_16x16x32_bf16 v[20:23], v[166:169], v[194:197], 0
	v_mfma_f32_16x16x32_bf16 v[8:11], v[132:135], v[202:205], 0
	v_mfma_f32_16x16x32_bf16 v[4:7], v[166:169], v[202:205], 0
	v_mfma_f32_16x16x32_bf16 v[56:59], v[136:139], v[182:185], v[56:59]
	v_mfma_f32_16x16x32_bf16 v[52:55], v[170:173], v[182:185], v[52:55]
	v_mfma_f32_16x16x32_bf16 v[40:43], v[136:139], v[190:193], v[40:43]
	v_mfma_f32_16x16x32_bf16 v[36:39], v[170:173], v[190:193], v[36:39]
	v_mfma_f32_16x16x32_bf16 v[24:27], v[136:139], v[198:201], v[24:27]
	v_mfma_f32_16x16x32_bf16 v[20:23], v[170:173], v[198:201], v[20:23]
	v_mfma_f32_16x16x32_bf16 v[8:11], v[136:139], v[206:209], v[8:11]
	v_mfma_f32_16x16x32_bf16 v[4:7], v[170:173], v[206:209], v[4:7]
	s_barrier
	s_setprio 0
	s_add_i32 s26, 0, 0x18000
	s_add_i32 s31, 0, 0x1c000
	v_add_u32_e32 v128, s26, v178
	v_add_u32_e32 v170, s31, v178
	ds_read_b128 v[116:119], v128
	ds_read_b128 v[120:123], v128 offset:1024
	ds_read_b128 v[124:127], v128 offset:2048
	ds_read_b128 v[128:131], v128 offset:3072
	ds_read_b128 v[132:135], v170
	ds_read_b128 v[136:139], v170 offset:1024
	ds_read_b128 v[166:169], v170 offset:2048
	ds_read_b128 v[170:173], v170 offset:3072
	s_add_u32 s44, s44, 0x80000
	s_addc_u32 s45, s45, 0
	s_mov_b32 m0, s51
	v_lshl_add_u64 v[218:219], s[44:45], 0, v[160:161]
	ds_read_b128 v[174:177], v181 offset:32768
	ds_read_b128 v[182:185], v181 offset:33792
	ds_read_b128 v[186:189], v181 offset:34816
	ds_read_b128 v[190:193], v181 offset:35840
	ds_read_b128 v[194:197], v181 offset:36864
	ds_read_b128 v[198:201], v181 offset:37888
	ds_read_b128 v[202:205], v181 offset:38912
	ds_read_b128 v[206:209], v181 offset:39936
	global_load_lds_dwordx4 v[218:219], off
	v_lshl_add_u64 v[218:219], s[44:45], 0, v[158:159]
	s_mov_b32 m0, s52
	s_nop 0
	global_load_lds_dwordx4 v[218:219], off
	s_waitcnt vmcnt(8)
	s_waitcnt lgkmcnt(0)
	s_setprio 1
	s_barrier
	v_mfma_f32_16x16x32_bf16 v[152:155], v[116:119], v[174:177], v[152:155]
	v_mfma_f32_16x16x32_bf16 v[148:151], v[124:127], v[174:177], v[148:151]
	v_mfma_f32_16x16x32_bf16 v[112:115], v[116:119], v[186:189], v[112:115]
	v_mfma_f32_16x16x32_bf16 v[108:111], v[124:127], v[186:189], v[108:111]
	v_mfma_f32_16x16x32_bf16 v[96:99], v[116:119], v[194:197], v[96:99]
	v_mfma_f32_16x16x32_bf16 v[92:95], v[124:127], v[194:197], v[92:95]
	v_mfma_f32_16x16x32_bf16 v[80:83], v[116:119], v[202:205], v[80:83]
	v_mfma_f32_16x16x32_bf16 v[76:79], v[124:127], v[202:205], v[76:79]
	v_mfma_f32_16x16x32_bf16 v[152:155], v[120:123], v[182:185], v[152:155]
	v_mfma_f32_16x16x32_bf16 v[148:151], v[128:131], v[182:185], v[148:151]
	v_mfma_f32_16x16x32_bf16 v[112:115], v[120:123], v[190:193], v[112:115]
	v_mfma_f32_16x16x32_bf16 v[108:111], v[128:131], v[190:193], v[108:111]
	v_mfma_f32_16x16x32_bf16 v[96:99], v[120:123], v[198:201], v[96:99]
	v_mfma_f32_16x16x32_bf16 v[92:95], v[128:131], v[198:201], v[92:95]
	v_mfma_f32_16x16x32_bf16 v[80:83], v[120:123], v[206:209], v[80:83]
	v_mfma_f32_16x16x32_bf16 v[76:79], v[128:131], v[206:209], v[76:79]
	s_setprio 0
	s_setprio 1
	v_mfma_f32_16x16x32_bf16 v[144:147], v[132:135], v[174:177], v[144:147]
	v_mfma_f32_16x16x32_bf16 v[140:143], v[166:169], v[174:177], v[140:143]
	v_mfma_f32_16x16x32_bf16 v[104:107], v[132:135], v[186:189], v[104:107]
	v_mfma_f32_16x16x32_bf16 v[100:103], v[166:169], v[186:189], v[100:103]
	v_mfma_f32_16x16x32_bf16 v[88:91], v[132:135], v[194:197], v[88:91]
	v_mfma_f32_16x16x32_bf16 v[84:87], v[166:169], v[194:197], v[84:87]
	v_mfma_f32_16x16x32_bf16 v[72:75], v[132:135], v[202:205], v[72:75]
	v_mfma_f32_16x16x32_bf16 v[68:71], v[166:169], v[202:205], v[68:71]
	v_mfma_f32_16x16x32_bf16 v[144:147], v[136:139], v[182:185], v[144:147]
	v_mfma_f32_16x16x32_bf16 v[140:143], v[170:173], v[182:185], v[140:143]
	v_mfma_f32_16x16x32_bf16 v[104:107], v[136:139], v[190:193], v[104:107]
	v_mfma_f32_16x16x32_bf16 v[100:103], v[170:173], v[190:193], v[100:103]
	v_mfma_f32_16x16x32_bf16 v[88:91], v[136:139], v[198:201], v[88:91]
	v_mfma_f32_16x16x32_bf16 v[84:87], v[170:173], v[198:201], v[84:87]
	v_mfma_f32_16x16x32_bf16 v[72:75], v[136:139], v[206:209], v[72:75]
	v_mfma_f32_16x16x32_bf16 v[68:71], v[170:173], v[206:209], v[68:71]
	s_barrier
; #define PG8_STAGE(bufoff, gbase, voff) do { _Pragma("unroll") for (int _i = 0; _i < 2; ++_i) \
;         __builtin_amdgcn_global_load_lds((const unsigned*)((const char*)(gbase) + (voff)[_i]), (PG8_LAS unsigned*)(lds + (bufoff) + ldsw + _i * 8192), 16, 0, 0); } while (0)
; #define PG8_LDA(dst, b, h) do { _Pragma("unroll") for (int m = 0; m < 4; ++m) _Pragma("unroll") for (int k = 0; k < 2; ++k) dst[m][k] = *(const PG8_LAS bf16x8*)(lds + PG8_SA(b, h) + aoff + m * 2048 + k * 1024); } while (0)
; #define PG8_LDB(dst, b, h) do { _Pragma("unroll") for (int n = 0; n < 2; ++n) _Pragma("unroll") for (int k = 0; k < 2; ++k) dst[n][k] = *(const PG8_LAS bf16x8*)(lds + PG8_SB(b, h) + boff + n * 2048 + k * 1024); } while (0)
; #define PG8_MMA(ai, bj, At, Bt) do { __builtin_amdgcn_s_setprio(1); _Pragma("unroll") for (int m = 0; m < 4; ++m) _Pragma("unroll") for (int n = 0; n < 2; ++n) _Pragma("unroll") for (int k = 0; k < 2; ++k) \
;         acc[ai][bj][m][n] = __builtin_amdgcn_mfma_f32_16x16x32_bf16(Bt[n][k], At[m][k], acc[ai][bj][m][n], 0, 0, 0); __builtin_amdgcn_s_setprio(0); } while (0)
; #define PG8_WAIT_V(n) asm volatile("s_waitcnt vmcnt(" #n ")" ::: "memory")
; template <class Epi, class Sched, bool ALIGN_EPI = false, bool SP2 = false>
; __device__ __forceinline__ void gemm_phase(PG8_LAS unsigned char* lds, const Gemm g, const Sched& S, const Epi& E) {
;     ...
;             PG8_LDB(B0, 0, 0); PG8_LDB(B1, 0, 1); PG8_SCHED; PG8_LDA(At, 0, 0); PG8_STAGE(PG8_SA(1, 1), a1 + hstep, voffA);
;             PG8_WAIT_V(8); PG8_WAIT_L(0); PG8_BAR; PG8_MMA(0, 0, At, B0); PG8_MMA(0, 1, At, B1); PG8_BAR; PG8_SCHED;
;             PG8_LDA(At, 0, 1); PG8_STAGE(PG8_SB(0, 0), b2, voffB); PG8_STAGE(PG8_SB(0, 1), b2 + hstep, voffB); PG8_STAGE(PG8_SA(0, 0), a2, voffA);
;             PG8_WAIT_V(8); PG8_WAIT_L(0); PG8_BAR; PG8_MMA(1, 0, At, B0); PG8_MMA(1, 1, At, B1); PG8_BAR; PG8_SCHED;
;             PG8_LDB(B0, 1, 0); PG8_LDB(B1, 1, 1); PG8_SCHED; PG8_LDA(At, 1, 0); PG8_STAGE(PG8_SA(0, 1), a2 + hstep, voffA);
;             PG8_WAIT_V(8); PG8_WAIT_L(0); PG8_BAR; PG8_MMA(0, 0, At, B0); PG8_MMA(0, 1, At, B1); PG8_BAR; PG8_SCHED;
;             PG8_LDA(At, 1, 1); PG8_STAGE(PG8_SB(1, 0), b3, voffB); PG8_STAGE(PG8_SB(1, 1), b3 + hstep, voffB); PG8_STAGE(PG8_SA(1, 0), a3, voffA);
;             PG8_WAIT_V(8); PG8_WAIT_L(0); PG8_BAR; PG8_MMA(1, 0, At, B0); PG8_MMA(1, 1, At, B1); PG8_BAR; PG8_SCHED;
	s_setprio 0
	s_add_i32 s26, s26, s46
	v_lshl_add_u64 v[210:211], v[210:211], 0, s[60:61]
	s_mov_b32 m0, s26
	ds_read_b128 v[174:177], v181 offset:49152
	ds_read_b128 v[182:185], v181 offset:50176
	ds_read_b128 v[186:189], v181 offset:51200
	ds_read_b128 v[190:193], v181 offset:52224
	ds_read_b128 v[194:197], v181 offset:53248
	ds_read_b128 v[198:201], v181 offset:54272
	ds_read_b128 v[202:205], v181 offset:55296
	ds_read_b128 v[206:209], v181 offset:56320
	global_load_lds_dwordx4 v[210:211], off
	s_add_i32 m0, s26, 0x2000
	s_add_u32 s42, s42, 0x80080
	v_lshl_add_u64 v[210:211], v[212:213], 0, s[60:61]
	s_addc_u32 s43, s43, 0
	s_add_i32 s26, s31, s46
	global_load_lds_dwordx4 v[210:211], off
	v_lshl_add_u64 v[210:211], s[42:43], 0, v[2:3]
	s_mov_b32 m0, s26
	s_nop 0
	global_load_lds_dwordx4 v[210:211], off
	v_lshl_add_u64 v[210:211], s[42:43], 0, v[156:157]
	s_add_i32 m0, s26, 0x2000
	s_nop 0
	global_load_lds_dwordx4 v[210:211], off
	v_lshl_add_u64 v[210:211], v[214:215], 0, s[60:61]
	s_mov_b32 m0, s54
	s_nop 0
	global_load_lds_dwordx4 v[210:211], off
	v_lshl_add_u64 v[210:211], v[216:217], 0, s[60:61]
	s_mov_b32 m0, s55
	s_nop 0
	global_load_lds_dwordx4 v[210:211], off
	s_waitcnt vmcnt(8)
	s_waitcnt lgkmcnt(0)
	s_setprio 1
	s_barrier
	v_mfma_f32_16x16x32_bf16 v[64:67], v[116:119], v[174:177], v[64:67]
	v_mfma_f32_16x16x32_bf16 v[60:63], v[124:127], v[174:177], v[60:63]
	v_mfma_f32_16x16x32_bf16 v[48:51], v[116:119], v[186:189], v[48:51]
	v_mfma_f32_16x16x32_bf16 v[44:47], v[124:127], v[186:189], v[44:47]
	v_mfma_f32_16x16x32_bf16 v[32:35], v[116:119], v[194:197], v[32:35]
	v_mfma_f32_16x16x32_bf16 v[28:31], v[124:127], v[194:197], v[28:31]
	v_mfma_f32_16x16x32_bf16 v[16:19], v[116:119], v[202:205], v[16:19]
	v_mfma_f32_16x16x32_bf16 v[12:15], v[124:127], v[202:205], v[12:15]
	v_mfma_f32_16x16x32_bf16 v[64:67], v[120:123], v[182:185], v[64:67]
	v_mfma_f32_16x16x32_bf16 v[60:63], v[128:131], v[182:185], v[60:63]
	v_mfma_f32_16x16x32_bf16 v[48:51], v[120:123], v[190:193], v[48:51]
	v_mfma_f32_16x16x32_bf16 v[44:47], v[128:131], v[190:193], v[44:47]
	v_mfma_f32_16x16x32_bf16 v[32:35], v[120:123], v[198:201], v[32:35]
	v_mfma_f32_16x16x32_bf16 v[28:31], v[128:131], v[198:201], v[28:31]
	v_mfma_f32_16x16x32_bf16 v[16:19], v[120:123], v[206:209], v[16:19]
	v_mfma_f32_16x16x32_bf16 v[12:15], v[128:131], v[206:209], v[12:15]
	s_setprio 0
	s_setprio 1
	v_mfma_f32_16x16x32_bf16 v[56:59], v[132:135], v[174:177], v[56:59]
	v_mfma_f32_16x16x32_bf16 v[52:55], v[166:169], v[174:177], v[52:55]
	v_mfma_f32_16x16x32_bf16 v[40:43], v[132:135], v[186:189], v[40:43]
	v_mfma_f32_16x16x32_bf16 v[36:39], v[166:169], v[186:189], v[36:39]
	v_mfma_f32_16x16x32_bf16 v[24:27], v[132:135], v[194:197], v[24:27]
	v_mfma_f32_16x16x32_bf16 v[20:23], v[166:169], v[194:197], v[20:23]
	v_mfma_f32_16x16x32_bf16 v[8:11], v[132:135], v[202:205], v[8:11]
	v_mfma_f32_16x16x32_bf16 v[4:7], v[166:169], v[202:205], v[4:7]
	v_mfma_f32_16x16x32_bf16 v[56:59], v[136:139], v[182:185], v[56:59]
	v_mfma_f32_16x16x32_bf16 v[52:55], v[170:173], v[182:185], v[52:55]
	v_mfma_f32_16x16x32_bf16 v[40:43], v[136:139], v[190:193], v[40:43]
	v_mfma_f32_16x16x32_bf16 v[36:39], v[170:173], v[190:193], v[36:39]
	v_mfma_f32_16x16x32_bf16 v[24:27], v[136:139], v[198:201], v[24:27]
	v_mfma_f32_16x16x32_bf16 v[20:23], v[170:173], v[198:201], v[20:23]
	v_mfma_f32_16x16x32_bf16 v[8:11], v[136:139], v[206:209], v[8:11]
	v_mfma_f32_16x16x32_bf16 v[4:7], v[170:173], v[206:209], v[4:7]
	s_barrier
	s_setprio 0
	s_add_i32 s66, s66, 2
	s_add_u32 s38, s38, 0x100
	s_addc_u32 s39, s39, 0
	s_add_u32 s63, s63, 0x100
	s_addc_u32 s64, s64, 0
	s_cmp_gt_u32 s66, 29
	s_cbranch_scc0 .LBB0_1961
	s_branch .Lpeel_post_p4
.LBB0_1961:
	s_add_u32 s26, s38, 0xfff80080
	s_addc_u32 s31, s39, -1
	s_add_i32 s67, 0, 0x10000
	s_cmp_eq_u32 s66, 28
	s_cselect_b32 s45, s21, s31
	s_cselect_b32 s44, s57, s26
	s_cselect_b32 s43, s19, s64
	s_cselect_b32 s42, s62, s63
	s_add_i32 s26, 0, 0x14000
	v_add_u32_e32 v128, s67, v178
	v_add_u32_e32 v170, s26, v178
	ds_read_b128 v[116:119], v128
	ds_read_b128 v[120:123], v128 offset:1024
	ds_read_b128 v[124:127], v128 offset:2048
	ds_read_b128 v[128:131], v128 offset:3072
	ds_read_b128 v[132:135], v170
	ds_read_b128 v[136:139], v170 offset:1024
	ds_read_b128 v[166:169], v170 offset:2048
	ds_read_b128 v[170:173], v170 offset:3072
	v_lshl_add_u64 v[210:211], s[38:39], 0, v[162:163]
	s_add_i32 m0, s47, 0xc000
	ds_read_b128 v[174:177], v181
	ds_read_b128 v[182:185], v181 offset:1024
	ds_read_b128 v[186:189], v181 offset:2048
	ds_read_b128 v[190:193], v181 offset:3072
	ds_read_b128 v[194:197], v181 offset:4096
	ds_read_b128 v[198:201], v181 offset:5120
	ds_read_b128 v[202:205], v181 offset:6144
	ds_read_b128 v[206:209], v181 offset:7168
	global_load_lds_dwordx4 v[210:211], off
	v_lshl_add_u64 v[210:211], s[38:39], 0, v[164:165]
	s_add_i32 m0, s47, 0xe000
	s_nop 0
	global_load_lds_dwordx4 v[210:211], off
	s_waitcnt vmcnt(8)
	s_waitcnt lgkmcnt(0)
	s_setprio 1
	s_barrier
; #define PG8_STAGE(bufoff, gbase, voff) do { _Pragma("unroll") for (int _i = 0; _i < 2; ++_i) \
;         __builtin_amdgcn_global_load_lds((const unsigned*)((const char*)(gbase) + (voff)[_i]), (PG8_LAS unsigned*)(lds + (bufoff) + ldsw + _i * 8192), 16, 0, 0); } while (0)
; #define PG8_LDA(dst, b, h) do { _Pragma("unroll") for (int m = 0; m < 4; ++m) _Pragma("unroll") for (int k = 0; k < 2; ++k) dst[m][k] = *(const PG8_LAS bf16x8*)(lds + PG8_SA(b, h) + aoff + m * 2048 + k * 1024); } while (0)
; #define PG8_MMA(ai, bj, At, Bt) do { __builtin_amdgcn_s_setprio(1); _Pragma("unroll") for (int m = 0; m < 4; ++m) _Pragma("unroll") for (int n = 0; n < 2; ++n) _Pragma("unroll") for (int k = 0; k < 2; ++k) \
;         acc[ai][bj][m][n] = __builtin_amdgcn_mfma_f32_16x16x32_bf16(Bt[n][k], At[m][k], acc[ai][bj][m][n], 0, 0, 0); __builtin_amdgcn_s_setprio(0); } while (0)
; #define PG8_WAIT_V(n) asm volatile("s_waitcnt vmcnt(" #n ")" ::: "memory")
; #define PG8_WAIT_L(n) asm volatile("s_waitcnt lgkmcnt(" #n ")" ::: "memory")
; #define PG8_BAR __builtin_amdgcn_s_barrier()
; #define PG8_SCHED __builtin_amdgcn_sched_barrier(0)
; template <class Epi, class Sched, bool ALIGN_EPI = false, bool SP2 = false>
; __device__ __forceinline__ void gemm_phase(PG8_LAS unsigned char* lds, const Gemm g, const Sched& S, const Epi& E) {
;     ...
;             PG8_WAIT_V(8); PG8_WAIT_L(0); PG8_BAR; PG8_MMA(0, 0, At, B0); PG8_MMA(0, 1, At, B1); PG8_BAR; PG8_SCHED;
;             PG8_LDA(At, 0, 1); PG8_STAGE(PG8_SB(0, 0), b2, voffB); PG8_STAGE(PG8_SB(0, 1), b2 + hstep, voffB); PG8_STAGE(PG8_SA(0, 0), a2, voffA);
;             PG8_WAIT_V(8); PG8_WAIT_L(0); PG8_BAR; PG8_MMA(1, 0, At, B0); PG8_MMA(1, 1, At, B1); PG8_BAR; PG8_SCHED;
	v_mfma_f32_16x16x32_bf16 v[152:155], v[116:119], v[174:177], v[152:155]
	v_mfma_f32_16x16x32_bf16 v[148:151], v[124:127], v[174:177], v[148:151]
	v_mfma_f32_16x16x32_bf16 v[112:115], v[116:119], v[186:189], v[112:115]
	v_mfma_f32_16x16x32_bf16 v[108:111], v[124:127], v[186:189], v[108:111]
	v_mfma_f32_16x16x32_bf16 v[96:99], v[116:119], v[194:197], v[96:99]
	v_mfma_f32_16x16x32_bf16 v[92:95], v[124:127], v[194:197], v[92:95]
	v_mfma_f32_16x16x32_bf16 v[80:83], v[116:119], v[202:205], v[80:83]
	v_mfma_f32_16x16x32_bf16 v[76:79], v[124:127], v[202:205], v[76:79]
	v_mfma_f32_16x16x32_bf16 v[152:155], v[120:123], v[182:185], v[152:155]
	v_mfma_f32_16x16x32_bf16 v[148:151], v[128:131], v[182:185], v[148:151]
	v_mfma_f32_16x16x32_bf16 v[112:115], v[120:123], v[190:193], v[112:115]
	v_mfma_f32_16x16x32_bf16 v[108:111], v[128:131], v[190:193], v[108:111]
	v_mfma_f32_16x16x32_bf16 v[96:99], v[120:123], v[198:201], v[96:99]
	v_mfma_f32_16x16x32_bf16 v[92:95], v[128:131], v[198:201], v[92:95]
	v_mfma_f32_16x16x32_bf16 v[80:83], v[120:123], v[206:209], v[80:83]
	v_mfma_f32_16x16x32_bf16 v[76:79], v[128:131], v[206:209], v[76:79]
	s_setprio 0
	s_setprio 1
	v_mfma_f32_16x16x32_bf16 v[144:147], v[132:135], v[174:177], v[144:147]
	v_mfma_f32_16x16x32_bf16 v[140:143], v[166:169], v[174:177], v[140:143]
	v_mfma_f32_16x16x32_bf16 v[104:107], v[132:135], v[186:189], v[104:107]
	v_mfma_f32_16x16x32_bf16 v[100:103], v[166:169], v[186:189], v[100:103]
	v_mfma_f32_16x16x32_bf16 v[88:91], v[132:135], v[194:197], v[88:91]
	v_mfma_f32_16x16x32_bf16 v[84:87], v[166:169], v[194:197], v[84:87]
	v_mfma_f32_16x16x32_bf16 v[72:75], v[132:135], v[202:205], v[72:75]
	v_mfma_f32_16x16x32_bf16 v[68:71], v[166:169], v[202:205], v[68:71]
	v_mfma_f32_16x16x32_bf16 v[144:147], v[136:139], v[182:185], v[144:147]
	v_mfma_f32_16x16x32_bf16 v[140:143], v[170:173], v[182:185], v[140:143]
	v_mfma_f32_16x16x32_bf16 v[104:107], v[136:139], v[190:193], v[104:107]
	v_mfma_f32_16x16x32_bf16 v[100:103], v[170:173], v[190:193], v[100:103]
	v_mfma_f32_16x16x32_bf16 v[88:91], v[136:139], v[198:201], v[88:91]
	v_mfma_f32_16x16x32_bf16 v[84:87], v[170:173], v[198:201], v[84:87]
	v_mfma_f32_16x16x32_bf16 v[72:75], v[136:139], v[206:209], v[72:75]
	v_mfma_f32_16x16x32_bf16 v[68:71], v[170:173], v[206:209], v[68:71]
	s_barrier
	s_setprio 0
	s_add_i32 s31, s67, s46
	v_lshl_add_u64 v[210:211], s[42:43], 0, v[2:3]
	s_mov_b32 m0, s31
	ds_read_b128 v[174:177], v181 offset:16384
	ds_read_b128 v[182:185], v181 offset:17408
	ds_read_b128 v[186:189], v181 offset:18432
	ds_read_b128 v[190:193], v181 offset:19456
	ds_read_b128 v[194:197], v181 offset:20480
	ds_read_b128 v[198:201], v181 offset:21504
	ds_read_b128 v[202:205], v181 offset:22528
	ds_read_b128 v[206:209], v181 offset:23552
	global_load_lds_dwordx4 v[210:211], off
	s_add_i32 m0, s31, 0x2000
	s_add_u32 s68, s42, 0x80000
	v_lshl_add_u64 v[212:213], s[42:43], 0, v[156:157]
	s_addc_u32 s69, s43, 0
	s_add_i32 s26, s26, s46
	global_load_lds_dwordx4 v[212:213], off
	v_lshl_add_u64 v[214:215], s[68:69], 0, v[2:3]
	s_mov_b32 m0, s26
	v_lshl_add_u64 v[216:217], s[44:45], 0, v[158:159]
	global_load_lds_dwordx4 v[214:215], off
	v_lshl_add_u64 v[214:215], s[68:69], 0, v[156:157]
	s_add_i32 m0, s26, 0x2000
	s_nop 0
	global_load_lds_dwordx4 v[214:215], off
	v_lshl_add_u64 v[214:215], s[44:45], 0, v[160:161]
	s_mov_b32 m0, s47
	s_nop 0
	global_load_lds_dwordx4 v[214:215], off
	s_mov_b32 m0, s50
	s_nop 0
	global_load_lds_dwordx4 v[216:217], off
	s_waitcnt vmcnt(8)
	s_waitcnt lgkmcnt(0)
	s_setprio 1
	s_barrier
	v_mfma_f32_16x16x32_bf16 v[64:67], v[116:119], v[174:177], v[64:67]
	v_mfma_f32_16x16x32_bf16 v[60:63], v[124:127], v[174:177], v[60:63]
	v_mfma_f32_16x16x32_bf16 v[48:51], v[116:119], v[186:189], v[48:51]
	v_mfma_f32_16x16x32_bf16 v[44:47], v[124:127], v[186:189], v[44:47]
	v_mfma_f32_16x16x32_bf16 v[32:35], v[116:119], v[194:197], v[32:35]
	v_mfma_f32_16x16x32_bf16 v[28:31], v[124:127], v[194:197], v[28:31]
	v_mfma_f32_16x16x32_bf16 v[16:19], v[116:119], v[202:205], v[16:19]
	v_mfma_f32_16x16x32_bf16 v[12:15], v[124:127], v[202:205], v[12:15]
	v_mfma_f32_16x16x32_bf16 v[64:67], v[120:123], v[182:185], v[64:67]
	v_mfma_f32_16x16x32_bf16 v[60:63], v[128:131], v[182:185], v[60:63]
	v_mfma_f32_16x16x32_bf16 v[48:51], v[120:123], v[190:193], v[48:51]
	v_mfma_f32_16x16x32_bf16 v[44:47], v[128:131], v[190:193], v[44:47]
	v_mfma_f32_16x16x32_bf16 v[32:35], v[120:123], v[198:201], v[32:35]
	v_mfma_f32_16x16x32_bf16 v[28:31], v[128:131], v[198:201], v[28:31]
	v_mfma_f32_16x16x32_bf16 v[16:19], v[120:123], v[206:209], v[16:19]
	v_mfma_f32_16x16x32_bf16 v[12:15], v[128:131], v[206:209], v[12:15]
	s_setprio 0
	s_setprio 1
	v_mfma_f32_16x16x32_bf16 v[56:59], v[132:135], v[174:177], v[56:59]
	v_mfma_f32_16x16x32_bf16 v[52:55], v[166:169], v[174:177], v[52:55]
	v_mfma_f32_16x16x32_bf16 v[40:43], v[132:135], v[186:189], v[40:43]
	v_mfma_f32_16x16x32_bf16 v[36:39], v[166:169], v[186:189], v[36:39]
	v_mfma_f32_16x16x32_bf16 v[24:27], v[132:135], v[194:197], v[24:27]
	v_mfma_f32_16x16x32_bf16 v[20:23], v[166:169], v[194:197], v[20:23]
	v_mfma_f32_16x16x32_bf16 v[8:11], v[132:135], v[202:205], v[8:11]
	v_mfma_f32_16x16x32_bf16 v[4:7], v[166:169], v[202:205], v[4:7]
	v_mfma_f32_16x16x32_bf16 v[56:59], v[136:139], v[182:185], v[56:59]
	v_mfma_f32_16x16x32_bf16 v[52:55], v[170:173], v[182:185], v[52:55]
	v_mfma_f32_16x16x32_bf16 v[40:43], v[136:139], v[190:193], v[40:43]
	v_mfma_f32_16x16x32_bf16 v[36:39], v[170:173], v[190:193], v[36:39]
	v_mfma_f32_16x16x32_bf16 v[24:27], v[136:139], v[198:201], v[24:27]
	v_mfma_f32_16x16x32_bf16 v[20:23], v[170:173], v[198:201], v[20:23]
	v_mfma_f32_16x16x32_bf16 v[8:11], v[136:139], v[206:209], v[8:11]
	v_mfma_f32_16x16x32_bf16 v[4:7], v[170:173], v[206:209], v[4:7]
	s_barrier
; #define PG8_STAGE(bufoff, gbase, voff) do { _Pragma("unroll") for (int _i = 0; _i < 2; ++_i) \
;         __builtin_amdgcn_global_load_lds((const unsigned*)((const char*)(gbase) + (voff)[_i]), (PG8_LAS unsigned*)(lds + (bufoff) + ldsw + _i * 8192), 16, 0, 0); } while (0)
; #define PG8_LDA(dst, b, h) do { _Pragma("unroll") for (int m = 0; m < 4; ++m) _Pragma("unroll") for (int k = 0; k < 2; ++k) dst[m][k] = *(const PG8_LAS bf16x8*)(lds + PG8_SA(b, h) + aoff + m * 2048 + k * 1024); } while (0)
; #define PG8_LDB(dst, b, h) do { _Pragma("unroll") for (int n = 0; n < 2; ++n) _Pragma("unroll") for (int k = 0; k < 2; ++k) dst[n][k] = *(const PG8_LAS bf16x8*)(lds + PG8_SB(b, h) + boff + n * 2048 + k * 1024); } while (0)
; #define PG8_MMA(ai, bj, At, Bt) do { __builtin_amdgcn_s_setprio(1); _Pragma("unroll") for (int m = 0; m < 4; ++m) _Pragma("unroll") for (int n = 0; n < 2; ++n) _Pragma("unroll") for (int k = 0; k < 2; ++k) \
;         acc[ai][bj][m][n] = __builtin_amdgcn_mfma_f32_16x16x32_bf16(Bt[n][k], At[m][k], acc[ai][bj][m][n], 0, 0, 0); __builtin_amdgcn_s_setprio(0); } while (0)
; #define PG8_WAIT_V(n) asm volatile("s_waitcnt vmcnt(" #n ")" ::: "memory")
; #define PG8_WAIT_L(n) asm volatile("s_waitcnt lgkmcnt(" #n ")" ::: "memory")
; #define PG8_BAR __builtin_amdgcn_s_barrier()
; #define PG8_SCHED __builtin_amdgcn_sched_barrier(0)
; template <class Epi, class Sched, bool ALIGN_EPI = false, bool SP2 = false>
; __device__ __forceinline__ void gemm_phase(PG8_LAS unsigned char* lds, const Gemm g, const Sched& S, const Epi& E) {
;     ...
;             PG8_LDB(B0, 1, 0); PG8_LDB(B1, 1, 1); PG8_SCHED; PG8_LDA(At, 1, 0); PG8_STAGE(PG8_SA(0, 1), a2 + hstep, voffA);
;             PG8_WAIT_V(8); PG8_WAIT_L(0); PG8_BAR; PG8_MMA(0, 0, At, B0); PG8_MMA(0, 1, At, B1); PG8_BAR; PG8_SCHED;
	s_setprio 0
	s_add_i32 s26, 0, 0x18000
	s_add_i32 s31, 0, 0x1c000
	v_add_u32_e32 v128, s26, v178
	v_add_u32_e32 v170, s31, v178
	ds_read_b128 v[116:119], v128
	ds_read_b128 v[120:123], v128 offset:1024
	ds_read_b128 v[124:127], v128 offset:2048
	ds_read_b128 v[128:131], v128 offset:3072
	ds_read_b128 v[132:135], v170
	ds_read_b128 v[136:139], v170 offset:1024
	ds_read_b128 v[166:169], v170 offset:2048
	ds_read_b128 v[170:173], v170 offset:3072
	s_add_u32 s44, s44, 0x80000
	s_addc_u32 s45, s45, 0
	s_mov_b32 m0, s51
	v_lshl_add_u64 v[218:219], s[44:45], 0, v[160:161]
	ds_read_b128 v[174:177], v181 offset:32768
	ds_read_b128 v[182:185], v181 offset:33792
	ds_read_b128 v[186:189], v181 offset:34816
	ds_read_b128 v[190:193], v181 offset:35840
	ds_read_b128 v[194:197], v181 offset:36864
	ds_read_b128 v[198:201], v181 offset:37888
	ds_read_b128 v[202:205], v181 offset:38912
	ds_read_b128 v[206:209], v181 offset:39936
	global_load_lds_dwordx4 v[218:219], off
	v_lshl_add_u64 v[218:219], s[44:45], 0, v[158:159]
	s_mov_b32 m0, s52
	s_nop 0
	global_load_lds_dwordx4 v[218:219], off
	s_waitcnt vmcnt(8)
	s_waitcnt lgkmcnt(0)
	s_setprio 1
	s_barrier
	v_mfma_f32_16x16x32_bf16 v[152:155], v[116:119], v[174:177], v[152:155]
	v_mfma_f32_16x16x32_bf16 v[148:151], v[124:127], v[174:177], v[148:151]
	v_mfma_f32_16x16x32_bf16 v[112:115], v[116:119], v[186:189], v[112:115]
	v_mfma_f32_16x16x32_bf16 v[108:111], v[124:127], v[186:189], v[108:111]
	v_mfma_f32_16x16x32_bf16 v[96:99], v[116:119], v[194:197], v[96:99]
	v_mfma_f32_16x16x32_bf16 v[92:95], v[124:127], v[194:197], v[92:95]
	v_mfma_f32_16x16x32_bf16 v[80:83], v[116:119], v[202:205], v[80:83]
	v_mfma_f32_16x16x32_bf16 v[76:79], v[124:127], v[202:205], v[76:79]
	v_mfma_f32_16x16x32_bf16 v[152:155], v[120:123], v[182:185], v[152:155]
	v_mfma_f32_16x16x32_bf16 v[148:151], v[128:131], v[182:185], v[148:151]
	v_mfma_f32_16x16x32_bf16 v[112:115], v[120:123], v[190:193], v[112:115]
	v_mfma_f32_16x16x32_bf16 v[108:111], v[128:131], v[190:193], v[108:111]
	v_mfma_f32_16x16x32_bf16 v[96:99], v[120:123], v[198:201], v[96:99]
	v_mfma_f32_16x16x32_bf16 v[92:95], v[128:131], v[198:201], v[92:95]
	v_mfma_f32_16x16x32_bf16 v[80:83], v[120:123], v[206:209], v[80:83]
	v_mfma_f32_16x16x32_bf16 v[76:79], v[128:131], v[206:209], v[76:79]
	s_setprio 0
	s_setprio 1
	v_mfma_f32_16x16x32_bf16 v[144:147], v[132:135], v[174:177], v[144:147]
	v_mfma_f32_16x16x32_bf16 v[140:143], v[166:169], v[174:177], v[140:143]
	v_mfma_f32_16x16x32_bf16 v[104:107], v[132:135], v[186:189], v[104:107]
	v_mfma_f32_16x16x32_bf16 v[100:103], v[166:169], v[186:189], v[100:103]
	v_mfma_f32_16x16x32_bf16 v[88:91], v[132:135], v[194:197], v[88:91]
	v_mfma_f32_16x16x32_bf16 v[84:87], v[166:169], v[194:197], v[84:87]
	v_mfma_f32_16x16x32_bf16 v[72:75], v[132:135], v[202:205], v[72:75]
	v_mfma_f32_16x16x32_bf16 v[68:71], v[166:169], v[202:205], v[68:71]
	v_mfma_f32_16x16x32_bf16 v[144:147], v[136:139], v[182:185], v[144:147]
	v_mfma_f32_16x16x32_bf16 v[140:143], v[170:173], v[182:185], v[140:143]
	v_mfma_f32_16x16x32_bf16 v[104:107], v[136:139], v[190:193], v[104:107]
	v_mfma_f32_16x16x32_bf16 v[100:103], v[170:173], v[190:193], v[100:103]
	v_mfma_f32_16x16x32_bf16 v[88:91], v[136:139], v[198:201], v[88:91]
	v_mfma_f32_16x16x32_bf16 v[84:87], v[170:173], v[198:201], v[84:87]
	v_mfma_f32_16x16x32_bf16 v[72:75], v[136:139], v[206:209], v[72:75]
	v_mfma_f32_16x16x32_bf16 v[68:71], v[170:173], v[206:209], v[68:71]
	s_barrier
; #define PG8_STAGE(bufoff, gbase, voff) do { _Pragma("unroll") for (int _i = 0; _i < 2; ++_i) \
;         __builtin_amdgcn_global_load_lds((const unsigned*)((const char*)(gbase) + (voff)[_i]), (PG8_LAS unsigned*)(lds + (bufoff) + ldsw + _i * 8192), 16, 0, 0); } while (0)
; #define PG8_LDA(dst, b, h) do { _Pragma("unroll") for (int m = 0; m < 4; ++m) _Pragma("unroll") for (int k = 0; k < 2; ++k) dst[m][k] = *(const PG8_LAS bf16x8*)(lds + PG8_SA(b, h) + aoff + m * 2048 + k * 1024); } while (0)
; #define PG8_MMA(ai, bj, At, Bt) do { __builtin_amdgcn_s_setprio(1); _Pragma("unroll") for (int m = 0; m < 4; ++m) _Pragma("unroll") for (int n = 0; n < 2; ++n) _Pragma("unroll") for (int k = 0; k < 2; ++k) \
;         acc[ai][bj][m][n] = __builtin_amdgcn_mfma_f32_16x16x32_bf16(Bt[n][k], At[m][k], acc[ai][bj][m][n], 0, 0, 0); __builtin_amdgcn_s_setprio(0); } while (0)
; #define PG8_WAIT_V(n) asm volatile("s_waitcnt vmcnt(" #n ")" ::: "memory")
; #define PG8_WAIT_L(n) asm volatile("s_waitcnt lgkmcnt(" #n ")" ::: "memory")
; #define PG8_BAR __builtin_amdgcn_s_barrier()
; #define PG8_SCHED __builtin_amdgcn_sched_barrier(0)
; template <class Epi, class Sched, bool ALIGN_EPI = false, bool SP2 = false>
; __device__ __forceinline__ void gemm_phase(PG8_LAS unsigned char* lds, const Gemm g, const Sched& S, const Epi& E) {
;     ...
;             PG8_LDA(At, 1, 1); PG8_STAGE(PG8_SB(1, 0), b3, voffB); PG8_STAGE(PG8_SB(1, 1), b3 + hstep, voffB); PG8_STAGE(PG8_SA(1, 0), a3, voffA);
;             PG8_WAIT_V(8); PG8_WAIT_L(0); PG8_BAR; PG8_MMA(1, 0, At, B0); PG8_MMA(1, 1, At, B1); PG8_BAR; PG8_SCHED;
;     ...
;         if constexpr (ALIGN_EPI) { if (wr == 0) PG8_BAR; }
	s_setprio 0
	s_add_i32 s26, s26, s46
	v_lshl_add_u64 v[210:211], v[210:211], 0, s[60:61]
	s_mov_b32 m0, s26
	ds_read_b128 v[174:177], v181 offset:49152
	ds_read_b128 v[182:185], v181 offset:50176
	ds_read_b128 v[186:189], v181 offset:51200
	ds_read_b128 v[190:193], v181 offset:52224
	ds_read_b128 v[194:197], v181 offset:53248
	ds_read_b128 v[198:201], v181 offset:54272
	ds_read_b128 v[202:205], v181 offset:55296
	ds_read_b128 v[206:209], v181 offset:56320
	global_load_lds_dwordx4 v[210:211], off
	s_add_i32 m0, s26, 0x2000
	s_add_u32 s42, s42, 0x80080
	v_lshl_add_u64 v[210:211], v[212:213], 0, s[60:61]
	s_addc_u32 s43, s43, 0
	s_add_i32 s26, s31, s46
	global_load_lds_dwordx4 v[210:211], off
	v_lshl_add_u64 v[210:211], s[42:43], 0, v[2:3]
	s_mov_b32 m0, s26
	s_nop 0
	global_load_lds_dwordx4 v[210:211], off
	v_lshl_add_u64 v[210:211], s[42:43], 0, v[156:157]
	s_add_i32 m0, s26, 0x2000
	s_nop 0
	global_load_lds_dwordx4 v[210:211], off
	v_lshl_add_u64 v[210:211], v[214:215], 0, s[60:61]
	s_mov_b32 m0, s54
	s_nop 0
	global_load_lds_dwordx4 v[210:211], off
	v_lshl_add_u64 v[210:211], v[216:217], 0, s[60:61]
	s_mov_b32 m0, s55
	s_nop 0
	global_load_lds_dwordx4 v[210:211], off
	s_waitcnt vmcnt(8)
	s_waitcnt lgkmcnt(0)
	s_setprio 1
	s_barrier
	v_mfma_f32_16x16x32_bf16 v[64:67], v[116:119], v[174:177], v[64:67]
	v_mfma_f32_16x16x32_bf16 v[60:63], v[124:127], v[174:177], v[60:63]
	v_mfma_f32_16x16x32_bf16 v[48:51], v[116:119], v[186:189], v[48:51]
	v_mfma_f32_16x16x32_bf16 v[44:47], v[124:127], v[186:189], v[44:47]
	v_mfma_f32_16x16x32_bf16 v[32:35], v[116:119], v[194:197], v[32:35]
	v_mfma_f32_16x16x32_bf16 v[28:31], v[124:127], v[194:197], v[28:31]
	v_mfma_f32_16x16x32_bf16 v[16:19], v[116:119], v[202:205], v[16:19]
	v_mfma_f32_16x16x32_bf16 v[12:15], v[124:127], v[202:205], v[12:15]
	v_mfma_f32_16x16x32_bf16 v[64:67], v[120:123], v[182:185], v[64:67]
	v_mfma_f32_16x16x32_bf16 v[60:63], v[128:131], v[182:185], v[60:63]
	v_mfma_f32_16x16x32_bf16 v[48:51], v[120:123], v[190:193], v[48:51]
	v_mfma_f32_16x16x32_bf16 v[44:47], v[128:131], v[190:193], v[44:47]
	v_mfma_f32_16x16x32_bf16 v[32:35], v[120:123], v[198:201], v[32:35]
	v_mfma_f32_16x16x32_bf16 v[28:31], v[128:131], v[198:201], v[28:31]
	v_mfma_f32_16x16x32_bf16 v[16:19], v[120:123], v[206:209], v[16:19]
	v_mfma_f32_16x16x32_bf16 v[12:15], v[128:131], v[206:209], v[12:15]
	s_setprio 0
	s_setprio 1
	v_mfma_f32_16x16x32_bf16 v[56:59], v[132:135], v[174:177], v[56:59]
	v_mfma_f32_16x16x32_bf16 v[52:55], v[166:169], v[174:177], v[52:55]
	v_mfma_f32_16x16x32_bf16 v[40:43], v[132:135], v[186:189], v[40:43]
	v_mfma_f32_16x16x32_bf16 v[36:39], v[166:169], v[186:189], v[36:39]
	v_mfma_f32_16x16x32_bf16 v[24:27], v[132:135], v[194:197], v[24:27]
	v_mfma_f32_16x16x32_bf16 v[20:23], v[166:169], v[194:197], v[20:23]
	v_mfma_f32_16x16x32_bf16 v[8:11], v[132:135], v[202:205], v[8:11]
	v_mfma_f32_16x16x32_bf16 v[4:7], v[166:169], v[202:205], v[4:7]
	v_mfma_f32_16x16x32_bf16 v[56:59], v[136:139], v[182:185], v[56:59]
	v_mfma_f32_16x16x32_bf16 v[52:55], v[170:173], v[182:185], v[52:55]
	v_mfma_f32_16x16x32_bf16 v[40:43], v[136:139], v[190:193], v[40:43]
	v_mfma_f32_16x16x32_bf16 v[36:39], v[170:173], v[190:193], v[36:39]
	v_mfma_f32_16x16x32_bf16 v[24:27], v[136:139], v[198:201], v[24:27]
	v_mfma_f32_16x16x32_bf16 v[20:23], v[170:173], v[198:201], v[20:23]
	v_mfma_f32_16x16x32_bf16 v[8:11], v[136:139], v[206:209], v[8:11]
	v_mfma_f32_16x16x32_bf16 v[4:7], v[170:173], v[206:209], v[4:7]
	s_barrier
	s_setprio 0
	s_add_i32 s66, s66, 2
	s_add_u32 s38, s38, 0x100
	s_addc_u32 s39, s39, 0
	s_add_u32 s63, s63, 0x100
	s_addc_u32 s64, s64, 0
	s_cmp_gt_u32 s66, 29
	s_cbranch_scc0 .LBB0_1961
.Lpeel_post_p4:
	s_and_b64 vcc, exec, s[16:17]
	s_cbranch_vccz .LBB0_1964
	s_barrier

; #define PG8_STAGE(bufoff, gbase, voff) do { _Pragma("unroll") for (int _i = 0; _i < 2; ++_i) \
;         __builtin_amdgcn_global_load_lds((const unsigned*)((const char*)(gbase) + (voff)[_i]), (PG8_LAS unsigned*)(lds + (bufoff) + ldsw + _i * 8192), 16, 0, 0); } while (0)
; #define PG8_LDA(dst, b, h) do { _Pragma("unroll") for (int m = 0; m < 4; ++m) _Pragma("unroll") for (int k = 0; k < 2; ++k) dst[m][k] = *(const PG8_LAS bf16x8*)(lds + PG8_SA(b, h) + aoff + m * 2048 + k * 1024); } while (0)
; #define PG8_LDB(dst, b, h) do { _Pragma("unroll") for (int n = 0; n < 2; ++n) _Pragma("unroll") for (int k = 0; k < 2; ++k) dst[n][k] = *(const PG8_LAS bf16x8*)(lds + PG8_SB(b, h) + boff + n * 2048 + k * 1024); } while (0)
; template <class Epi, class Sched, bool ALIGN_EPI = false, bool SP2 = false>
; __device__ __forceinline__ void gemm_phase(PG8_LAS unsigned char* lds, const Gemm g, const Sched& S, const Epi& E) {
;     ...
;         const bool has_next = S.next(ui + 1, nxt);
;         const char* nA = has_next ? (const char*)g.A + (size_t)nxt.pm * tstep : cA; const char* nB = has_next ? (const char*)g.Bt + (size_t)nxt.pn * tstep : cB;
;         for (int t = 0; t < nt; t += 2) {
;             const bool last = (t == nt - 2);
;             const char* a1 = cA + (size_t)(t + 1) * kstep;
;             const char* a2 = last ? nA : cA + (size_t)(t + 2) * kstep; const char* b2 = last ? nB : cB + (size_t)(t + 2) * kstep;
;             const char* a3 = a2 + kstep; const char* b3 = b2 + kstep;
;             if (last && has_next) S.a_ready(nxt);
;             if constexpr (SP2) {
;             PG8_LDB(B0, 0, 0); PG8_LDB(B1, 0, 1); PG8_SCHED; PG8_LDA(At, 0, 0); PG8_STAGE(PG8_SA(1, 1), a1 + hstep, voffA);
;             PG8_WAIT_V(8); PG8_WAIT_L(0); PG8_BAR; PG8_MMA(0, 0, At, B0); PG8_MMA(0, 1, At, B1); PG8_BAR; PG8_SCHED;
;             PG8_LDA(At, 0, 1); PG8_STAGE(PG8_SB(0, 0), b2, voffB); PG8_STAGE(PG8_SB(0, 1), b2 + hstep, voffB); PG8_STAGE(PG8_SA(0, 0), a2, voffA);
;             PG8_WAIT_V(8); PG8_WAIT_L(0); PG8_BAR; PG8_MMA(1, 0, At, B0); PG8_MMA(1, 1, At, B1); PG8_BAR; PG8_SCHED;
;     ...
; #pragma unroll
;         for (int a = 0; a < 2; ++a)
; #pragma unroll
;             for (int b = 0; b < 2; ++b)
; #pragma unroll
;                 for (int m = 0; m < 4; ++m)
; #pragma unroll
;                     for (int n = 0; n < 2; ++n) acc[a][b][m][n] = (f32x4){0.f, 0.f, 0.f, 0.f};
.LBB0_2103:
	s_ashr_i32 s17, s16, 31
	s_lshl_b64 s[18:19], s[16:17], 20
	s_add_u32 s18, s2, s18
	s_addc_u32 s19, s3, s19
	s_and_b64 s[20:21], s[4:5], exec
	s_cselect_b32 s17, s19, s35
	s_cselect_b32 s52, s18, s34
	s_ashr_i32 s15, s14, 31
	s_lshl_b64 s[20:21], s[14:15], 20
	s_add_u32 s20, s29, s20
	s_addc_u32 s21, s40, s21
	s_and_b64 s[38:39], s[4:5], exec
	s_cselect_b32 s15, s21, s37
	s_cselect_b32 s53, s20, s36
	s_add_u32 s34, s34, 0x80080
	s_addc_u32 s35, s35, 0
	s_add_u32 s54, s36, 0x100
	s_addc_u32 s55, s37, 0
	s_mov_b32 s56, -2
	s_add_u32 s26, s34, 0xfff80080
	s_addc_u32 s31, s35, -1
	s_add_i32 s57, 0, 0x10000
	s_cmp_eq_u32 s56, 28
	s_cselect_b32 s39, s17, s31
	s_cselect_b32 s38, s52, s26
	v_add_u32_e32 v149, s57, v146
	s_cselect_b32 s37, s15, s55
	s_cselect_b32 s36, s53, s54
	s_add_i32 s26, 0, 0x14000
	ds_read_b128 v[142:145], v149
	ds_read_b128 v[150:153], v149 offset:1024
	ds_read_b128 v[154:157], v149 offset:2048
	ds_read_b128 v[158:161], v149 offset:3072
	v_add_u32_e32 v149, s26, v146
	ds_read_b128 v[162:165], v149
	ds_read_b128 v[166:169], v149 offset:1024
	ds_read_b128 v[170:173], v149 offset:2048
	ds_read_b128 v[174:177], v149 offset:3072
	v_lshl_add_u64 v[178:179], s[34:35], 0, v[138:139]
	s_add_i32 m0, s43, 0xc000
	ds_read_b128 v[182:185], v148
	ds_read_b128 v[186:189], v148 offset:1024
	ds_read_b128 v[190:193], v148 offset:2048
	ds_read_b128 v[194:197], v148 offset:3072
	ds_read_b128 v[198:201], v148 offset:4096
	ds_read_b128 v[202:205], v148 offset:5120
	ds_read_b128 v[206:209], v148 offset:6144
	ds_read_b128 v[210:213], v148 offset:7168
	global_load_lds_dwordx4 v[178:179], off
	v_lshl_add_u64 v[178:179], s[34:35], 0, v[140:141]
	s_add_i32 m0, s43, 0xe000
	s_nop 0
	global_load_lds_dwordx4 v[178:179], off
	s_waitcnt vmcnt(8)
	s_waitcnt lgkmcnt(0)
	s_setprio 1
	s_barrier
	v_mfma_f32_16x16x32_bf16 v[128:131], v[142:145], v[182:185], 0
	v_mfma_f32_16x16x32_bf16 v[124:127], v[154:157], v[182:185], 0
	v_mfma_f32_16x16x32_bf16 v[112:115], v[142:145], v[190:193], 0
	v_mfma_f32_16x16x32_bf16 v[108:111], v[154:157], v[190:193], 0
	v_mfma_f32_16x16x32_bf16 v[96:99], v[142:145], v[198:201], 0
	v_mfma_f32_16x16x32_bf16 v[92:95], v[154:157], v[198:201], 0
	v_mfma_f32_16x16x32_bf16 v[80:83], v[142:145], v[206:209], 0
	v_mfma_f32_16x16x32_bf16 v[76:79], v[154:157], v[206:209], 0
	v_mfma_f32_16x16x32_bf16 v[128:131], v[150:153], v[186:189], v[128:131]
	v_mfma_f32_16x16x32_bf16 v[124:127], v[158:161], v[186:189], v[124:127]
	v_mfma_f32_16x16x32_bf16 v[112:115], v[150:153], v[194:197], v[112:115]
	v_mfma_f32_16x16x32_bf16 v[108:111], v[158:161], v[194:197], v[108:111]
	v_mfma_f32_16x16x32_bf16 v[96:99], v[150:153], v[202:205], v[96:99]
	v_mfma_f32_16x16x32_bf16 v[92:95], v[158:161], v[202:205], v[92:95]
	v_mfma_f32_16x16x32_bf16 v[80:83], v[150:153], v[210:213], v[80:83]
	v_mfma_f32_16x16x32_bf16 v[76:79], v[158:161], v[210:213], v[76:79]
	s_setprio 0
	s_setprio 1
	v_mfma_f32_16x16x32_bf16 v[120:123], v[162:165], v[182:185], 0
	v_mfma_f32_16x16x32_bf16 v[116:119], v[170:173], v[182:185], 0
	v_mfma_f32_16x16x32_bf16 v[104:107], v[162:165], v[190:193], 0
	v_mfma_f32_16x16x32_bf16 v[100:103], v[170:173], v[190:193], 0
	v_mfma_f32_16x16x32_bf16 v[88:91], v[162:165], v[198:201], 0
	v_mfma_f32_16x16x32_bf16 v[84:87], v[170:173], v[198:201], 0
	v_mfma_f32_16x16x32_bf16 v[72:75], v[162:165], v[206:209], 0
	v_mfma_f32_16x16x32_bf16 v[68:71], v[170:173], v[206:209], 0
	v_mfma_f32_16x16x32_bf16 v[120:123], v[166:169], v[186:189], v[120:123]
	v_mfma_f32_16x16x32_bf16 v[116:119], v[174:177], v[186:189], v[116:119]
	v_mfma_f32_16x16x32_bf16 v[104:107], v[166:169], v[194:197], v[104:107]
	v_mfma_f32_16x16x32_bf16 v[100:103], v[174:177], v[194:197], v[100:103]
	v_mfma_f32_16x16x32_bf16 v[88:91], v[166:169], v[202:205], v[88:91]
	v_mfma_f32_16x16x32_bf16 v[84:87], v[174:177], v[202:205], v[84:87]
	v_mfma_f32_16x16x32_bf16 v[72:75], v[166:169], v[210:213], v[72:75]
	v_mfma_f32_16x16x32_bf16 v[68:71], v[174:177], v[210:213], v[68:71]
	s_barrier
	s_setprio 0
	s_add_i32 s31, s57, s42
	v_lshl_add_u64 v[178:179], s[36:37], 0, v[2:3]
	s_mov_b32 m0, s31
	ds_read_b128 v[182:185], v148 offset:16384
	ds_read_b128 v[186:189], v148 offset:17408
	ds_read_b128 v[190:193], v148 offset:18432
	ds_read_b128 v[194:197], v148 offset:19456
	ds_read_b128 v[198:201], v148 offset:20480
	ds_read_b128 v[202:205], v148 offset:21504
	ds_read_b128 v[206:209], v148 offset:22528
	ds_read_b128 v[210:213], v148 offset:23552
	global_load_lds_dwordx4 v[178:179], off
	s_add_i32 m0, s31, 0x2000
	s_add_u32 s62, s36, 0x80000
	v_lshl_add_u64 v[214:215], s[36:37], 0, v[132:133]
	s_addc_u32 s63, s37, 0
	s_add_i32 s26, s26, s42
	global_load_lds_dwordx4 v[214:215], off
	v_lshl_add_u64 v[216:217], s[62:63], 0, v[2:3]
	s_mov_b32 m0, s26
	v_lshl_add_u64 v[218:219], s[38:39], 0, v[134:135]
	global_load_lds_dwordx4 v[216:217], off
	v_lshl_add_u64 v[216:217], s[62:63], 0, v[132:133]
	s_add_i32 m0, s26, 0x2000
	s_nop 0
	global_load_lds_dwordx4 v[216:217], off
	v_lshl_add_u64 v[216:217], s[38:39], 0, v[136:137]
	s_mov_b32 m0, s43
	s_nop 0
	global_load_lds_dwordx4 v[216:217], off
	s_mov_b32 m0, s44
	s_nop 0
	global_load_lds_dwordx4 v[218:219], off
	s_waitcnt vmcnt(8)
	s_waitcnt lgkmcnt(0)
	s_setprio 1
	s_barrier
; #define PG8_STAGE(bufoff, gbase, voff) do { _Pragma("unroll") for (int _i = 0; _i < 2; ++_i) \
;         __builtin_amdgcn_global_load_lds((const unsigned*)((const char*)(gbase) + (voff)[_i]), (PG8_LAS unsigned*)(lds + (bufoff) + ldsw + _i * 8192), 16, 0, 0); } while (0)
; #define PG8_LDA(dst, b, h) do { _Pragma("unroll") for (int m = 0; m < 4; ++m) _Pragma("unroll") for (int k = 0; k < 2; ++k) dst[m][k] = *(const PG8_LAS bf16x8*)(lds + PG8_SA(b, h) + aoff + m * 2048 + k * 1024); } while (0)
; #define PG8_LDB(dst, b, h) do { _Pragma("unroll") for (int n = 0; n < 2; ++n) _Pragma("unroll") for (int k = 0; k < 2; ++k) dst[n][k] = *(const PG8_LAS bf16x8*)(lds + PG8_SB(b, h) + boff + n * 2048 + k * 1024); } while (0)
; #define PG8_MMA(ai, bj, At, Bt) do { __builtin_amdgcn_s_setprio(1); _Pragma("unroll") for (int m = 0; m < 4; ++m) _Pragma("unroll") for (int n = 0; n < 2; ++n) _Pragma("unroll") for (int k = 0; k < 2; ++k) \
;         acc[ai][bj][m][n] = __builtin_amdgcn_mfma_f32_16x16x32_bf16(Bt[n][k], At[m][k], acc[ai][bj][m][n], 0, 0, 0); __builtin_amdgcn_s_setprio(0); } while (0)
; #define PG8_WAIT_V(n) asm volatile("s_waitcnt vmcnt(" #n ")" ::: "memory")
; #define PG8_WAIT_L(n) asm volatile("s_waitcnt lgkmcnt(" #n ")" ::: "memory")
; #define PG8_BAR __builtin_amdgcn_s_barrier()
; #define PG8_SCHED __builtin_amdgcn_sched_barrier(0)
; template <class Epi, class Sched, bool ALIGN_EPI = false, bool SP2 = false>
; __device__ __forceinline__ void gemm_phase(PG8_LAS unsigned char* lds, const Gemm g, const Sched& S, const Epi& E) {
;     ...
;             PG8_WAIT_V(8); PG8_WAIT_L(0); PG8_BAR; PG8_MMA(1, 0, At, B0); PG8_MMA(1, 1, At, B1); PG8_BAR; PG8_SCHED;
;             PG8_LDB(B0, 1, 0); PG8_LDB(B1, 1, 1); PG8_SCHED; PG8_LDA(At, 1, 0); PG8_STAGE(PG8_SA(0, 1), a2 + hstep, voffA);
;             PG8_WAIT_V(8); PG8_WAIT_L(0); PG8_BAR; PG8_MMA(0, 0, At, B0); PG8_MMA(0, 1, At, B1); PG8_BAR; PG8_SCHED;
	v_mfma_f32_16x16x32_bf16 v[64:67], v[142:145], v[182:185], 0
	v_mfma_f32_16x16x32_bf16 v[60:63], v[154:157], v[182:185], 0
	v_mfma_f32_16x16x32_bf16 v[48:51], v[142:145], v[190:193], 0
	v_mfma_f32_16x16x32_bf16 v[44:47], v[154:157], v[190:193], 0
	v_mfma_f32_16x16x32_bf16 v[32:35], v[142:145], v[198:201], 0
	v_mfma_f32_16x16x32_bf16 v[28:31], v[154:157], v[198:201], 0
	v_mfma_f32_16x16x32_bf16 v[16:19], v[142:145], v[206:209], 0
	v_mfma_f32_16x16x32_bf16 v[12:15], v[154:157], v[206:209], 0
	v_mfma_f32_16x16x32_bf16 v[64:67], v[150:153], v[186:189], v[64:67]
	v_mfma_f32_16x16x32_bf16 v[60:63], v[158:161], v[186:189], v[60:63]
	v_mfma_f32_16x16x32_bf16 v[48:51], v[150:153], v[194:197], v[48:51]
	v_mfma_f32_16x16x32_bf16 v[44:47], v[158:161], v[194:197], v[44:47]
	v_mfma_f32_16x16x32_bf16 v[32:35], v[150:153], v[202:205], v[32:35]
	v_mfma_f32_16x16x32_bf16 v[28:31], v[158:161], v[202:205], v[28:31]
	v_mfma_f32_16x16x32_bf16 v[16:19], v[150:153], v[210:213], v[16:19]
	v_mfma_f32_16x16x32_bf16 v[12:15], v[158:161], v[210:213], v[12:15]
	s_setprio 0
	s_setprio 1
	v_mfma_f32_16x16x32_bf16 v[56:59], v[162:165], v[182:185], 0
	v_mfma_f32_16x16x32_bf16 v[52:55], v[170:173], v[182:185], 0
	v_mfma_f32_16x16x32_bf16 v[40:43], v[162:165], v[190:193], 0
	v_mfma_f32_16x16x32_bf16 v[36:39], v[170:173], v[190:193], 0
	v_mfma_f32_16x16x32_bf16 v[24:27], v[162:165], v[198:201], 0
	v_mfma_f32_16x16x32_bf16 v[20:23], v[170:173], v[198:201], 0
	v_mfma_f32_16x16x32_bf16 v[8:11], v[162:165], v[206:209], 0
	v_mfma_f32_16x16x32_bf16 v[4:7], v[170:173], v[206:209], 0
	v_mfma_f32_16x16x32_bf16 v[56:59], v[166:169], v[186:189], v[56:59]
	v_mfma_f32_16x16x32_bf16 v[52:55], v[174:177], v[186:189], v[52:55]
	v_mfma_f32_16x16x32_bf16 v[40:43], v[166:169], v[194:197], v[40:43]
	v_mfma_f32_16x16x32_bf16 v[36:39], v[174:177], v[194:197], v[36:39]
	v_mfma_f32_16x16x32_bf16 v[24:27], v[166:169], v[202:205], v[24:27]
	v_mfma_f32_16x16x32_bf16 v[20:23], v[174:177], v[202:205], v[20:23]
	v_mfma_f32_16x16x32_bf16 v[8:11], v[166:169], v[210:213], v[8:11]
	v_mfma_f32_16x16x32_bf16 v[4:7], v[174:177], v[210:213], v[4:7]
	s_barrier
	s_setprio 0
	s_add_i32 s26, 0, 0x18000
	v_add_u32_e32 v149, s26, v146
	s_add_i32 s31, 0, 0x1c000
	ds_read_b128 v[142:145], v149
	ds_read_b128 v[150:153], v149 offset:1024
	ds_read_b128 v[154:157], v149 offset:2048
	ds_read_b128 v[158:161], v149 offset:3072
	v_add_u32_e32 v149, s31, v146
	ds_read_b128 v[162:165], v149
	ds_read_b128 v[166:169], v149 offset:1024
	ds_read_b128 v[170:173], v149 offset:2048
	ds_read_b128 v[174:177], v149 offset:3072
	s_add_u32 s38, s38, 0x80000
	s_addc_u32 s39, s39, 0
	s_mov_b32 m0, s45
	v_lshl_add_u64 v[220:221], s[38:39], 0, v[136:137]
	ds_read_b128 v[182:185], v148 offset:32768
	ds_read_b128 v[186:189], v148 offset:33792
	ds_read_b128 v[190:193], v148 offset:34816
	ds_read_b128 v[194:197], v148 offset:35840
	ds_read_b128 v[198:201], v148 offset:36864
	ds_read_b128 v[202:205], v148 offset:37888
	ds_read_b128 v[206:209], v148 offset:38912
	ds_read_b128 v[210:213], v148 offset:39936
	global_load_lds_dwordx4 v[220:221], off
	v_lshl_add_u64 v[220:221], s[38:39], 0, v[134:135]
	s_mov_b32 m0, s46
	s_nop 0
	global_load_lds_dwordx4 v[220:221], off
	s_waitcnt vmcnt(8)
	s_waitcnt lgkmcnt(0)
	s_setprio 1
	s_barrier
	v_mfma_f32_16x16x32_bf16 v[128:131], v[142:145], v[182:185], v[128:131]
	v_mfma_f32_16x16x32_bf16 v[124:127], v[154:157], v[182:185], v[124:127]
	v_mfma_f32_16x16x32_bf16 v[112:115], v[142:145], v[190:193], v[112:115]
	v_mfma_f32_16x16x32_bf16 v[108:111], v[154:157], v[190:193], v[108:111]
	v_mfma_f32_16x16x32_bf16 v[96:99], v[142:145], v[198:201], v[96:99]
	v_mfma_f32_16x16x32_bf16 v[92:95], v[154:157], v[198:201], v[92:95]
	v_mfma_f32_16x16x32_bf16 v[80:83], v[142:145], v[206:209], v[80:83]
	v_mfma_f32_16x16x32_bf16 v[76:79], v[154:157], v[206:209], v[76:79]
	v_mfma_f32_16x16x32_bf16 v[128:131], v[150:153], v[186:189], v[128:131]
	v_mfma_f32_16x16x32_bf16 v[124:127], v[158:161], v[186:189], v[124:127]
	v_mfma_f32_16x16x32_bf16 v[112:115], v[150:153], v[194:197], v[112:115]
	v_mfma_f32_16x16x32_bf16 v[108:111], v[158:161], v[194:197], v[108:111]
	v_mfma_f32_16x16x32_bf16 v[96:99], v[150:153], v[202:205], v[96:99]
	v_mfma_f32_16x16x32_bf16 v[92:95], v[158:161], v[202:205], v[92:95]
	v_mfma_f32_16x16x32_bf16 v[80:83], v[150:153], v[210:213], v[80:83]
	v_mfma_f32_16x16x32_bf16 v[76:79], v[158:161], v[210:213], v[76:79]
	s_setprio 0
	s_setprio 1
	v_mfma_f32_16x16x32_bf16 v[120:123], v[162:165], v[182:185], v[120:123]
	v_mfma_f32_16x16x32_bf16 v[116:119], v[170:173], v[182:185], v[116:119]
	v_mfma_f32_16x16x32_bf16 v[104:107], v[162:165], v[190:193], v[104:107]
	v_mfma_f32_16x16x32_bf16 v[100:103], v[170:173], v[190:193], v[100:103]
	v_mfma_f32_16x16x32_bf16 v[88:91], v[162:165], v[198:201], v[88:91]
	v_mfma_f32_16x16x32_bf16 v[84:87], v[170:173], v[198:201], v[84:87]
	v_mfma_f32_16x16x32_bf16 v[72:75], v[162:165], v[206:209], v[72:75]
	v_mfma_f32_16x16x32_bf16 v[68:71], v[170:173], v[206:209], v[68:71]
	v_mfma_f32_16x16x32_bf16 v[120:123], v[166:169], v[186:189], v[120:123]
	v_mfma_f32_16x16x32_bf16 v[116:119], v[174:177], v[186:189], v[116:119]
	v_mfma_f32_16x16x32_bf16 v[104:107], v[166:169], v[194:197], v[104:107]
	v_mfma_f32_16x16x32_bf16 v[100:103], v[174:177], v[194:197], v[100:103]
	v_mfma_f32_16x16x32_bf16 v[88:91], v[166:169], v[202:205], v[88:91]
	v_mfma_f32_16x16x32_bf16 v[84:87], v[174:177], v[202:205], v[84:87]
	v_mfma_f32_16x16x32_bf16 v[72:75], v[166:169], v[210:213], v[72:75]
	v_mfma_f32_16x16x32_bf16 v[68:71], v[174:177], v[210:213], v[68:71]
	s_barrier
; #define PG8_STAGE(bufoff, gbase, voff) do { _Pragma("unroll") for (int _i = 0; _i < 2; ++_i) \
;         __builtin_amdgcn_global_load_lds((const unsigned*)((const char*)(gbase) + (voff)[_i]), (PG8_LAS unsigned*)(lds + (bufoff) + ldsw + _i * 8192), 16, 0, 0); } while (0)
; #define PG8_LDA(dst, b, h) do { _Pragma("unroll") for (int m = 0; m < 4; ++m) _Pragma("unroll") for (int k = 0; k < 2; ++k) dst[m][k] = *(const PG8_LAS bf16x8*)(lds + PG8_SA(b, h) + aoff + m * 2048 + k * 1024); } while (0)
; #define PG8_LDB(dst, b, h) do { _Pragma("unroll") for (int n = 0; n < 2; ++n) _Pragma("unroll") for (int k = 0; k < 2; ++k) dst[n][k] = *(const PG8_LAS bf16x8*)(lds + PG8_SB(b, h) + boff + n * 2048 + k * 1024); } while (0)
; template <class Epi, class Sched, bool ALIGN_EPI = false, bool SP2 = false>
; __device__ __forceinline__ void gemm_phase(PG8_LAS unsigned char* lds, const Gemm g, const Sched& S, const Epi& E) {
;     ...
;         for (int t = 0; t < nt; t += 2) {
;             const bool last = (t == nt - 2);
;             const char* a1 = cA + (size_t)(t + 1) * kstep;
;             const char* a2 = last ? nA : cA + (size_t)(t + 2) * kstep; const char* b2 = last ? nB : cB + (size_t)(t + 2) * kstep;
;             const char* a3 = a2 + kstep; const char* b3 = b2 + kstep;
;             if (last && has_next) S.a_ready(nxt);
;             if constexpr (SP2) {
;             PG8_LDB(B0, 0, 0); PG8_LDB(B1, 0, 1); PG8_SCHED; PG8_LDA(At, 0, 0); PG8_STAGE(PG8_SA(1, 1), a1 + hstep, voffA);
;             PG8_WAIT_V(8); PG8_WAIT_L(0); PG8_BAR; PG8_MMA(0, 0, At, B0); PG8_MMA(0, 1, At, B1); PG8_BAR; PG8_SCHED;
;             PG8_LDA(At, 0, 1); PG8_STAGE(PG8_SB(0, 0), b2, voffB); PG8_STAGE(PG8_SB(0, 1), b2 + hstep, voffB); PG8_STAGE(PG8_SA(0, 0), a2, voffA);
;             PG8_WAIT_V(8); PG8_WAIT_L(0); PG8_BAR; PG8_MMA(1, 0, At, B0); PG8_MMA(1, 1, At, B1); PG8_BAR; PG8_SCHED;
;             PG8_LDB(B0, 1, 0); PG8_LDB(B1, 1, 1); PG8_SCHED; PG8_LDA(At, 1, 0); PG8_STAGE(PG8_SA(0, 1), a2 + hstep, voffA);
;             PG8_WAIT_V(8); PG8_WAIT_L(0); PG8_BAR; PG8_MMA(0, 0, At, B0); PG8_MMA(0, 1, At, B1); PG8_BAR; PG8_SCHED;
;             PG8_LDA(At, 1, 1); PG8_STAGE(PG8_SB(1, 0), b3, voffB); PG8_STAGE(PG8_SB(1, 1), b3 + hstep, voffB); PG8_STAGE(PG8_SA(1, 0), a3, voffA);
;             PG8_WAIT_V(8); PG8_WAIT_L(0); PG8_BAR; PG8_MMA(1, 0, At, B0); PG8_MMA(1, 1, At, B1); PG8_BAR; PG8_SCHED;
	s_setprio 0
	s_add_i32 s26, s26, s42
	v_lshl_add_u64 v[178:179], v[178:179], 0, s[60:61]
	s_mov_b32 m0, s26
	ds_read_b128 v[182:185], v148 offset:49152
	ds_read_b128 v[186:189], v148 offset:50176
	ds_read_b128 v[190:193], v148 offset:51200
	ds_read_b128 v[194:197], v148 offset:52224
	ds_read_b128 v[198:201], v148 offset:53248
	ds_read_b128 v[202:205], v148 offset:54272
	ds_read_b128 v[206:209], v148 offset:55296
	ds_read_b128 v[210:213], v148 offset:56320
	global_load_lds_dwordx4 v[178:179], off
	s_add_i32 m0, s26, 0x2000
	s_add_u32 s36, s36, 0x80080
	v_lshl_add_u64 v[178:179], v[214:215], 0, s[60:61]
	s_addc_u32 s37, s37, 0
	s_add_i32 s26, s31, s42
	global_load_lds_dwordx4 v[178:179], off
	v_lshl_add_u64 v[178:179], s[36:37], 0, v[2:3]
	s_mov_b32 m0, s26
	s_nop 0
	global_load_lds_dwordx4 v[178:179], off
	v_lshl_add_u64 v[178:179], s[36:37], 0, v[132:133]
	s_add_i32 m0, s26, 0x2000
	s_nop 0
	global_load_lds_dwordx4 v[178:179], off
	v_lshl_add_u64 v[178:179], v[216:217], 0, s[60:61]
	s_mov_b32 m0, s47
	s_nop 0
	global_load_lds_dwordx4 v[178:179], off
	v_lshl_add_u64 v[178:179], v[218:219], 0, s[60:61]
	s_mov_b32 m0, s50
	s_nop 0
	global_load_lds_dwordx4 v[178:179], off
	s_waitcnt vmcnt(8)
	s_waitcnt lgkmcnt(0)
	s_setprio 1
	s_barrier
	v_mfma_f32_16x16x32_bf16 v[64:67], v[142:145], v[182:185], v[64:67]
	v_mfma_f32_16x16x32_bf16 v[60:63], v[154:157], v[182:185], v[60:63]
	v_mfma_f32_16x16x32_bf16 v[48:51], v[142:145], v[190:193], v[48:51]
	v_mfma_f32_16x16x32_bf16 v[44:47], v[154:157], v[190:193], v[44:47]
	v_mfma_f32_16x16x32_bf16 v[32:35], v[142:145], v[198:201], v[32:35]
	v_mfma_f32_16x16x32_bf16 v[28:31], v[154:157], v[198:201], v[28:31]
	v_mfma_f32_16x16x32_bf16 v[16:19], v[142:145], v[206:209], v[16:19]
	v_mfma_f32_16x16x32_bf16 v[12:15], v[154:157], v[206:209], v[12:15]
	v_mfma_f32_16x16x32_bf16 v[64:67], v[150:153], v[186:189], v[64:67]
	v_mfma_f32_16x16x32_bf16 v[60:63], v[158:161], v[186:189], v[60:63]
	v_mfma_f32_16x16x32_bf16 v[48:51], v[150:153], v[194:197], v[48:51]
	v_mfma_f32_16x16x32_bf16 v[44:47], v[158:161], v[194:197], v[44:47]
	v_mfma_f32_16x16x32_bf16 v[32:35], v[150:153], v[202:205], v[32:35]
	v_mfma_f32_16x16x32_bf16 v[28:31], v[158:161], v[202:205], v[28:31]
	v_mfma_f32_16x16x32_bf16 v[16:19], v[150:153], v[210:213], v[16:19]
	v_mfma_f32_16x16x32_bf16 v[12:15], v[158:161], v[210:213], v[12:15]
	s_setprio 0
	s_setprio 1
	v_mfma_f32_16x16x32_bf16 v[56:59], v[162:165], v[182:185], v[56:59]
	v_mfma_f32_16x16x32_bf16 v[52:55], v[170:173], v[182:185], v[52:55]
	v_mfma_f32_16x16x32_bf16 v[40:43], v[162:165], v[190:193], v[40:43]
	v_mfma_f32_16x16x32_bf16 v[36:39], v[170:173], v[190:193], v[36:39]
	v_mfma_f32_16x16x32_bf16 v[24:27], v[162:165], v[198:201], v[24:27]
	v_mfma_f32_16x16x32_bf16 v[20:23], v[170:173], v[198:201], v[20:23]
	v_mfma_f32_16x16x32_bf16 v[8:11], v[162:165], v[206:209], v[8:11]
	v_mfma_f32_16x16x32_bf16 v[4:7], v[170:173], v[206:209], v[4:7]
	v_mfma_f32_16x16x32_bf16 v[56:59], v[166:169], v[186:189], v[56:59]
	v_mfma_f32_16x16x32_bf16 v[52:55], v[174:177], v[186:189], v[52:55]
	v_mfma_f32_16x16x32_bf16 v[40:43], v[166:169], v[194:197], v[40:43]
	v_mfma_f32_16x16x32_bf16 v[36:39], v[174:177], v[194:197], v[36:39]
	v_mfma_f32_16x16x32_bf16 v[24:27], v[166:169], v[202:205], v[24:27]
	v_mfma_f32_16x16x32_bf16 v[20:23], v[174:177], v[202:205], v[20:23]
	v_mfma_f32_16x16x32_bf16 v[8:11], v[166:169], v[210:213], v[8:11]
	v_mfma_f32_16x16x32_bf16 v[4:7], v[174:177], v[210:213], v[4:7]
	s_barrier
	s_setprio 0
	s_add_i32 s56, s56, 2
	s_add_u32 s34, s34, 0x100
	s_addc_u32 s35, s35, 0
	s_add_u32 s54, s54, 0x100
	s_addc_u32 s55, s55, 0
	s_cmp_gt_u32 s56, 29
	s_cbranch_scc0 .LBB0_2104
	s_branch .Lpeel_post_p6
.LBB0_2104:
	s_add_u32 s26, s34, 0xfff80080
	s_addc_u32 s31, s35, -1
	s_add_i32 s57, 0, 0x10000
	s_cmp_eq_u32 s56, 28
	s_cselect_b32 s39, s17, s31
	s_cselect_b32 s38, s52, s26
	v_add_u32_e32 v149, s57, v146
	s_cselect_b32 s37, s15, s55
	s_cselect_b32 s36, s53, s54
	s_add_i32 s26, 0, 0x14000
	ds_read_b128 v[142:145], v149
	ds_read_b128 v[150:153], v149 offset:1024
	ds_read_b128 v[154:157], v149 offset:2048
	ds_read_b128 v[158:161], v149 offset:3072
	v_add_u32_e32 v149, s26, v146
	ds_read_b128 v[162:165], v149
	ds_read_b128 v[166:169], v149 offset:1024
	ds_read_b128 v[170:173], v149 offset:2048
	ds_read_b128 v[174:177], v149 offset:3072
	v_lshl_add_u64 v[178:179], s[34:35], 0, v[138:139]
	s_add_i32 m0, s43, 0xc000
	ds_read_b128 v[182:185], v148
	ds_read_b128 v[186:189], v148 offset:1024
	ds_read_b128 v[190:193], v148 offset:2048
	ds_read_b128 v[194:197], v148 offset:3072
	ds_read_b128 v[198:201], v148 offset:4096
	ds_read_b128 v[202:205], v148 offset:5120
	ds_read_b128 v[206:209], v148 offset:6144
	ds_read_b128 v[210:213], v148 offset:7168
	global_load_lds_dwordx4 v[178:179], off
	v_lshl_add_u64 v[178:179], s[34:35], 0, v[140:141]
	s_add_i32 m0, s43, 0xe000
	s_nop 0
	global_load_lds_dwordx4 v[178:179], off
	s_waitcnt vmcnt(8)
	s_waitcnt lgkmcnt(0)
	s_setprio 1
	s_barrier
; #define PG8_STAGE(bufoff, gbase, voff) do { _Pragma("unroll") for (int _i = 0; _i < 2; ++_i) \
;         __builtin_amdgcn_global_load_lds((const unsigned*)((const char*)(gbase) + (voff)[_i]), (PG8_LAS unsigned*)(lds + (bufoff) + ldsw + _i * 8192), 16, 0, 0); } while (0)
; #define PG8_LDA(dst, b, h) do { _Pragma("unroll") for (int m = 0; m < 4; ++m) _Pragma("unroll") for (int k = 0; k < 2; ++k) dst[m][k] = *(const PG8_LAS bf16x8*)(lds + PG8_SA(b, h) + aoff + m * 2048 + k * 1024); } while (0)
; #define PG8_LDB(dst, b, h) do { _Pragma("unroll") for (int n = 0; n < 2; ++n) _Pragma("unroll") for (int k = 0; k < 2; ++k) dst[n][k] = *(const PG8_LAS bf16x8*)(lds + PG8_SB(b, h) + boff + n * 2048 + k * 1024); } while (0)
; #define PG8_MMA(ai, bj, At, Bt) do { __builtin_amdgcn_s_setprio(1); _Pragma("unroll") for (int m = 0; m < 4; ++m) _Pragma("unroll") for (int n = 0; n < 2; ++n) _Pragma("unroll") for (int k = 0; k < 2; ++k) \
;         acc[ai][bj][m][n] = __builtin_amdgcn_mfma_f32_16x16x32_bf16(Bt[n][k], At[m][k], acc[ai][bj][m][n], 0, 0, 0); __builtin_amdgcn_s_setprio(0); } while (0)
; #define PG8_WAIT_V(n) asm volatile("s_waitcnt vmcnt(" #n ")" ::: "memory")
; #define PG8_WAIT_L(n) asm volatile("s_waitcnt lgkmcnt(" #n ")" ::: "memory")
; #define PG8_BAR __builtin_amdgcn_s_barrier()
; #define PG8_SCHED __builtin_amdgcn_sched_barrier(0)
; template <class Epi, class Sched, bool ALIGN_EPI = false, bool SP2 = false>
; __device__ __forceinline__ void gemm_phase(PG8_LAS unsigned char* lds, const Gemm g, const Sched& S, const Epi& E) {
;     ...
;             PG8_LDB(B0, 0, 0); PG8_LDB(B1, 0, 1); PG8_SCHED; PG8_LDA(At, 0, 0); PG8_STAGE(PG8_SA(1, 1), a1 + hstep, voffA);
;             PG8_WAIT_V(8); PG8_WAIT_L(0); PG8_BAR; PG8_MMA(0, 0, At, B0); PG8_MMA(0, 1, At, B1); PG8_BAR; PG8_SCHED;
;             PG8_LDA(At, 0, 1); PG8_STAGE(PG8_SB(0, 0), b2, voffB); PG8_STAGE(PG8_SB(0, 1), b2 + hstep, voffB); PG8_STAGE(PG8_SA(0, 0), a2, voffA);
;             PG8_WAIT_V(8); PG8_WAIT_L(0); PG8_BAR; PG8_MMA(1, 0, At, B0); PG8_MMA(1, 1, At, B1); PG8_BAR; PG8_SCHED;
	v_mfma_f32_16x16x32_bf16 v[128:131], v[142:145], v[182:185], v[128:131]
	v_mfma_f32_16x16x32_bf16 v[124:127], v[154:157], v[182:185], v[124:127]
	v_mfma_f32_16x16x32_bf16 v[112:115], v[142:145], v[190:193], v[112:115]
	v_mfma_f32_16x16x32_bf16 v[108:111], v[154:157], v[190:193], v[108:111]
	v_mfma_f32_16x16x32_bf16 v[96:99], v[142:145], v[198:201], v[96:99]
	v_mfma_f32_16x16x32_bf16 v[92:95], v[154:157], v[198:201], v[92:95]
	v_mfma_f32_16x16x32_bf16 v[80:83], v[142:145], v[206:209], v[80:83]
	v_mfma_f32_16x16x32_bf16 v[76:79], v[154:157], v[206:209], v[76:79]
	v_mfma_f32_16x16x32_bf16 v[128:131], v[150:153], v[186:189], v[128:131]
	v_mfma_f32_16x16x32_bf16 v[124:127], v[158:161], v[186:189], v[124:127]
	v_mfma_f32_16x16x32_bf16 v[112:115], v[150:153], v[194:197], v[112:115]
	v_mfma_f32_16x16x32_bf16 v[108:111], v[158:161], v[194:197], v[108:111]
	v_mfma_f32_16x16x32_bf16 v[96:99], v[150:153], v[202:205], v[96:99]
	v_mfma_f32_16x16x32_bf16 v[92:95], v[158:161], v[202:205], v[92:95]
	v_mfma_f32_16x16x32_bf16 v[80:83], v[150:153], v[210:213], v[80:83]
	v_mfma_f32_16x16x32_bf16 v[76:79], v[158:161], v[210:213], v[76:79]
	s_setprio 0
	s_setprio 1
	v_mfma_f32_16x16x32_bf16 v[120:123], v[162:165], v[182:185], v[120:123]
	v_mfma_f32_16x16x32_bf16 v[116:119], v[170:173], v[182:185], v[116:119]
	v_mfma_f32_16x16x32_bf16 v[104:107], v[162:165], v[190:193], v[104:107]
	v_mfma_f32_16x16x32_bf16 v[100:103], v[170:173], v[190:193], v[100:103]
	v_mfma_f32_16x16x32_bf16 v[88:91], v[162:165], v[198:201], v[88:91]
	v_mfma_f32_16x16x32_bf16 v[84:87], v[170:173], v[198:201], v[84:87]
	v_mfma_f32_16x16x32_bf16 v[72:75], v[162:165], v[206:209], v[72:75]
	v_mfma_f32_16x16x32_bf16 v[68:71], v[170:173], v[206:209], v[68:71]
	v_mfma_f32_16x16x32_bf16 v[120:123], v[166:169], v[186:189], v[120:123]
	v_mfma_f32_16x16x32_bf16 v[116:119], v[174:177], v[186:189], v[116:119]
	v_mfma_f32_16x16x32_bf16 v[104:107], v[166:169], v[194:197], v[104:107]
	v_mfma_f32_16x16x32_bf16 v[100:103], v[174:177], v[194:197], v[100:103]
	v_mfma_f32_16x16x32_bf16 v[88:91], v[166:169], v[202:205], v[88:91]
	v_mfma_f32_16x16x32_bf16 v[84:87], v[174:177], v[202:205], v[84:87]
	v_mfma_f32_16x16x32_bf16 v[72:75], v[166:169], v[210:213], v[72:75]
	v_mfma_f32_16x16x32_bf16 v[68:71], v[174:177], v[210:213], v[68:71]
	s_barrier
	s_setprio 0
	s_add_i32 s31, s57, s42
	v_lshl_add_u64 v[178:179], s[36:37], 0, v[2:3]
	s_mov_b32 m0, s31
	ds_read_b128 v[182:185], v148 offset:16384
	ds_read_b128 v[186:189], v148 offset:17408
	ds_read_b128 v[190:193], v148 offset:18432
	ds_read_b128 v[194:197], v148 offset:19456
	ds_read_b128 v[198:201], v148 offset:20480
	ds_read_b128 v[202:205], v148 offset:21504
	ds_read_b128 v[206:209], v148 offset:22528
	ds_read_b128 v[210:213], v148 offset:23552
	global_load_lds_dwordx4 v[178:179], off
	s_add_i32 m0, s31, 0x2000
	s_add_u32 s62, s36, 0x80000
	v_lshl_add_u64 v[214:215], s[36:37], 0, v[132:133]
	s_addc_u32 s63, s37, 0
	s_add_i32 s26, s26, s42
	global_load_lds_dwordx4 v[214:215], off
	v_lshl_add_u64 v[216:217], s[62:63], 0, v[2:3]
	s_mov_b32 m0, s26
	v_lshl_add_u64 v[218:219], s[38:39], 0, v[134:135]
	global_load_lds_dwordx4 v[216:217], off
	v_lshl_add_u64 v[216:217], s[62:63], 0, v[132:133]
	s_add_i32 m0, s26, 0x2000
	s_nop 0
	global_load_lds_dwordx4 v[216:217], off
	v_lshl_add_u64 v[216:217], s[38:39], 0, v[136:137]
	s_mov_b32 m0, s43
	s_nop 0
	global_load_lds_dwordx4 v[216:217], off
	s_mov_b32 m0, s44
	s_nop 0
	global_load_lds_dwordx4 v[218:219], off
	s_waitcnt vmcnt(8)
	s_waitcnt lgkmcnt(0)
	s_setprio 1
	s_barrier
	v_mfma_f32_16x16x32_bf16 v[64:67], v[142:145], v[182:185], v[64:67]
	v_mfma_f32_16x16x32_bf16 v[60:63], v[154:157], v[182:185], v[60:63]
	v_mfma_f32_16x16x32_bf16 v[48:51], v[142:145], v[190:193], v[48:51]
	v_mfma_f32_16x16x32_bf16 v[44:47], v[154:157], v[190:193], v[44:47]
	v_mfma_f32_16x16x32_bf16 v[32:35], v[142:145], v[198:201], v[32:35]
	v_mfma_f32_16x16x32_bf16 v[28:31], v[154:157], v[198:201], v[28:31]
	v_mfma_f32_16x16x32_bf16 v[16:19], v[142:145], v[206:209], v[16:19]
	v_mfma_f32_16x16x32_bf16 v[12:15], v[154:157], v[206:209], v[12:15]
	v_mfma_f32_16x16x32_bf16 v[64:67], v[150:153], v[186:189], v[64:67]
	v_mfma_f32_16x16x32_bf16 v[60:63], v[158:161], v[186:189], v[60:63]
	v_mfma_f32_16x16x32_bf16 v[48:51], v[150:153], v[194:197], v[48:51]
	v_mfma_f32_16x16x32_bf16 v[44:47], v[158:161], v[194:197], v[44:47]
	v_mfma_f32_16x16x32_bf16 v[32:35], v[150:153], v[202:205], v[32:35]
	v_mfma_f32_16x16x32_bf16 v[28:31], v[158:161], v[202:205], v[28:31]
	v_mfma_f32_16x16x32_bf16 v[16:19], v[150:153], v[210:213], v[16:19]
	v_mfma_f32_16x16x32_bf16 v[12:15], v[158:161], v[210:213], v[12:15]
	s_setprio 0
	s_setprio 1
	v_mfma_f32_16x16x32_bf16 v[56:59], v[162:165], v[182:185], v[56:59]
	v_mfma_f32_16x16x32_bf16 v[52:55], v[170:173], v[182:185], v[52:55]
	v_mfma_f32_16x16x32_bf16 v[40:43], v[162:165], v[190:193], v[40:43]
	v_mfma_f32_16x16x32_bf16 v[36:39], v[170:173], v[190:193], v[36:39]
	v_mfma_f32_16x16x32_bf16 v[24:27], v[162:165], v[198:201], v[24:27]
	v_mfma_f32_16x16x32_bf16 v[20:23], v[170:173], v[198:201], v[20:23]
	v_mfma_f32_16x16x32_bf16 v[8:11], v[162:165], v[206:209], v[8:11]
	v_mfma_f32_16x16x32_bf16 v[4:7], v[170:173], v[206:209], v[4:7]
	v_mfma_f32_16x16x32_bf16 v[56:59], v[166:169], v[186:189], v[56:59]
	v_mfma_f32_16x16x32_bf16 v[52:55], v[174:177], v[186:189], v[52:55]
	v_mfma_f32_16x16x32_bf16 v[40:43], v[166:169], v[194:197], v[40:43]
	v_mfma_f32_16x16x32_bf16 v[36:39], v[174:177], v[194:197], v[36:39]
	v_mfma_f32_16x16x32_bf16 v[24:27], v[166:169], v[202:205], v[24:27]
	v_mfma_f32_16x16x32_bf16 v[20:23], v[174:177], v[202:205], v[20:23]
	v_mfma_f32_16x16x32_bf16 v[8:11], v[166:169], v[210:213], v[8:11]
	v_mfma_f32_16x16x32_bf16 v[4:7], v[174:177], v[210:213], v[4:7]
	s_barrier
; #define PG8_STAGE(bufoff, gbase, voff) do { _Pragma("unroll") for (int _i = 0; _i < 2; ++_i) \
;         __builtin_amdgcn_global_load_lds((const unsigned*)((const char*)(gbase) + (voff)[_i]), (PG8_LAS unsigned*)(lds + (bufoff) + ldsw + _i * 8192), 16, 0, 0); } while (0)
; #define PG8_LDA(dst, b, h) do { _Pragma("unroll") for (int m = 0; m < 4; ++m) _Pragma("unroll") for (int k = 0; k < 2; ++k) dst[m][k] = *(const PG8_LAS bf16x8*)(lds + PG8_SA(b, h) + aoff + m * 2048 + k * 1024); } while (0)
; #define PG8_LDB(dst, b, h) do { _Pragma("unroll") for (int n = 0; n < 2; ++n) _Pragma("unroll") for (int k = 0; k < 2; ++k) dst[n][k] = *(const PG8_LAS bf16x8*)(lds + PG8_SB(b, h) + boff + n * 2048 + k * 1024); } while (0)
; #define PG8_MMA(ai, bj, At, Bt) do { __builtin_amdgcn_s_setprio(1); _Pragma("unroll") for (int m = 0; m < 4; ++m) _Pragma("unroll") for (int n = 0; n < 2; ++n) _Pragma("unroll") for (int k = 0; k < 2; ++k) \
;         acc[ai][bj][m][n] = __builtin_amdgcn_mfma_f32_16x16x32_bf16(Bt[n][k], At[m][k], acc[ai][bj][m][n], 0, 0, 0); __builtin_amdgcn_s_setprio(0); } while (0)
; #define PG8_WAIT_V(n) asm volatile("s_waitcnt vmcnt(" #n ")" ::: "memory")
; #define PG8_WAIT_L(n) asm volatile("s_waitcnt lgkmcnt(" #n ")" ::: "memory")
; #define PG8_BAR __builtin_amdgcn_s_barrier()
; #define PG8_SCHED __builtin_amdgcn_sched_barrier(0)
; template <class Epi, class Sched, bool ALIGN_EPI = false, bool SP2 = false>
; __device__ __forceinline__ void gemm_phase(PG8_LAS unsigned char* lds, const Gemm g, const Sched& S, const Epi& E) {
;     ...
;             PG8_LDB(B0, 1, 0); PG8_LDB(B1, 1, 1); PG8_SCHED; PG8_LDA(At, 1, 0); PG8_STAGE(PG8_SA(0, 1), a2 + hstep, voffA);
;             PG8_WAIT_V(8); PG8_WAIT_L(0); PG8_BAR; PG8_MMA(0, 0, At, B0); PG8_MMA(0, 1, At, B1); PG8_BAR; PG8_SCHED;
	s_setprio 0
	s_add_i32 s26, 0, 0x18000
	v_add_u32_e32 v149, s26, v146
	s_add_i32 s31, 0, 0x1c000
	ds_read_b128 v[142:145], v149
	ds_read_b128 v[150:153], v149 offset:1024
	ds_read_b128 v[154:157], v149 offset:2048
	ds_read_b128 v[158:161], v149 offset:3072
	v_add_u32_e32 v149, s31, v146
	ds_read_b128 v[162:165], v149
	ds_read_b128 v[166:169], v149 offset:1024
	ds_read_b128 v[170:173], v149 offset:2048
	ds_read_b128 v[174:177], v149 offset:3072
	s_add_u32 s38, s38, 0x80000
	s_addc_u32 s39, s39, 0
	s_mov_b32 m0, s45
	v_lshl_add_u64 v[220:221], s[38:39], 0, v[136:137]
	ds_read_b128 v[182:185], v148 offset:32768
	ds_read_b128 v[186:189], v148 offset:33792
	ds_read_b128 v[190:193], v148 offset:34816
	ds_read_b128 v[194:197], v148 offset:35840
	ds_read_b128 v[198:201], v148 offset:36864
	ds_read_b128 v[202:205], v148 offset:37888
	ds_read_b128 v[206:209], v148 offset:38912
	ds_read_b128 v[210:213], v148 offset:39936
	global_load_lds_dwordx4 v[220:221], off
	v_lshl_add_u64 v[220:221], s[38:39], 0, v[134:135]
	s_mov_b32 m0, s46
	s_nop 0
	global_load_lds_dwordx4 v[220:221], off
	s_waitcnt vmcnt(8)
	s_waitcnt lgkmcnt(0)
	s_setprio 1
	s_barrier
	v_mfma_f32_16x16x32_bf16 v[128:131], v[142:145], v[182:185], v[128:131]
	v_mfma_f32_16x16x32_bf16 v[124:127], v[154:157], v[182:185], v[124:127]
	v_mfma_f32_16x16x32_bf16 v[112:115], v[142:145], v[190:193], v[112:115]
	v_mfma_f32_16x16x32_bf16 v[108:111], v[154:157], v[190:193], v[108:111]
	v_mfma_f32_16x16x32_bf16 v[96:99], v[142:145], v[198:201], v[96:99]
	v_mfma_f32_16x16x32_bf16 v[92:95], v[154:157], v[198:201], v[92:95]
	v_mfma_f32_16x16x32_bf16 v[80:83], v[142:145], v[206:209], v[80:83]
	v_mfma_f32_16x16x32_bf16 v[76:79], v[154:157], v[206:209], v[76:79]
	v_mfma_f32_16x16x32_bf16 v[128:131], v[150:153], v[186:189], v[128:131]
	v_mfma_f32_16x16x32_bf16 v[124:127], v[158:161], v[186:189], v[124:127]
	v_mfma_f32_16x16x32_bf16 v[112:115], v[150:153], v[194:197], v[112:115]
	v_mfma_f32_16x16x32_bf16 v[108:111], v[158:161], v[194:197], v[108:111]
	v_mfma_f32_16x16x32_bf16 v[96:99], v[150:153], v[202:205], v[96:99]
	v_mfma_f32_16x16x32_bf16 v[92:95], v[158:161], v[202:205], v[92:95]
	v_mfma_f32_16x16x32_bf16 v[80:83], v[150:153], v[210:213], v[80:83]
	v_mfma_f32_16x16x32_bf16 v[76:79], v[158:161], v[210:213], v[76:79]
	s_setprio 0
	s_setprio 1
	v_mfma_f32_16x16x32_bf16 v[120:123], v[162:165], v[182:185], v[120:123]
	v_mfma_f32_16x16x32_bf16 v[116:119], v[170:173], v[182:185], v[116:119]
	v_mfma_f32_16x16x32_bf16 v[104:107], v[162:165], v[190:193], v[104:107]
	v_mfma_f32_16x16x32_bf16 v[100:103], v[170:173], v[190:193], v[100:103]
	v_mfma_f32_16x16x32_bf16 v[88:91], v[162:165], v[198:201], v[88:91]
	v_mfma_f32_16x16x32_bf16 v[84:87], v[170:173], v[198:201], v[84:87]
	v_mfma_f32_16x16x32_bf16 v[72:75], v[162:165], v[206:209], v[72:75]
	v_mfma_f32_16x16x32_bf16 v[68:71], v[170:173], v[206:209], v[68:71]
	v_mfma_f32_16x16x32_bf16 v[120:123], v[166:169], v[186:189], v[120:123]
	v_mfma_f32_16x16x32_bf16 v[116:119], v[174:177], v[186:189], v[116:119]
	v_mfma_f32_16x16x32_bf16 v[104:107], v[166:169], v[194:197], v[104:107]
	v_mfma_f32_16x16x32_bf16 v[100:103], v[174:177], v[194:197], v[100:103]
	v_mfma_f32_16x16x32_bf16 v[88:91], v[166:169], v[202:205], v[88:91]
	v_mfma_f32_16x16x32_bf16 v[84:87], v[174:177], v[202:205], v[84:87]
	v_mfma_f32_16x16x32_bf16 v[72:75], v[166:169], v[210:213], v[72:75]
	v_mfma_f32_16x16x32_bf16 v[68:71], v[174:177], v[210:213], v[68:71]
	s_barrier
; #define PG8_STAGE(bufoff, gbase, voff) do { _Pragma("unroll") for (int _i = 0; _i < 2; ++_i) \
;         __builtin_amdgcn_global_load_lds((const unsigned*)((const char*)(gbase) + (voff)[_i]), (PG8_LAS unsigned*)(lds + (bufoff) + ldsw + _i * 8192), 16, 0, 0); } while (0)
; #define PG8_LDA(dst, b, h) do { _Pragma("unroll") for (int m = 0; m < 4; ++m) _Pragma("unroll") for (int k = 0; k < 2; ++k) dst[m][k] = *(const PG8_LAS bf16x8*)(lds + PG8_SA(b, h) + aoff + m * 2048 + k * 1024); } while (0)
; #define PG8_MMA(ai, bj, At, Bt) do { __builtin_amdgcn_s_setprio(1); _Pragma("unroll") for (int m = 0; m < 4; ++m) _Pragma("unroll") for (int n = 0; n < 2; ++n) _Pragma("unroll") for (int k = 0; k < 2; ++k) \
;         acc[ai][bj][m][n] = __builtin_amdgcn_mfma_f32_16x16x32_bf16(Bt[n][k], At[m][k], acc[ai][bj][m][n], 0, 0, 0); __builtin_amdgcn_s_setprio(0); } while (0)
; #define PG8_WAIT_V(n) asm volatile("s_waitcnt vmcnt(" #n ")" ::: "memory")
; #define PG8_WAIT_L(n) asm volatile("s_waitcnt lgkmcnt(" #n ")" ::: "memory")
; #define PG8_BAR __builtin_amdgcn_s_barrier()
; #define PG8_SCHED __builtin_amdgcn_sched_barrier(0)
; template <class Epi, class Sched, bool ALIGN_EPI = false, bool SP2 = false>
; __device__ __forceinline__ void gemm_phase(PG8_LAS unsigned char* lds, const Gemm g, const Sched& S, const Epi& E) {
;     ...
;             PG8_LDA(At, 1, 1); PG8_STAGE(PG8_SB(1, 0), b3, voffB); PG8_STAGE(PG8_SB(1, 1), b3 + hstep, voffB); PG8_STAGE(PG8_SA(1, 0), a3, voffA);
;             PG8_WAIT_V(8); PG8_WAIT_L(0); PG8_BAR; PG8_MMA(1, 0, At, B0); PG8_MMA(1, 1, At, B1); PG8_BAR; PG8_SCHED;
;     ...
;         if constexpr (ALIGN_EPI) { if (wr == 0) PG8_BAR; }
	s_setprio 0
	s_add_i32 s26, s26, s42
	v_lshl_add_u64 v[178:179], v[178:179], 0, s[60:61]
	s_mov_b32 m0, s26
	ds_read_b128 v[182:185], v148 offset:49152
	ds_read_b128 v[186:189], v148 offset:50176
	ds_read_b128 v[190:193], v148 offset:51200
	ds_read_b128 v[194:197], v148 offset:52224
	ds_read_b128 v[198:201], v148 offset:53248
	ds_read_b128 v[202:205], v148 offset:54272
	ds_read_b128 v[206:209], v148 offset:55296
	ds_read_b128 v[210:213], v148 offset:56320
	global_load_lds_dwordx4 v[178:179], off
	s_add_i32 m0, s26, 0x2000
	s_add_u32 s36, s36, 0x80080
	v_lshl_add_u64 v[178:179], v[214:215], 0, s[60:61]
	s_addc_u32 s37, s37, 0
	s_add_i32 s26, s31, s42
	global_load_lds_dwordx4 v[178:179], off
	v_lshl_add_u64 v[178:179], s[36:37], 0, v[2:3]
	s_mov_b32 m0, s26
	s_nop 0
	global_load_lds_dwordx4 v[178:179], off
	v_lshl_add_u64 v[178:179], s[36:37], 0, v[132:133]
	s_add_i32 m0, s26, 0x2000
	s_nop 0
	global_load_lds_dwordx4 v[178:179], off
	v_lshl_add_u64 v[178:179], v[216:217], 0, s[60:61]
	s_mov_b32 m0, s47
	s_nop 0
	global_load_lds_dwordx4 v[178:179], off
	v_lshl_add_u64 v[178:179], v[218:219], 0, s[60:61]
	s_mov_b32 m0, s50
	s_nop 0
	global_load_lds_dwordx4 v[178:179], off
	s_waitcnt vmcnt(8)
	s_waitcnt lgkmcnt(0)
	s_setprio 1
	s_barrier
	v_mfma_f32_16x16x32_bf16 v[64:67], v[142:145], v[182:185], v[64:67]
	v_mfma_f32_16x16x32_bf16 v[60:63], v[154:157], v[182:185], v[60:63]
	v_mfma_f32_16x16x32_bf16 v[48:51], v[142:145], v[190:193], v[48:51]
	v_mfma_f32_16x16x32_bf16 v[44:47], v[154:157], v[190:193], v[44:47]
	v_mfma_f32_16x16x32_bf16 v[32:35], v[142:145], v[198:201], v[32:35]
	v_mfma_f32_16x16x32_bf16 v[28:31], v[154:157], v[198:201], v[28:31]
	v_mfma_f32_16x16x32_bf16 v[16:19], v[142:145], v[206:209], v[16:19]
	v_mfma_f32_16x16x32_bf16 v[12:15], v[154:157], v[206:209], v[12:15]
	v_mfma_f32_16x16x32_bf16 v[64:67], v[150:153], v[186:189], v[64:67]
	v_mfma_f32_16x16x32_bf16 v[60:63], v[158:161], v[186:189], v[60:63]
	v_mfma_f32_16x16x32_bf16 v[48:51], v[150:153], v[194:197], v[48:51]
	v_mfma_f32_16x16x32_bf16 v[44:47], v[158:161], v[194:197], v[44:47]
	v_mfma_f32_16x16x32_bf16 v[32:35], v[150:153], v[202:205], v[32:35]
	v_mfma_f32_16x16x32_bf16 v[28:31], v[158:161], v[202:205], v[28:31]
	v_mfma_f32_16x16x32_bf16 v[16:19], v[150:153], v[210:213], v[16:19]
	v_mfma_f32_16x16x32_bf16 v[12:15], v[158:161], v[210:213], v[12:15]
	s_setprio 0
	s_setprio 1
	v_mfma_f32_16x16x32_bf16 v[56:59], v[162:165], v[182:185], v[56:59]
	v_mfma_f32_16x16x32_bf16 v[52:55], v[170:173], v[182:185], v[52:55]
	v_mfma_f32_16x16x32_bf16 v[40:43], v[162:165], v[190:193], v[40:43]
	v_mfma_f32_16x16x32_bf16 v[36:39], v[170:173], v[190:193], v[36:39]
	v_mfma_f32_16x16x32_bf16 v[24:27], v[162:165], v[198:201], v[24:27]
	v_mfma_f32_16x16x32_bf16 v[20:23], v[170:173], v[198:201], v[20:23]
	v_mfma_f32_16x16x32_bf16 v[8:11], v[162:165], v[206:209], v[8:11]
	v_mfma_f32_16x16x32_bf16 v[4:7], v[170:173], v[206:209], v[4:7]
	v_mfma_f32_16x16x32_bf16 v[56:59], v[166:169], v[186:189], v[56:59]
	v_mfma_f32_16x16x32_bf16 v[52:55], v[174:177], v[186:189], v[52:55]
	v_mfma_f32_16x16x32_bf16 v[40:43], v[166:169], v[194:197], v[40:43]
	v_mfma_f32_16x16x32_bf16 v[36:39], v[174:177], v[194:197], v[36:39]
	v_mfma_f32_16x16x32_bf16 v[24:27], v[166:169], v[202:205], v[24:27]
	v_mfma_f32_16x16x32_bf16 v[20:23], v[174:177], v[202:205], v[20:23]
	v_mfma_f32_16x16x32_bf16 v[8:11], v[166:169], v[210:213], v[8:11]
	v_mfma_f32_16x16x32_bf16 v[4:7], v[174:177], v[210:213], v[4:7]
	s_barrier
	s_setprio 0
	s_add_i32 s56, s56, 2
	s_add_u32 s34, s34, 0x100
	s_addc_u32 s35, s35, 0
	s_add_u32 s54, s54, 0x100
	s_addc_u32 s55, s55, 0
	s_cmp_gt_u32 s56, 29
	s_cbranch_scc0 .LBB0_2104
.Lpeel_post_p6:
	s_and_b64 vcc, exec, s[12:13]
	s_cbranch_vccz .LBB0_2107
	s_barrier

; #define PG8_STAGE(bufoff, gbase, voff) do { _Pragma("unroll") for (int _i = 0; _i < 2; ++_i) \
;         __builtin_amdgcn_global_load_lds((const unsigned*)((const char*)(gbase) + (voff)[_i]), (PG8_LAS unsigned*)(lds + (bufoff) + ldsw + _i * 8192), 16, 0, 0); } while (0)
; #define PG8_LDA(dst, b, h) do { _Pragma("unroll") for (int m = 0; m < 4; ++m) _Pragma("unroll") for (int k = 0; k < 2; ++k) dst[m][k] = *(const PG8_LAS bf16x8*)(lds + PG8_SA(b, h) + aoff + m * 2048 + k * 1024); } while (0)
; #define PG8_LDB(dst, b, h) do { _Pragma("unroll") for (int n = 0; n < 2; ++n) _Pragma("unroll") for (int k = 0; k < 2; ++k) dst[n][k] = *(const PG8_LAS bf16x8*)(lds + PG8_SB(b, h) + boff + n * 2048 + k * 1024); } while (0)
; #define PG8_WAIT_V(n) asm volatile("s_waitcnt vmcnt(" #n ")" ::: "memory")
; #define PG8_WAIT_L(n) asm volatile("s_waitcnt lgkmcnt(" #n ")" ::: "memory")
; #define PG8_BAR __builtin_amdgcn_s_barrier()
; #define PG8_SCHED __builtin_amdgcn_sched_barrier(0)
; template <class Epi, class Sched, bool ALIGN_EPI = false, bool SP2 = false>
; __device__ __forceinline__ void gemm_phase(PG8_LAS unsigned char* lds, const Gemm g, const Sched& S, const Epi& E) {
;     ...
;         const bool has_next = S.next(ui + 1, nxt);
;         const char* nA = has_next ? (const char*)g.A + (size_t)nxt.pm * tstep : cA; const char* nB = has_next ? (const char*)g.Bt + (size_t)nxt.pn * tstep : cB;
;         for (int t = 0; t < nt; t += 2) {
;             const bool last = (t == nt - 2);
;             const char* a1 = cA + (size_t)(t + 1) * kstep;
;             const char* a2 = last ? nA : cA + (size_t)(t + 2) * kstep; const char* b2 = last ? nB : cB + (size_t)(t + 2) * kstep;
;             const char* a3 = a2 + kstep; const char* b3 = b2 + kstep;
;             if (last && has_next) S.a_ready(nxt);
;             if constexpr (SP2) {
;             PG8_LDB(B0, 0, 0); PG8_LDB(B1, 0, 1); PG8_SCHED; PG8_LDA(At, 0, 0); PG8_STAGE(PG8_SA(1, 1), a1 + hstep, voffA);
;             PG8_WAIT_V(8); PG8_WAIT_L(0); PG8_BAR; PG8_MMA(0, 0, At, B0); PG8_MMA(0, 1, At, B1); PG8_BAR; PG8_SCHED;
;             PG8_LDA(At, 0, 1); PG8_STAGE(PG8_SB(0, 0), b2, voffB); PG8_STAGE(PG8_SB(0, 1), b2 + hstep, voffB); PG8_STAGE(PG8_SA(0, 0), a2, voffA);
;             PG8_WAIT_V(8); PG8_WAIT_L(0); PG8_BAR; PG8_MMA(1, 0, At, B0); PG8_MMA(1, 1, At, B1); PG8_BAR; PG8_SCHED;
.LBB0_2175:
	s_ashr_i32 s37, s36, 31
	s_lshl_b64 s[38:39], s[36:37], 22
	s_add_u32 s38, s2, s38
	s_addc_u32 s39, s3, s39
	s_and_b64 s[42:43], s[4:5], exec
	s_cselect_b32 s30, s39, s7
	s_cselect_b32 s37, s38, s6
	s_ashr_i32 s35, s34, 31
	s_lshl_b64 s[42:43], s[34:35], 22
	s_add_u32 s42, s29, s42
	s_addc_u32 s43, s40, s43
	s_and_b64 s[46:47], s[4:5], exec
	s_cselect_b32 s35, s43, s45
	s_cselect_b32 s64, s42, s44
	s_add_u32 s6, s6, 0x200080
	s_addc_u32 s7, s7, 0
	s_add_u32 s66, s44, 0x100
	s_addc_u32 s70, s45, 0
	s_mov_b32 s74, -2
	s_waitcnt lgkmcnt(0)
	s_add_u32 s26, s6, 0xffe00080
	s_addc_u32 s31, s7, -1
	s_add_i32 s67, 0, 0x10000
	s_cmpk_eq_i32 s74, 0x7c
	s_cselect_b32 s47, s30, s31
	s_cselect_b32 s46, s37, s26
	s_cselect_b32 s45, s35, s70
	s_cselect_b32 s44, s64, s66
	s_add_i32 s26, 0, 0x14000
	v_add_u32_e32 v144, s67, v181
	v_add_u32_e32 v170, s26, v181
	ds_read_b128 v[124:127], v144
	ds_read_b128 v[136:139], v144 offset:1024
	ds_read_b128 v[140:143], v144 offset:2048
	ds_read_b128 v[144:147], v144 offset:3072
	ds_read_b128 v[148:151], v170
	ds_read_b128 v[152:155], v170 offset:1024
	ds_read_b128 v[156:159], v170 offset:2048
	ds_read_b128 v[170:173], v170 offset:3072
	v_lshl_add_u64 v[178:179], s[6:7], 0, v[166:167]
	s_add_i32 m0, s51, 0xc000
	ds_read_b128 v[174:177], v183
	ds_read_b128 v[184:187], v183 offset:1024
	ds_read_b128 v[188:191], v183 offset:2048
	ds_read_b128 v[192:195], v183 offset:3072
	ds_read_b128 v[196:199], v183 offset:4096
	ds_read_b128 v[200:203], v183 offset:5120
	ds_read_b128 v[204:207], v183 offset:6144
	ds_read_b128 v[208:211], v183 offset:7168
	global_load_lds_dwordx4 v[178:179], off
	v_lshl_add_u64 v[178:179], s[6:7], 0, v[168:169]
	s_add_i32 m0, s51, 0xe000
	s_nop 0
	global_load_lds_dwordx4 v[178:179], off
	s_waitcnt vmcnt(8)
	s_waitcnt lgkmcnt(0)
	s_setprio 1
	s_barrier
	v_mfma_f32_16x16x32_bf16 v[132:135], v[124:127], v[174:177], 0
	v_mfma_f32_16x16x32_bf16 v[128:131], v[140:143], v[174:177], 0
	v_mfma_f32_16x16x32_bf16 v[112:115], v[124:127], v[188:191], 0
	v_mfma_f32_16x16x32_bf16 v[108:111], v[140:143], v[188:191], 0
	v_mfma_f32_16x16x32_bf16 v[96:99], v[124:127], v[196:199], 0
	v_mfma_f32_16x16x32_bf16 v[92:95], v[140:143], v[196:199], 0
	v_mfma_f32_16x16x32_bf16 v[80:83], v[124:127], v[204:207], 0
	v_mfma_f32_16x16x32_bf16 v[76:79], v[140:143], v[204:207], 0
	v_mfma_f32_16x16x32_bf16 v[132:135], v[136:139], v[184:187], v[132:135]
	v_mfma_f32_16x16x32_bf16 v[128:131], v[144:147], v[184:187], v[128:131]
	v_mfma_f32_16x16x32_bf16 v[112:115], v[136:139], v[192:195], v[112:115]
	v_mfma_f32_16x16x32_bf16 v[108:111], v[144:147], v[192:195], v[108:111]
	v_mfma_f32_16x16x32_bf16 v[96:99], v[136:139], v[200:203], v[96:99]
	v_mfma_f32_16x16x32_bf16 v[92:95], v[144:147], v[200:203], v[92:95]
	v_mfma_f32_16x16x32_bf16 v[80:83], v[136:139], v[208:211], v[80:83]
	v_mfma_f32_16x16x32_bf16 v[76:79], v[144:147], v[208:211], v[76:79]
	s_setprio 0
	s_setprio 1
	v_mfma_f32_16x16x32_bf16 v[120:123], v[148:151], v[174:177], 0
	v_mfma_f32_16x16x32_bf16 v[116:119], v[156:159], v[174:177], 0
	v_mfma_f32_16x16x32_bf16 v[104:107], v[148:151], v[188:191], 0
	v_mfma_f32_16x16x32_bf16 v[100:103], v[156:159], v[188:191], 0
	v_mfma_f32_16x16x32_bf16 v[88:91], v[148:151], v[196:199], 0
	v_mfma_f32_16x16x32_bf16 v[84:87], v[156:159], v[196:199], 0
	v_mfma_f32_16x16x32_bf16 v[72:75], v[148:151], v[204:207], 0
	v_mfma_f32_16x16x32_bf16 v[68:71], v[156:159], v[204:207], 0
	v_mfma_f32_16x16x32_bf16 v[120:123], v[152:155], v[184:187], v[120:123]
	v_mfma_f32_16x16x32_bf16 v[116:119], v[170:173], v[184:187], v[116:119]
	v_mfma_f32_16x16x32_bf16 v[104:107], v[152:155], v[192:195], v[104:107]
	v_mfma_f32_16x16x32_bf16 v[100:103], v[170:173], v[192:195], v[100:103]
	v_mfma_f32_16x16x32_bf16 v[88:91], v[152:155], v[200:203], v[88:91]
	v_mfma_f32_16x16x32_bf16 v[84:87], v[170:173], v[200:203], v[84:87]
	v_mfma_f32_16x16x32_bf16 v[72:75], v[152:155], v[208:211], v[72:75]
	v_mfma_f32_16x16x32_bf16 v[68:71], v[170:173], v[208:211], v[68:71]
	s_barrier
	s_setprio 0
	s_add_i32 s31, s67, s50
	v_lshl_add_u64 v[178:179], s[44:45], 0, v[2:3]
	s_mov_b32 m0, s31
	ds_read_b128 v[174:177], v183 offset:16384
	ds_read_b128 v[184:187], v183 offset:17408
	ds_read_b128 v[188:191], v183 offset:18432
	ds_read_b128 v[192:195], v183 offset:19456
	ds_read_b128 v[196:199], v183 offset:20480
	ds_read_b128 v[200:203], v183 offset:21504
	ds_read_b128 v[204:207], v183 offset:22528
	ds_read_b128 v[208:211], v183 offset:23552
	global_load_lds_dwordx4 v[178:179], off
	s_add_i32 m0, s31, 0x2000
	s_add_u32 s68, s44, 0x200000
	v_lshl_add_u64 v[212:213], s[44:45], 0, v[160:161]
	s_addc_u32 s69, s45, 0
	s_add_i32 s26, s26, s50
	global_load_lds_dwordx4 v[212:213], off
	v_lshl_add_u64 v[214:215], s[68:69], 0, v[2:3]
	s_mov_b32 m0, s26
	v_lshl_add_u64 v[216:217], s[46:47], 0, v[162:163]
	global_load_lds_dwordx4 v[214:215], off
	v_lshl_add_u64 v[214:215], s[68:69], 0, v[160:161]
	s_add_i32 m0, s26, 0x2000
	s_nop 0
	global_load_lds_dwordx4 v[214:215], off
	v_lshl_add_u64 v[214:215], s[46:47], 0, v[164:165]
	s_mov_b32 m0, s51
	s_nop 0
	global_load_lds_dwordx4 v[214:215], off
	s_mov_b32 m0, s52
	s_nop 0
	global_load_lds_dwordx4 v[216:217], off
	s_waitcnt vmcnt(8)
	s_waitcnt lgkmcnt(0)
	s_setprio 1
	s_barrier
; #define PG8_STAGE(bufoff, gbase, voff) do { _Pragma("unroll") for (int _i = 0; _i < 2; ++_i) \
;         __builtin_amdgcn_global_load_lds((const unsigned*)((const char*)(gbase) + (voff)[_i]), (PG8_LAS unsigned*)(lds + (bufoff) + ldsw + _i * 8192), 16, 0, 0); } while (0)
; #define PG8_LDA(dst, b, h) do { _Pragma("unroll") for (int m = 0; m < 4; ++m) _Pragma("unroll") for (int k = 0; k < 2; ++k) dst[m][k] = *(const PG8_LAS bf16x8*)(lds + PG8_SA(b, h) + aoff + m * 2048 + k * 1024); } while (0)
; #define PG8_LDB(dst, b, h) do { _Pragma("unroll") for (int n = 0; n < 2; ++n) _Pragma("unroll") for (int k = 0; k < 2; ++k) dst[n][k] = *(const PG8_LAS bf16x8*)(lds + PG8_SB(b, h) + boff + n * 2048 + k * 1024); } while (0)
; #define PG8_MMA(ai, bj, At, Bt) do { __builtin_amdgcn_s_setprio(1); _Pragma("unroll") for (int m = 0; m < 4; ++m) _Pragma("unroll") for (int n = 0; n < 2; ++n) _Pragma("unroll") for (int k = 0; k < 2; ++k) \
;         acc[ai][bj][m][n] = __builtin_amdgcn_mfma_f32_16x16x32_bf16(Bt[n][k], At[m][k], acc[ai][bj][m][n], 0, 0, 0); __builtin_amdgcn_s_setprio(0); } while (0)
; #define PG8_WAIT_V(n) asm volatile("s_waitcnt vmcnt(" #n ")" ::: "memory")
; #define PG8_WAIT_L(n) asm volatile("s_waitcnt lgkmcnt(" #n ")" ::: "memory")
; #define PG8_BAR __builtin_amdgcn_s_barrier()
; #define PG8_SCHED __builtin_amdgcn_sched_barrier(0)
; template <class Epi, class Sched, bool ALIGN_EPI = false, bool SP2 = false>
; __device__ __forceinline__ void gemm_phase(PG8_LAS unsigned char* lds, const Gemm g, const Sched& S, const Epi& E) {
;     ...
;             PG8_WAIT_V(8); PG8_WAIT_L(0); PG8_BAR; PG8_MMA(1, 0, At, B0); PG8_MMA(1, 1, At, B1); PG8_BAR; PG8_SCHED;
;             PG8_LDB(B0, 1, 0); PG8_LDB(B1, 1, 1); PG8_SCHED; PG8_LDA(At, 1, 0); PG8_STAGE(PG8_SA(0, 1), a2 + hstep, voffA);
;             PG8_WAIT_V(8); PG8_WAIT_L(0); PG8_BAR; PG8_MMA(0, 0, At, B0); PG8_MMA(0, 1, At, B1); PG8_BAR; PG8_SCHED;
	v_mfma_f32_16x16x32_bf16 v[64:67], v[124:127], v[174:177], 0
	v_mfma_f32_16x16x32_bf16 v[60:63], v[140:143], v[174:177], 0
	v_mfma_f32_16x16x32_bf16 v[48:51], v[124:127], v[188:191], 0
	v_mfma_f32_16x16x32_bf16 v[44:47], v[140:143], v[188:191], 0
	v_mfma_f32_16x16x32_bf16 v[32:35], v[124:127], v[196:199], 0
	v_mfma_f32_16x16x32_bf16 v[28:31], v[140:143], v[196:199], 0
	v_mfma_f32_16x16x32_bf16 v[16:19], v[124:127], v[204:207], 0
	v_mfma_f32_16x16x32_bf16 v[12:15], v[140:143], v[204:207], 0
	v_mfma_f32_16x16x32_bf16 v[64:67], v[136:139], v[184:187], v[64:67]
	v_mfma_f32_16x16x32_bf16 v[60:63], v[144:147], v[184:187], v[60:63]
	v_mfma_f32_16x16x32_bf16 v[48:51], v[136:139], v[192:195], v[48:51]
	v_mfma_f32_16x16x32_bf16 v[44:47], v[144:147], v[192:195], v[44:47]
	v_mfma_f32_16x16x32_bf16 v[32:35], v[136:139], v[200:203], v[32:35]
	v_mfma_f32_16x16x32_bf16 v[28:31], v[144:147], v[200:203], v[28:31]
	v_mfma_f32_16x16x32_bf16 v[16:19], v[136:139], v[208:211], v[16:19]
	v_mfma_f32_16x16x32_bf16 v[12:15], v[144:147], v[208:211], v[12:15]
	s_setprio 0
	s_setprio 1
	v_mfma_f32_16x16x32_bf16 v[56:59], v[148:151], v[174:177], 0
	v_mfma_f32_16x16x32_bf16 v[52:55], v[156:159], v[174:177], 0
	v_mfma_f32_16x16x32_bf16 v[40:43], v[148:151], v[188:191], 0
	v_mfma_f32_16x16x32_bf16 v[36:39], v[156:159], v[188:191], 0
	v_mfma_f32_16x16x32_bf16 v[24:27], v[148:151], v[196:199], 0
	v_mfma_f32_16x16x32_bf16 v[20:23], v[156:159], v[196:199], 0
	v_mfma_f32_16x16x32_bf16 v[8:11], v[148:151], v[204:207], 0
	v_mfma_f32_16x16x32_bf16 v[4:7], v[156:159], v[204:207], 0
	v_mfma_f32_16x16x32_bf16 v[56:59], v[152:155], v[184:187], v[56:59]
	v_mfma_f32_16x16x32_bf16 v[52:55], v[170:173], v[184:187], v[52:55]
	v_mfma_f32_16x16x32_bf16 v[40:43], v[152:155], v[192:195], v[40:43]
	v_mfma_f32_16x16x32_bf16 v[36:39], v[170:173], v[192:195], v[36:39]
	v_mfma_f32_16x16x32_bf16 v[24:27], v[152:155], v[200:203], v[24:27]
	v_mfma_f32_16x16x32_bf16 v[20:23], v[170:173], v[200:203], v[20:23]
	v_mfma_f32_16x16x32_bf16 v[8:11], v[152:155], v[208:211], v[8:11]
	v_mfma_f32_16x16x32_bf16 v[4:7], v[170:173], v[208:211], v[4:7]
	s_barrier
	s_setprio 0
	s_add_i32 s26, 0, 0x18000
	s_add_i32 s31, 0, 0x1c000
	v_add_u32_e32 v144, s26, v181
	v_add_u32_e32 v170, s31, v181
	ds_read_b128 v[124:127], v144
	ds_read_b128 v[136:139], v144 offset:1024
	ds_read_b128 v[140:143], v144 offset:2048
	ds_read_b128 v[144:147], v144 offset:3072
	ds_read_b128 v[148:151], v170
	ds_read_b128 v[152:155], v170 offset:1024
	ds_read_b128 v[156:159], v170 offset:2048
	ds_read_b128 v[170:173], v170 offset:3072
	s_add_u32 s46, s46, 0x200000
	s_addc_u32 s47, s47, 0
	s_mov_b32 m0, s53
	v_lshl_add_u64 v[218:219], s[46:47], 0, v[164:165]
	ds_read_b128 v[174:177], v183 offset:32768
	ds_read_b128 v[184:187], v183 offset:33792
	ds_read_b128 v[188:191], v183 offset:34816
	ds_read_b128 v[192:195], v183 offset:35840
	ds_read_b128 v[196:199], v183 offset:36864
	ds_read_b128 v[200:203], v183 offset:37888
	ds_read_b128 v[204:207], v183 offset:38912
	ds_read_b128 v[208:211], v183 offset:39936
	global_load_lds_dwordx4 v[218:219], off
	v_lshl_add_u64 v[218:219], s[46:47], 0, v[162:163]
	s_mov_b32 m0, s54
	s_nop 0
	global_load_lds_dwordx4 v[218:219], off
	s_waitcnt vmcnt(8)
	s_waitcnt lgkmcnt(0)
	s_setprio 1
	s_barrier
	v_mfma_f32_16x16x32_bf16 v[132:135], v[124:127], v[174:177], v[132:135]
	v_mfma_f32_16x16x32_bf16 v[128:131], v[140:143], v[174:177], v[128:131]
	v_mfma_f32_16x16x32_bf16 v[112:115], v[124:127], v[188:191], v[112:115]
	v_mfma_f32_16x16x32_bf16 v[108:111], v[140:143], v[188:191], v[108:111]
	v_mfma_f32_16x16x32_bf16 v[96:99], v[124:127], v[196:199], v[96:99]
	v_mfma_f32_16x16x32_bf16 v[92:95], v[140:143], v[196:199], v[92:95]
	v_mfma_f32_16x16x32_bf16 v[80:83], v[124:127], v[204:207], v[80:83]
	v_mfma_f32_16x16x32_bf16 v[76:79], v[140:143], v[204:207], v[76:79]
	v_mfma_f32_16x16x32_bf16 v[132:135], v[136:139], v[184:187], v[132:135]
	v_mfma_f32_16x16x32_bf16 v[128:131], v[144:147], v[184:187], v[128:131]
	v_mfma_f32_16x16x32_bf16 v[112:115], v[136:139], v[192:195], v[112:115]
	v_mfma_f32_16x16x32_bf16 v[108:111], v[144:147], v[192:195], v[108:111]
	v_mfma_f32_16x16x32_bf16 v[96:99], v[136:139], v[200:203], v[96:99]
	v_mfma_f32_16x16x32_bf16 v[92:95], v[144:147], v[200:203], v[92:95]
	v_mfma_f32_16x16x32_bf16 v[80:83], v[136:139], v[208:211], v[80:83]
	v_mfma_f32_16x16x32_bf16 v[76:79], v[144:147], v[208:211], v[76:79]
	s_setprio 0
	s_setprio 1
	v_mfma_f32_16x16x32_bf16 v[120:123], v[148:151], v[174:177], v[120:123]
	v_mfma_f32_16x16x32_bf16 v[116:119], v[156:159], v[174:177], v[116:119]
	v_mfma_f32_16x16x32_bf16 v[104:107], v[148:151], v[188:191], v[104:107]
	v_mfma_f32_16x16x32_bf16 v[100:103], v[156:159], v[188:191], v[100:103]
	v_mfma_f32_16x16x32_bf16 v[88:91], v[148:151], v[196:199], v[88:91]
	v_mfma_f32_16x16x32_bf16 v[84:87], v[156:159], v[196:199], v[84:87]
	v_mfma_f32_16x16x32_bf16 v[72:75], v[148:151], v[204:207], v[72:75]
	v_mfma_f32_16x16x32_bf16 v[68:71], v[156:159], v[204:207], v[68:71]
	v_mfma_f32_16x16x32_bf16 v[120:123], v[152:155], v[184:187], v[120:123]
	v_mfma_f32_16x16x32_bf16 v[116:119], v[170:173], v[184:187], v[116:119]
	v_mfma_f32_16x16x32_bf16 v[104:107], v[152:155], v[192:195], v[104:107]
	v_mfma_f32_16x16x32_bf16 v[100:103], v[170:173], v[192:195], v[100:103]
	v_mfma_f32_16x16x32_bf16 v[88:91], v[152:155], v[200:203], v[88:91]
	v_mfma_f32_16x16x32_bf16 v[84:87], v[170:173], v[200:203], v[84:87]
	v_mfma_f32_16x16x32_bf16 v[72:75], v[152:155], v[208:211], v[72:75]
	v_mfma_f32_16x16x32_bf16 v[68:71], v[170:173], v[208:211], v[68:71]
	s_barrier
; #define PG8_STAGE(bufoff, gbase, voff) do { _Pragma("unroll") for (int _i = 0; _i < 2; ++_i) \
;         __builtin_amdgcn_global_load_lds((const unsigned*)((const char*)(gbase) + (voff)[_i]), (PG8_LAS unsigned*)(lds + (bufoff) + ldsw + _i * 8192), 16, 0, 0); } while (0)
; #define PG8_LDA(dst, b, h) do { _Pragma("unroll") for (int m = 0; m < 4; ++m) _Pragma("unroll") for (int k = 0; k < 2; ++k) dst[m][k] = *(const PG8_LAS bf16x8*)(lds + PG8_SA(b, h) + aoff + m * 2048 + k * 1024); } while (0)
; #define PG8_LDB(dst, b, h) do { _Pragma("unroll") for (int n = 0; n < 2; ++n) _Pragma("unroll") for (int k = 0; k < 2; ++k) dst[n][k] = *(const PG8_LAS bf16x8*)(lds + PG8_SB(b, h) + boff + n * 2048 + k * 1024); } while (0)
; template <class Epi, class Sched, bool ALIGN_EPI = false, bool SP2 = false>
; __device__ __forceinline__ void gemm_phase(PG8_LAS unsigned char* lds, const Gemm g, const Sched& S, const Epi& E) {
;     ...
;         for (int t = 0; t < nt; t += 2) {
;             const bool last = (t == nt - 2);
;             const char* a1 = cA + (size_t)(t + 1) * kstep;
;             const char* a2 = last ? nA : cA + (size_t)(t + 2) * kstep; const char* b2 = last ? nB : cB + (size_t)(t + 2) * kstep;
;             const char* a3 = a2 + kstep; const char* b3 = b2 + kstep;
;             if (last && has_next) S.a_ready(nxt);
;             if constexpr (SP2) {
;             PG8_LDB(B0, 0, 0); PG8_LDB(B1, 0, 1); PG8_SCHED; PG8_LDA(At, 0, 0); PG8_STAGE(PG8_SA(1, 1), a1 + hstep, voffA);
;             PG8_WAIT_V(8); PG8_WAIT_L(0); PG8_BAR; PG8_MMA(0, 0, At, B0); PG8_MMA(0, 1, At, B1); PG8_BAR; PG8_SCHED;
;             PG8_LDA(At, 0, 1); PG8_STAGE(PG8_SB(0, 0), b2, voffB); PG8_STAGE(PG8_SB(0, 1), b2 + hstep, voffB); PG8_STAGE(PG8_SA(0, 0), a2, voffA);
;             PG8_WAIT_V(8); PG8_WAIT_L(0); PG8_BAR; PG8_MMA(1, 0, At, B0); PG8_MMA(1, 1, At, B1); PG8_BAR; PG8_SCHED;
;             PG8_LDB(B0, 1, 0); PG8_LDB(B1, 1, 1); PG8_SCHED; PG8_LDA(At, 1, 0); PG8_STAGE(PG8_SA(0, 1), a2 + hstep, voffA);
;             PG8_WAIT_V(8); PG8_WAIT_L(0); PG8_BAR; PG8_MMA(0, 0, At, B0); PG8_MMA(0, 1, At, B1); PG8_BAR; PG8_SCHED;
;             PG8_LDA(At, 1, 1); PG8_STAGE(PG8_SB(1, 0), b3, voffB); PG8_STAGE(PG8_SB(1, 1), b3 + hstep, voffB); PG8_STAGE(PG8_SA(1, 0), a3, voffA);
;             PG8_WAIT_V(8); PG8_WAIT_L(0); PG8_BAR; PG8_MMA(1, 0, At, B0); PG8_MMA(1, 1, At, B1); PG8_BAR; PG8_SCHED;
	s_setprio 0
	s_add_i32 s26, s26, s50
	v_lshl_add_u64 v[178:179], v[178:179], 0, s[60:61]
	s_mov_b32 m0, s26
	ds_read_b128 v[174:177], v183 offset:49152
	ds_read_b128 v[184:187], v183 offset:50176
	ds_read_b128 v[188:191], v183 offset:51200
	ds_read_b128 v[192:195], v183 offset:52224
	ds_read_b128 v[196:199], v183 offset:53248
	ds_read_b128 v[200:203], v183 offset:54272
	ds_read_b128 v[204:207], v183 offset:55296
	ds_read_b128 v[208:211], v183 offset:56320
	global_load_lds_dwordx4 v[178:179], off
	s_add_i32 m0, s26, 0x2000
	s_add_u32 s44, s44, 0x200080
	v_lshl_add_u64 v[178:179], v[212:213], 0, s[60:61]
	s_addc_u32 s45, s45, 0
	s_add_i32 s26, s31, s50
	global_load_lds_dwordx4 v[178:179], off
	v_lshl_add_u64 v[178:179], s[44:45], 0, v[2:3]
	s_mov_b32 m0, s26
	s_nop 0
	global_load_lds_dwordx4 v[178:179], off
	v_lshl_add_u64 v[178:179], s[44:45], 0, v[160:161]
	s_add_i32 m0, s26, 0x2000
	s_nop 0
	global_load_lds_dwordx4 v[178:179], off
	v_lshl_add_u64 v[178:179], v[214:215], 0, s[60:61]
	s_mov_b32 m0, s56
	s_nop 0
	global_load_lds_dwordx4 v[178:179], off
	v_lshl_add_u64 v[178:179], v[216:217], 0, s[60:61]
	s_mov_b32 m0, s57
	s_nop 0
	global_load_lds_dwordx4 v[178:179], off
	s_waitcnt vmcnt(8)
	s_waitcnt lgkmcnt(0)
	s_setprio 1
	s_barrier
	v_mfma_f32_16x16x32_bf16 v[64:67], v[124:127], v[174:177], v[64:67]
	v_mfma_f32_16x16x32_bf16 v[60:63], v[140:143], v[174:177], v[60:63]
	v_mfma_f32_16x16x32_bf16 v[48:51], v[124:127], v[188:191], v[48:51]
	v_mfma_f32_16x16x32_bf16 v[44:47], v[140:143], v[188:191], v[44:47]
	v_mfma_f32_16x16x32_bf16 v[32:35], v[124:127], v[196:199], v[32:35]
	v_mfma_f32_16x16x32_bf16 v[28:31], v[140:143], v[196:199], v[28:31]
	v_mfma_f32_16x16x32_bf16 v[16:19], v[124:127], v[204:207], v[16:19]
	v_mfma_f32_16x16x32_bf16 v[12:15], v[140:143], v[204:207], v[12:15]
	v_mfma_f32_16x16x32_bf16 v[64:67], v[136:139], v[184:187], v[64:67]
	v_mfma_f32_16x16x32_bf16 v[60:63], v[144:147], v[184:187], v[60:63]
	v_mfma_f32_16x16x32_bf16 v[48:51], v[136:139], v[192:195], v[48:51]
	v_mfma_f32_16x16x32_bf16 v[44:47], v[144:147], v[192:195], v[44:47]
	v_mfma_f32_16x16x32_bf16 v[32:35], v[136:139], v[200:203], v[32:35]
	v_mfma_f32_16x16x32_bf16 v[28:31], v[144:147], v[200:203], v[28:31]
	v_mfma_f32_16x16x32_bf16 v[16:19], v[136:139], v[208:211], v[16:19]
	v_mfma_f32_16x16x32_bf16 v[12:15], v[144:147], v[208:211], v[12:15]
	s_setprio 0
	s_setprio 1
	v_mfma_f32_16x16x32_bf16 v[56:59], v[148:151], v[174:177], v[56:59]
	v_mfma_f32_16x16x32_bf16 v[52:55], v[156:159], v[174:177], v[52:55]
	v_mfma_f32_16x16x32_bf16 v[40:43], v[148:151], v[188:191], v[40:43]
	v_mfma_f32_16x16x32_bf16 v[36:39], v[156:159], v[188:191], v[36:39]
	v_mfma_f32_16x16x32_bf16 v[24:27], v[148:151], v[196:199], v[24:27]
	v_mfma_f32_16x16x32_bf16 v[20:23], v[156:159], v[196:199], v[20:23]
	v_mfma_f32_16x16x32_bf16 v[8:11], v[148:151], v[204:207], v[8:11]
	v_mfma_f32_16x16x32_bf16 v[4:7], v[156:159], v[204:207], v[4:7]
	v_mfma_f32_16x16x32_bf16 v[56:59], v[152:155], v[184:187], v[56:59]
	v_mfma_f32_16x16x32_bf16 v[52:55], v[170:173], v[184:187], v[52:55]
	v_mfma_f32_16x16x32_bf16 v[40:43], v[152:155], v[192:195], v[40:43]
	v_mfma_f32_16x16x32_bf16 v[36:39], v[170:173], v[192:195], v[36:39]
	v_mfma_f32_16x16x32_bf16 v[24:27], v[152:155], v[200:203], v[24:27]
	v_mfma_f32_16x16x32_bf16 v[20:23], v[170:173], v[200:203], v[20:23]
	v_mfma_f32_16x16x32_bf16 v[8:11], v[152:155], v[208:211], v[8:11]
	v_mfma_f32_16x16x32_bf16 v[4:7], v[170:173], v[208:211], v[4:7]
	s_barrier
	s_setprio 0
	s_add_i32 s74, s74, 2
	s_add_u32 s6, s6, 0x100
	s_addc_u32 s7, s7, 0
	s_add_u32 s66, s66, 0x100
	s_addc_u32 s70, s70, 0
	s_cmpk_gt_u32 s74, 0x7d
	s_cbranch_scc0 .LBB0_2176
	s_branch .Lpeel_post_p7
.LBB0_2176:
	s_add_u32 s26, s6, 0xffe00080
	s_addc_u32 s31, s7, -1
	s_add_i32 s67, 0, 0x10000
	s_cmpk_eq_i32 s74, 0x7c
	s_cselect_b32 s47, s30, s31
	s_cselect_b32 s46, s37, s26
	s_cselect_b32 s45, s35, s70
	s_cselect_b32 s44, s64, s66
	s_add_i32 s26, 0, 0x14000
	v_add_u32_e32 v144, s67, v181
	v_add_u32_e32 v170, s26, v181
	ds_read_b128 v[124:127], v144
	ds_read_b128 v[136:139], v144 offset:1024
	ds_read_b128 v[140:143], v144 offset:2048
	ds_read_b128 v[144:147], v144 offset:3072
	ds_read_b128 v[148:151], v170
	ds_read_b128 v[152:155], v170 offset:1024
	ds_read_b128 v[156:159], v170 offset:2048
	ds_read_b128 v[170:173], v170 offset:3072
	v_lshl_add_u64 v[178:179], s[6:7], 0, v[166:167]
	s_add_i32 m0, s51, 0xc000
	ds_read_b128 v[174:177], v183
	ds_read_b128 v[184:187], v183 offset:1024
	ds_read_b128 v[188:191], v183 offset:2048
	ds_read_b128 v[192:195], v183 offset:3072
	ds_read_b128 v[196:199], v183 offset:4096
	ds_read_b128 v[200:203], v183 offset:5120
	ds_read_b128 v[204:207], v183 offset:6144
	ds_read_b128 v[208:211], v183 offset:7168
	global_load_lds_dwordx4 v[178:179], off
	v_lshl_add_u64 v[178:179], s[6:7], 0, v[168:169]
	s_add_i32 m0, s51, 0xe000
	s_nop 0
	global_load_lds_dwordx4 v[178:179], off
	s_waitcnt vmcnt(8)
	s_waitcnt lgkmcnt(0)
	s_setprio 1
	s_barrier
; #define PG8_STAGE(bufoff, gbase, voff) do { _Pragma("unroll") for (int _i = 0; _i < 2; ++_i) \
;         __builtin_amdgcn_global_load_lds((const unsigned*)((const char*)(gbase) + (voff)[_i]), (PG8_LAS unsigned*)(lds + (bufoff) + ldsw + _i * 8192), 16, 0, 0); } while (0)
; #define PG8_LDA(dst, b, h) do { _Pragma("unroll") for (int m = 0; m < 4; ++m) _Pragma("unroll") for (int k = 0; k < 2; ++k) dst[m][k] = *(const PG8_LAS bf16x8*)(lds + PG8_SA(b, h) + aoff + m * 2048 + k * 1024); } while (0)
; #define PG8_LDB(dst, b, h) do { _Pragma("unroll") for (int n = 0; n < 2; ++n) _Pragma("unroll") for (int k = 0; k < 2; ++k) dst[n][k] = *(const PG8_LAS bf16x8*)(lds + PG8_SB(b, h) + boff + n * 2048 + k * 1024); } while (0)
; #define PG8_MMA(ai, bj, At, Bt) do { __builtin_amdgcn_s_setprio(1); _Pragma("unroll") for (int m = 0; m < 4; ++m) _Pragma("unroll") for (int n = 0; n < 2; ++n) _Pragma("unroll") for (int k = 0; k < 2; ++k) \
;         acc[ai][bj][m][n] = __builtin_amdgcn_mfma_f32_16x16x32_bf16(Bt[n][k], At[m][k], acc[ai][bj][m][n], 0, 0, 0); __builtin_amdgcn_s_setprio(0); } while (0)
; #define PG8_WAIT_V(n) asm volatile("s_waitcnt vmcnt(" #n ")" ::: "memory")
; #define PG8_WAIT_L(n) asm volatile("s_waitcnt lgkmcnt(" #n ")" ::: "memory")
; #define PG8_BAR __builtin_amdgcn_s_barrier()
; #define PG8_SCHED __builtin_amdgcn_sched_barrier(0)
; template <class Epi, class Sched, bool ALIGN_EPI = false, bool SP2 = false>
; __device__ __forceinline__ void gemm_phase(PG8_LAS unsigned char* lds, const Gemm g, const Sched& S, const Epi& E) {
;     ...
;             PG8_LDB(B0, 0, 0); PG8_LDB(B1, 0, 1); PG8_SCHED; PG8_LDA(At, 0, 0); PG8_STAGE(PG8_SA(1, 1), a1 + hstep, voffA);
;             PG8_WAIT_V(8); PG8_WAIT_L(0); PG8_BAR; PG8_MMA(0, 0, At, B0); PG8_MMA(0, 1, At, B1); PG8_BAR; PG8_SCHED;
;             PG8_LDA(At, 0, 1); PG8_STAGE(PG8_SB(0, 0), b2, voffB); PG8_STAGE(PG8_SB(0, 1), b2 + hstep, voffB); PG8_STAGE(PG8_SA(0, 0), a2, voffA);
;             PG8_WAIT_V(8); PG8_WAIT_L(0); PG8_BAR; PG8_MMA(1, 0, At, B0); PG8_MMA(1, 1, At, B1); PG8_BAR; PG8_SCHED;
	v_mfma_f32_16x16x32_bf16 v[132:135], v[124:127], v[174:177], v[132:135]
	v_mfma_f32_16x16x32_bf16 v[128:131], v[140:143], v[174:177], v[128:131]
	v_mfma_f32_16x16x32_bf16 v[112:115], v[124:127], v[188:191], v[112:115]
	v_mfma_f32_16x16x32_bf16 v[108:111], v[140:143], v[188:191], v[108:111]
	v_mfma_f32_16x16x32_bf16 v[96:99], v[124:127], v[196:199], v[96:99]
	v_mfma_f32_16x16x32_bf16 v[92:95], v[140:143], v[196:199], v[92:95]
	v_mfma_f32_16x16x32_bf16 v[80:83], v[124:127], v[204:207], v[80:83]
	v_mfma_f32_16x16x32_bf16 v[76:79], v[140:143], v[204:207], v[76:79]
	v_mfma_f32_16x16x32_bf16 v[132:135], v[136:139], v[184:187], v[132:135]
	v_mfma_f32_16x16x32_bf16 v[128:131], v[144:147], v[184:187], v[128:131]
	v_mfma_f32_16x16x32_bf16 v[112:115], v[136:139], v[192:195], v[112:115]
	v_mfma_f32_16x16x32_bf16 v[108:111], v[144:147], v[192:195], v[108:111]
	v_mfma_f32_16x16x32_bf16 v[96:99], v[136:139], v[200:203], v[96:99]
	v_mfma_f32_16x16x32_bf16 v[92:95], v[144:147], v[200:203], v[92:95]
	v_mfma_f32_16x16x32_bf16 v[80:83], v[136:139], v[208:211], v[80:83]
	v_mfma_f32_16x16x32_bf16 v[76:79], v[144:147], v[208:211], v[76:79]
	s_setprio 0
	s_setprio 1
	v_mfma_f32_16x16x32_bf16 v[120:123], v[148:151], v[174:177], v[120:123]
	v_mfma_f32_16x16x32_bf16 v[116:119], v[156:159], v[174:177], v[116:119]
	v_mfma_f32_16x16x32_bf16 v[104:107], v[148:151], v[188:191], v[104:107]
	v_mfma_f32_16x16x32_bf16 v[100:103], v[156:159], v[188:191], v[100:103]
	v_mfma_f32_16x16x32_bf16 v[88:91], v[148:151], v[196:199], v[88:91]
	v_mfma_f32_16x16x32_bf16 v[84:87], v[156:159], v[196:199], v[84:87]
	v_mfma_f32_16x16x32_bf16 v[72:75], v[148:151], v[204:207], v[72:75]
	v_mfma_f32_16x16x32_bf16 v[68:71], v[156:159], v[204:207], v[68:71]
	v_mfma_f32_16x16x32_bf16 v[120:123], v[152:155], v[184:187], v[120:123]
	v_mfma_f32_16x16x32_bf16 v[116:119], v[170:173], v[184:187], v[116:119]
	v_mfma_f32_16x16x32_bf16 v[104:107], v[152:155], v[192:195], v[104:107]
	v_mfma_f32_16x16x32_bf16 v[100:103], v[170:173], v[192:195], v[100:103]
	v_mfma_f32_16x16x32_bf16 v[88:91], v[152:155], v[200:203], v[88:91]
	v_mfma_f32_16x16x32_bf16 v[84:87], v[170:173], v[200:203], v[84:87]
	v_mfma_f32_16x16x32_bf16 v[72:75], v[152:155], v[208:211], v[72:75]
	v_mfma_f32_16x16x32_bf16 v[68:71], v[170:173], v[208:211], v[68:71]
	s_barrier
	s_setprio 0
	s_add_i32 s31, s67, s50
	v_lshl_add_u64 v[178:179], s[44:45], 0, v[2:3]
	s_mov_b32 m0, s31
	ds_read_b128 v[174:177], v183 offset:16384
	ds_read_b128 v[184:187], v183 offset:17408
	ds_read_b128 v[188:191], v183 offset:18432
	ds_read_b128 v[192:195], v183 offset:19456
	ds_read_b128 v[196:199], v183 offset:20480
	ds_read_b128 v[200:203], v183 offset:21504
	ds_read_b128 v[204:207], v183 offset:22528
	ds_read_b128 v[208:211], v183 offset:23552
	global_load_lds_dwordx4 v[178:179], off
	s_add_i32 m0, s31, 0x2000
	s_add_u32 s68, s44, 0x200000
	v_lshl_add_u64 v[212:213], s[44:45], 0, v[160:161]
	s_addc_u32 s69, s45, 0
	s_add_i32 s26, s26, s50
	global_load_lds_dwordx4 v[212:213], off
	v_lshl_add_u64 v[214:215], s[68:69], 0, v[2:3]
	s_mov_b32 m0, s26
	v_lshl_add_u64 v[216:217], s[46:47], 0, v[162:163]
	global_load_lds_dwordx4 v[214:215], off
	v_lshl_add_u64 v[214:215], s[68:69], 0, v[160:161]
	s_add_i32 m0, s26, 0x2000
	s_nop 0
	global_load_lds_dwordx4 v[214:215], off
	v_lshl_add_u64 v[214:215], s[46:47], 0, v[164:165]
	s_mov_b32 m0, s51
	s_nop 0
	global_load_lds_dwordx4 v[214:215], off
	s_mov_b32 m0, s52
	s_nop 0
	global_load_lds_dwordx4 v[216:217], off
	s_waitcnt vmcnt(8)
	s_waitcnt lgkmcnt(0)
	s_setprio 1
	s_barrier
	v_mfma_f32_16x16x32_bf16 v[64:67], v[124:127], v[174:177], v[64:67]
	v_mfma_f32_16x16x32_bf16 v[60:63], v[140:143], v[174:177], v[60:63]
	v_mfma_f32_16x16x32_bf16 v[48:51], v[124:127], v[188:191], v[48:51]
	v_mfma_f32_16x16x32_bf16 v[44:47], v[140:143], v[188:191], v[44:47]
	v_mfma_f32_16x16x32_bf16 v[32:35], v[124:127], v[196:199], v[32:35]
	v_mfma_f32_16x16x32_bf16 v[28:31], v[140:143], v[196:199], v[28:31]
	v_mfma_f32_16x16x32_bf16 v[16:19], v[124:127], v[204:207], v[16:19]
	v_mfma_f32_16x16x32_bf16 v[12:15], v[140:143], v[204:207], v[12:15]
	v_mfma_f32_16x16x32_bf16 v[64:67], v[136:139], v[184:187], v[64:67]
	v_mfma_f32_16x16x32_bf16 v[60:63], v[144:147], v[184:187], v[60:63]
	v_mfma_f32_16x16x32_bf16 v[48:51], v[136:139], v[192:195], v[48:51]
	v_mfma_f32_16x16x32_bf16 v[44:47], v[144:147], v[192:195], v[44:47]
	v_mfma_f32_16x16x32_bf16 v[32:35], v[136:139], v[200:203], v[32:35]
	v_mfma_f32_16x16x32_bf16 v[28:31], v[144:147], v[200:203], v[28:31]
	v_mfma_f32_16x16x32_bf16 v[16:19], v[136:139], v[208:211], v[16:19]
	v_mfma_f32_16x16x32_bf16 v[12:15], v[144:147], v[208:211], v[12:15]
	s_setprio 0
	s_setprio 1
	v_mfma_f32_16x16x32_bf16 v[56:59], v[148:151], v[174:177], v[56:59]
	v_mfma_f32_16x16x32_bf16 v[52:55], v[156:159], v[174:177], v[52:55]
	v_mfma_f32_16x16x32_bf16 v[40:43], v[148:151], v[188:191], v[40:43]
	v_mfma_f32_16x16x32_bf16 v[36:39], v[156:159], v[188:191], v[36:39]
	v_mfma_f32_16x16x32_bf16 v[24:27], v[148:151], v[196:199], v[24:27]
	v_mfma_f32_16x16x32_bf16 v[20:23], v[156:159], v[196:199], v[20:23]
	v_mfma_f32_16x16x32_bf16 v[8:11], v[148:151], v[204:207], v[8:11]
	v_mfma_f32_16x16x32_bf16 v[4:7], v[156:159], v[204:207], v[4:7]
	v_mfma_f32_16x16x32_bf16 v[56:59], v[152:155], v[184:187], v[56:59]
	v_mfma_f32_16x16x32_bf16 v[52:55], v[170:173], v[184:187], v[52:55]
	v_mfma_f32_16x16x32_bf16 v[40:43], v[152:155], v[192:195], v[40:43]
	v_mfma_f32_16x16x32_bf16 v[36:39], v[170:173], v[192:195], v[36:39]
	v_mfma_f32_16x16x32_bf16 v[24:27], v[152:155], v[200:203], v[24:27]
	v_mfma_f32_16x16x32_bf16 v[20:23], v[170:173], v[200:203], v[20:23]
	v_mfma_f32_16x16x32_bf16 v[8:11], v[152:155], v[208:211], v[8:11]
	v_mfma_f32_16x16x32_bf16 v[4:7], v[170:173], v[208:211], v[4:7]
	s_barrier
; #define PG8_STAGE(bufoff, gbase, voff) do { _Pragma("unroll") for (int _i = 0; _i < 2; ++_i) \
;         __builtin_amdgcn_global_load_lds((const unsigned*)((const char*)(gbase) + (voff)[_i]), (PG8_LAS unsigned*)(lds + (bufoff) + ldsw + _i * 8192), 16, 0, 0); } while (0)
; #define PG8_LDA(dst, b, h) do { _Pragma("unroll") for (int m = 0; m < 4; ++m) _Pragma("unroll") for (int k = 0; k < 2; ++k) dst[m][k] = *(const PG8_LAS bf16x8*)(lds + PG8_SA(b, h) + aoff + m * 2048 + k * 1024); } while (0)
; #define PG8_LDB(dst, b, h) do { _Pragma("unroll") for (int n = 0; n < 2; ++n) _Pragma("unroll") for (int k = 0; k < 2; ++k) dst[n][k] = *(const PG8_LAS bf16x8*)(lds + PG8_SB(b, h) + boff + n * 2048 + k * 1024); } while (0)
; #define PG8_MMA(ai, bj, At, Bt) do { __builtin_amdgcn_s_setprio(1); _Pragma("unroll") for (int m = 0; m < 4; ++m) _Pragma("unroll") for (int n = 0; n < 2; ++n) _Pragma("unroll") for (int k = 0; k < 2; ++k) \
;         acc[ai][bj][m][n] = __builtin_amdgcn_mfma_f32_16x16x32_bf16(Bt[n][k], At[m][k], acc[ai][bj][m][n], 0, 0, 0); __builtin_amdgcn_s_setprio(0); } while (0)
; #define PG8_WAIT_V(n) asm volatile("s_waitcnt vmcnt(" #n ")" ::: "memory")
; #define PG8_WAIT_L(n) asm volatile("s_waitcnt lgkmcnt(" #n ")" ::: "memory")
; #define PG8_BAR __builtin_amdgcn_s_barrier()
; #define PG8_SCHED __builtin_amdgcn_sched_barrier(0)
; template <class Epi, class Sched, bool ALIGN_EPI = false, bool SP2 = false>
; __device__ __forceinline__ void gemm_phase(PG8_LAS unsigned char* lds, const Gemm g, const Sched& S, const Epi& E) {
;     ...
;             PG8_LDB(B0, 1, 0); PG8_LDB(B1, 1, 1); PG8_SCHED; PG8_LDA(At, 1, 0); PG8_STAGE(PG8_SA(0, 1), a2 + hstep, voffA);
;             PG8_WAIT_V(8); PG8_WAIT_L(0); PG8_BAR; PG8_MMA(0, 0, At, B0); PG8_MMA(0, 1, At, B1); PG8_BAR; PG8_SCHED;
	s_setprio 0
	s_add_i32 s26, 0, 0x18000
	s_add_i32 s31, 0, 0x1c000
	v_add_u32_e32 v144, s26, v181
	v_add_u32_e32 v170, s31, v181
	ds_read_b128 v[124:127], v144
	ds_read_b128 v[136:139], v144 offset:1024
	ds_read_b128 v[140:143], v144 offset:2048
	ds_read_b128 v[144:147], v144 offset:3072
	ds_read_b128 v[148:151], v170
	ds_read_b128 v[152:155], v170 offset:1024
	ds_read_b128 v[156:159], v170 offset:2048
	ds_read_b128 v[170:173], v170 offset:3072
	s_add_u32 s46, s46, 0x200000
	s_addc_u32 s47, s47, 0
	s_mov_b32 m0, s53
	v_lshl_add_u64 v[218:219], s[46:47], 0, v[164:165]
	ds_read_b128 v[174:177], v183 offset:32768
	ds_read_b128 v[184:187], v183 offset:33792
	ds_read_b128 v[188:191], v183 offset:34816
	ds_read_b128 v[192:195], v183 offset:35840
	ds_read_b128 v[196:199], v183 offset:36864
	ds_read_b128 v[200:203], v183 offset:37888
	ds_read_b128 v[204:207], v183 offset:38912
	ds_read_b128 v[208:211], v183 offset:39936
	global_load_lds_dwordx4 v[218:219], off
	v_lshl_add_u64 v[218:219], s[46:47], 0, v[162:163]
	s_mov_b32 m0, s54
	s_nop 0
	global_load_lds_dwordx4 v[218:219], off
	s_waitcnt vmcnt(8)
	s_waitcnt lgkmcnt(0)
	s_setprio 1
	s_barrier
	v_mfma_f32_16x16x32_bf16 v[132:135], v[124:127], v[174:177], v[132:135]
	v_mfma_f32_16x16x32_bf16 v[128:131], v[140:143], v[174:177], v[128:131]
	v_mfma_f32_16x16x32_bf16 v[112:115], v[124:127], v[188:191], v[112:115]
	v_mfma_f32_16x16x32_bf16 v[108:111], v[140:143], v[188:191], v[108:111]
	v_mfma_f32_16x16x32_bf16 v[96:99], v[124:127], v[196:199], v[96:99]
	v_mfma_f32_16x16x32_bf16 v[92:95], v[140:143], v[196:199], v[92:95]
	v_mfma_f32_16x16x32_bf16 v[80:83], v[124:127], v[204:207], v[80:83]
	v_mfma_f32_16x16x32_bf16 v[76:79], v[140:143], v[204:207], v[76:79]
	v_mfma_f32_16x16x32_bf16 v[132:135], v[136:139], v[184:187], v[132:135]
	v_mfma_f32_16x16x32_bf16 v[128:131], v[144:147], v[184:187], v[128:131]
	v_mfma_f32_16x16x32_bf16 v[112:115], v[136:139], v[192:195], v[112:115]
	v_mfma_f32_16x16x32_bf16 v[108:111], v[144:147], v[192:195], v[108:111]
	v_mfma_f32_16x16x32_bf16 v[96:99], v[136:139], v[200:203], v[96:99]
	v_mfma_f32_16x16x32_bf16 v[92:95], v[144:147], v[200:203], v[92:95]
	v_mfma_f32_16x16x32_bf16 v[80:83], v[136:139], v[208:211], v[80:83]
	v_mfma_f32_16x16x32_bf16 v[76:79], v[144:147], v[208:211], v[76:79]
	s_setprio 0
	s_setprio 1
	v_mfma_f32_16x16x32_bf16 v[120:123], v[148:151], v[174:177], v[120:123]
	v_mfma_f32_16x16x32_bf16 v[116:119], v[156:159], v[174:177], v[116:119]
	v_mfma_f32_16x16x32_bf16 v[104:107], v[148:151], v[188:191], v[104:107]
	v_mfma_f32_16x16x32_bf16 v[100:103], v[156:159], v[188:191], v[100:103]
	v_mfma_f32_16x16x32_bf16 v[88:91], v[148:151], v[196:199], v[88:91]
	v_mfma_f32_16x16x32_bf16 v[84:87], v[156:159], v[196:199], v[84:87]
	v_mfma_f32_16x16x32_bf16 v[72:75], v[148:151], v[204:207], v[72:75]
	v_mfma_f32_16x16x32_bf16 v[68:71], v[156:159], v[204:207], v[68:71]
	v_mfma_f32_16x16x32_bf16 v[120:123], v[152:155], v[184:187], v[120:123]
	v_mfma_f32_16x16x32_bf16 v[116:119], v[170:173], v[184:187], v[116:119]
	v_mfma_f32_16x16x32_bf16 v[104:107], v[152:155], v[192:195], v[104:107]
	v_mfma_f32_16x16x32_bf16 v[100:103], v[170:173], v[192:195], v[100:103]
	v_mfma_f32_16x16x32_bf16 v[88:91], v[152:155], v[200:203], v[88:91]
	v_mfma_f32_16x16x32_bf16 v[84:87], v[170:173], v[200:203], v[84:87]
	v_mfma_f32_16x16x32_bf16 v[72:75], v[152:155], v[208:211], v[72:75]
	v_mfma_f32_16x16x32_bf16 v[68:71], v[170:173], v[208:211], v[68:71]
	s_barrier
; #define PG8_STAGE(bufoff, gbase, voff) do { _Pragma("unroll") for (int _i = 0; _i < 2; ++_i) \
;         __builtin_amdgcn_global_load_lds((const unsigned*)((const char*)(gbase) + (voff)[_i]), (PG8_LAS unsigned*)(lds + (bufoff) + ldsw + _i * 8192), 16, 0, 0); } while (0)
; #define PG8_LDA(dst, b, h) do { _Pragma("unroll") for (int m = 0; m < 4; ++m) _Pragma("unroll") for (int k = 0; k < 2; ++k) dst[m][k] = *(const PG8_LAS bf16x8*)(lds + PG8_SA(b, h) + aoff + m * 2048 + k * 1024); } while (0)
; #define PG8_MMA(ai, bj, At, Bt) do { __builtin_amdgcn_s_setprio(1); _Pragma("unroll") for (int m = 0; m < 4; ++m) _Pragma("unroll") for (int n = 0; n < 2; ++n) _Pragma("unroll") for (int k = 0; k < 2; ++k) \
;         acc[ai][bj][m][n] = __builtin_amdgcn_mfma_f32_16x16x32_bf16(Bt[n][k], At[m][k], acc[ai][bj][m][n], 0, 0, 0); __builtin_amdgcn_s_setprio(0); } while (0)
; #define PG8_WAIT_V(n) asm volatile("s_waitcnt vmcnt(" #n ")" ::: "memory")
; #define PG8_WAIT_L(n) asm volatile("s_waitcnt lgkmcnt(" #n ")" ::: "memory")
; #define PG8_BAR __builtin_amdgcn_s_barrier()
; #define PG8_SCHED __builtin_amdgcn_sched_barrier(0)
; template <class Epi, class Sched, bool ALIGN_EPI = false, bool SP2 = false>
; __device__ __forceinline__ void gemm_phase(PG8_LAS unsigned char* lds, const Gemm g, const Sched& S, const Epi& E) {
;     ...
;             PG8_LDA(At, 1, 1); PG8_STAGE(PG8_SB(1, 0), b3, voffB); PG8_STAGE(PG8_SB(1, 1), b3 + hstep, voffB); PG8_STAGE(PG8_SA(1, 0), a3, voffA);
;             PG8_WAIT_V(8); PG8_WAIT_L(0); PG8_BAR; PG8_MMA(1, 0, At, B0); PG8_MMA(1, 1, At, B1); PG8_BAR; PG8_SCHED;
;     ...
;         if constexpr (ALIGN_EPI) { if (wr == 0) PG8_BAR; }
	s_setprio 0
	s_add_i32 s26, s26, s50
	v_lshl_add_u64 v[178:179], v[178:179], 0, s[60:61]
	s_mov_b32 m0, s26
	ds_read_b128 v[174:177], v183 offset:49152
	ds_read_b128 v[184:187], v183 offset:50176
	ds_read_b128 v[188:191], v183 offset:51200
	ds_read_b128 v[192:195], v183 offset:52224
	ds_read_b128 v[196:199], v183 offset:53248
	ds_read_b128 v[200:203], v183 offset:54272
	ds_read_b128 v[204:207], v183 offset:55296
	ds_read_b128 v[208:211], v183 offset:56320
	global_load_lds_dwordx4 v[178:179], off
	s_add_i32 m0, s26, 0x2000
	s_add_u32 s44, s44, 0x200080
	v_lshl_add_u64 v[178:179], v[212:213], 0, s[60:61]
	s_addc_u32 s45, s45, 0
	s_add_i32 s26, s31, s50
	global_load_lds_dwordx4 v[178:179], off
	v_lshl_add_u64 v[178:179], s[44:45], 0, v[2:3]
	s_mov_b32 m0, s26
	s_nop 0
	global_load_lds_dwordx4 v[178:179], off
	v_lshl_add_u64 v[178:179], s[44:45], 0, v[160:161]
	s_add_i32 m0, s26, 0x2000
	s_nop 0
	global_load_lds_dwordx4 v[178:179], off
	v_lshl_add_u64 v[178:179], v[214:215], 0, s[60:61]
	s_mov_b32 m0, s56
	s_nop 0
	global_load_lds_dwordx4 v[178:179], off
	v_lshl_add_u64 v[178:179], v[216:217], 0, s[60:61]
	s_mov_b32 m0, s57
	s_nop 0
	global_load_lds_dwordx4 v[178:179], off
	s_waitcnt vmcnt(8)
	s_waitcnt lgkmcnt(0)
	s_setprio 1
	s_barrier
	v_mfma_f32_16x16x32_bf16 v[64:67], v[124:127], v[174:177], v[64:67]
	v_mfma_f32_16x16x32_bf16 v[60:63], v[140:143], v[174:177], v[60:63]
	v_mfma_f32_16x16x32_bf16 v[48:51], v[124:127], v[188:191], v[48:51]
	v_mfma_f32_16x16x32_bf16 v[44:47], v[140:143], v[188:191], v[44:47]
	v_mfma_f32_16x16x32_bf16 v[32:35], v[124:127], v[196:199], v[32:35]
	v_mfma_f32_16x16x32_bf16 v[28:31], v[140:143], v[196:199], v[28:31]
	v_mfma_f32_16x16x32_bf16 v[16:19], v[124:127], v[204:207], v[16:19]
	v_mfma_f32_16x16x32_bf16 v[12:15], v[140:143], v[204:207], v[12:15]
	v_mfma_f32_16x16x32_bf16 v[64:67], v[136:139], v[184:187], v[64:67]
	v_mfma_f32_16x16x32_bf16 v[60:63], v[144:147], v[184:187], v[60:63]
	v_mfma_f32_16x16x32_bf16 v[48:51], v[136:139], v[192:195], v[48:51]
	v_mfma_f32_16x16x32_bf16 v[44:47], v[144:147], v[192:195], v[44:47]
	v_mfma_f32_16x16x32_bf16 v[32:35], v[136:139], v[200:203], v[32:35]
	v_mfma_f32_16x16x32_bf16 v[28:31], v[144:147], v[200:203], v[28:31]
	v_mfma_f32_16x16x32_bf16 v[16:19], v[136:139], v[208:211], v[16:19]
	v_mfma_f32_16x16x32_bf16 v[12:15], v[144:147], v[208:211], v[12:15]
	s_setprio 0
	s_setprio 1
	v_mfma_f32_16x16x32_bf16 v[56:59], v[148:151], v[174:177], v[56:59]
	v_mfma_f32_16x16x32_bf16 v[52:55], v[156:159], v[174:177], v[52:55]
	v_mfma_f32_16x16x32_bf16 v[40:43], v[148:151], v[188:191], v[40:43]
	v_mfma_f32_16x16x32_bf16 v[36:39], v[156:159], v[188:191], v[36:39]
	v_mfma_f32_16x16x32_bf16 v[24:27], v[148:151], v[196:199], v[24:27]
	v_mfma_f32_16x16x32_bf16 v[20:23], v[156:159], v[196:199], v[20:23]
	v_mfma_f32_16x16x32_bf16 v[8:11], v[148:151], v[204:207], v[8:11]
	v_mfma_f32_16x16x32_bf16 v[4:7], v[156:159], v[204:207], v[4:7]
	v_mfma_f32_16x16x32_bf16 v[56:59], v[152:155], v[184:187], v[56:59]
	v_mfma_f32_16x16x32_bf16 v[52:55], v[170:173], v[184:187], v[52:55]
	v_mfma_f32_16x16x32_bf16 v[40:43], v[152:155], v[192:195], v[40:43]
	v_mfma_f32_16x16x32_bf16 v[36:39], v[170:173], v[192:195], v[36:39]
	v_mfma_f32_16x16x32_bf16 v[24:27], v[152:155], v[200:203], v[24:27]
	v_mfma_f32_16x16x32_bf16 v[20:23], v[170:173], v[200:203], v[20:23]
	v_mfma_f32_16x16x32_bf16 v[8:11], v[152:155], v[208:211], v[8:11]
	v_mfma_f32_16x16x32_bf16 v[4:7], v[170:173], v[208:211], v[4:7]
	s_barrier
	s_setprio 0
	s_add_i32 s74, s74, 2
	s_add_u32 s6, s6, 0x100
	s_addc_u32 s7, s7, 0
	s_add_u32 s66, s66, 0x100
	s_addc_u32 s70, s70, 0
	s_cmpk_gt_u32 s74, 0x7d
	s_cbranch_scc0 .LBB0_2176
.Lpeel_post_p7:
	s_and_b64 vcc, exec, s[18:19]
	s_cbranch_vccz .LBB0_2179
	s_barrier
